# static s_setprio 1 for waves 4-7 at kernel entry, no per-segment priority flips in the K-loops (on v24's other edits)
# baseline (speedup 1.0000x reference)
; #define LAS __attribute__((address_space(3)))
; __device__ __forceinline__ unsigned xb_add(unsigned* p, unsigned v) { return __hip_atomic_fetch_add(p, v, __ATOMIC_RELAXED, __HIP_MEMORY_SCOPE_AGENT); }
; __device__ __forceinline__ unsigned xb_xcc_id() { return (unsigned)__builtin_amdgcn_s_getreg((3 << 11) | 20) & 0xFu; }
; __device__ __forceinline__ bool xb_thread0(int wave) { unsigned z = 0u; asm volatile("" : "+v"(z)); return wave == 0 && __builtin_amdgcn_mbcnt_hi(~0u, __builtin_amdgcn_mbcnt_lo(~0u, z)) == 0u; }
; __device__ __forceinline__ XcdBarrier xcd_barrier_post(unsigned* bar, volatile LAS unsigned* st, int wave) {
;     XcdBarrier b; b.bar = bar; b.x = xb_xcc_id(); b.st = st; b.wave = wave; b.local_ok = false;
;     if (xb_thread0(wave)) (void)xb_add(&bar[XB_XCNT(b.x)], 1u);
;     return b;
; __global__ void __launch_bounds__(NTHREADS, 2) fwd_kernel(Args args) {
;     extern __shared__ __attribute__((aligned(16))) unsigned char lds[];
;     Frame F;
;     F.lds = (LAS unsigned char*)lds; F.tid = threadIdx.x; F.lane = F.tid & 63; F.wave = __builtin_amdgcn_readfirstlane(F.tid >> 6); F.G = gridDim.x; F.ws = args.ws;
;     const int lo = args.ph_lo, hi = args.ph_hi;
;     ...
;     for (int u = F.tid; u < (LDS_BYTES - RING_BYTES) / 4; u += NTHREADS) ((LAS unsigned*)(F.lds + RING_BYTES))[u] = 0u;
;     __syncthreads();
;     XcdBarrier bar; bar.bar = (unsigned*)(args.ws + WS_CTL) + 4096; bar.x = 0; bar.st = (volatile LAS unsigned*)(F.lds + MISC_OFF); bar.wave = F.wave;
;     if (hi - lo > 1) bar = xcd_barrier_post((unsigned*)(args.ws + WS_CTL) + 4096, (volatile LAS unsigned*)(F.lds + MISC_OFF), F.wave);
_Z10fwd_kernel4Args:
	v_readfirstlane_b32 s100, v0
	s_nop 3
	s_cmp_lt_u32 s100, 0x100
	s_cbranch_scc1 .Lprio_skip
	s_setprio 1
.Lprio_skip:
	s_mov_b32 s78, s2
	s_add_u32 s2, s0, 0xd8
	s_addc_u32 s3, s1, 0
	v_lshl_add_u32 v1, v0, 2, 0
	v_writelane_b32 v249, s2, 0
	v_add_u32_e32 v1, 0x20000, v1
	v_mov_b32_e32 v2, 0
	v_writelane_b32 v249, s3, 1
	s_load_dword s2, s[0:1], 0xd8
	v_readfirstlane_b32 s64, v0
	ds_write2st64_b32 v1, v2, v2 offset1:8
	ds_write2st64_b32 v1, v2, v2 offset0:16 offset1:24
	v_or_b32_e32 v1, 0x800, v0
	s_waitcnt lgkmcnt(0)
	v_writelane_b32 v249, s2, 2
	s_mov_b64 s[2:3], -1
	s_and_saveexec_b64 s[4:5], s[2:3]
	v_lshl_add_u32 v3, v1, 2, 0
	v_add_u32_e32 v3, 0x20000, v3
	ds_write_b32 v3, v2
	s_or_b64 exec, exec, s[4:5]
	s_and_saveexec_b64 s[4:5], s[2:3]
	s_add_i32 s2, 0, 0x20000
	v_lshl_add_u32 v1, v1, 2, s2
	v_mov_b32_e32 v2, 0
	ds_write_b32 v1, v2 offset:2048
	s_or_b64 exec, exec, s[4:5]
	s_load_dwordx4 s[68:71], s[0:1], 0xc0
	v_or_b32_e32 v0, 0xc00, v0
	v_cmp_gt_u32_e64 s[2:3], 7, 6
	v_cmp_gt_u32_e64 s[6:7], 7, 5
	s_and_saveexec_b64 s[4:5], s[6:7]
	v_lshl_add_u32 v1, v0, 2, 0
	v_add_u32_e32 v1, 0x20000, v1
	v_mov_b32_e32 v2, 0
	ds_write_b32 v1, v2
	s_or_b64 exec, exec, s[4:5]
	s_and_saveexec_b64 s[4:5], s[2:3]
	s_add_i32 s2, 0, 0x20000
	v_lshl_add_u32 v0, v0, 2, s2
	v_mov_b32_e32 v1, 0
	ds_write_b32 v0, v1 offset:2048
	s_or_b64 exec, exec, s[4:5]
	s_waitcnt lgkmcnt(0)
	s_add_u32 s96, s68, 0x4000
	s_addc_u32 s97, s69, 0
	s_sub_i32 s4, s71, s70
	s_cmp_gt_i32 s4, 1
	s_cselect_b64 s[2:3], -1, 0
	s_cmp_lt_i32 s4, 2
	s_mov_b32 s65, 0
	s_barrier
	s_cbranch_scc1 .LBB0_14
	s_getreg_b32 s4, hwreg(HW_REG_XCC_ID, 0, 4)
	s_and_b32 s65, s4, 15
	v_mov_b32_e32 v0, 0
	s_cmp_gt_u32 s64, 63
	s_cbranch_scc1 .LBB0_14
	v_mbcnt_lo_u32_b32 v0, -1, v0
	v_mbcnt_hi_u32_b32 v0, -1, v0
	v_cmp_eq_u32_e32 vcc, 0, v0
	s_and_saveexec_b64 s[4:5], vcc
	s_cbranch_execz .LBB0_13
	s_mov_b64 s[6:7], exec
	v_mbcnt_lo_u32_b32 v0, s6, 0
	v_mbcnt_hi_u32_b32 v0, s7, v0
	v_cmp_eq_u32_e32 vcc, 0, v0
	s_and_b64 s[8:9], exec, vcc
	s_mov_b64 exec, s[8:9]
	s_cbranch_execz .LBB0_13
	s_lshl_b32 s8, s65, 8
	s_bcnt1_i32_b64 s6, s[6:7]
	v_mov_b32_e32 v0, s8
	v_mov_b32_e32 v1, s6
	global_atomic_add v0, v1, s[96:97] offset:1024

; #define PG8_WAIT_V(n) asm volatile("s_waitcnt vmcnt(" #n ")" ::: "memory")
; template <class Epi, bool ALIGN_EPI, bool SP2, class Hook>
; __device__ __forceinline__ void gemm_phase(LAS unsigned char* lds, const Gemm g, const StaticOrder& S, const Epi& E, Acc& acc, const bool fresh, const Hook& H, const int wave_id) {
;     ...
;         if constexpr (SP2 && Epi::NSTORE > 0) {
;             const Src a1 = cA + kstep, a2 = cA + 2 * kstep, b2 = cB + 2 * kstep, a3 = a2 + kstep, b3 = b2 + kstep;
;             if constexpr (Epi::NSTORE == 16) PG8_TRIP_SP2(PG8_WAIT_V(24)); else PG8_TRIP_SP2(PG8_WAIT_V(16));
.LBB0_382:
	ds_read_b128 v[2:5], v150
	ds_read_b128 v[6:9], v150 offset:1024
	ds_read_b128 v[10:13], v150 offset:2048
	ds_read_b128 v[14:17], v150 offset:3072
	ds_read_b128 v[18:21], v151
	ds_read_b128 v[22:25], v151 offset:1024
	ds_read_b128 v[26:29], v151 offset:2048
	ds_read_b128 v[30:33], v151 offset:3072
	s_or_b32 s9, s68, 0x100
	s_or_b32 s8, s68, 0x180
	s_or_b32 s10, s69, 0x100
	s_or_b32 s11, s68, 0x40080
	s_mov_b32 m0, s45
	ds_read_b128 v[34:37], v149
	ds_read_b128 v[38:41], v149 offset:1024
	ds_read_b128 v[42:45], v149 offset:2048
	ds_read_b128 v[46:49], v149 offset:3072
	ds_read_b128 v[50:53], v149 offset:4096
	ds_read_b128 v[54:57], v149 offset:5120
	ds_read_b128 v[58:61], v149 offset:6144
	ds_read_b128 v[62:65], v149 offset:7168
	buffer_load_dwordx4 v144, s[0:3], s11 offen lds
	s_mov_b32 m0, s46
	s_nop 0
	buffer_load_dwordx4 v146, s[0:3], s11 offen lds
	s_waitcnt vmcnt(24)
	s_waitcnt lgkmcnt(0)
	s_barrier
	v_mfma_f32_16x16x32_bf16 v[86:89], v[10:13], v[50:53], 0
	v_mfma_f32_16x16x32_bf16 v[92:95], v[14:17], v[54:57], v[86:89]
	v_mfma_f32_16x16x32_bf16 v[86:89], v[2:5], v[58:61], 0
	v_mfma_f32_16x16x32_bf16 v[66:69], v[2:5], v[34:37], 0
	v_mfma_f32_16x16x32_bf16 v[70:73], v[10:13], v[34:37], 0
	v_mfma_f32_16x16x32_bf16 v[74:77], v[2:5], v[42:45], 0
	v_mfma_f32_16x16x32_bf16 v[78:81], v[10:13], v[42:45], 0
	v_mfma_f32_16x16x32_bf16 v[82:85], v[2:5], v[50:53], 0
	v_mfma_f32_16x16x32_bf16 v[96:99], v[6:9], v[62:65], v[86:89]
	v_mfma_f32_16x16x32_bf16 v[86:89], v[10:13], v[58:61], 0
	v_mfma_f32_16x16x32_bf16 v[66:69], v[6:9], v[38:41], v[66:69]
	v_mfma_f32_16x16x32_bf16 v[70:73], v[14:17], v[38:41], v[70:73]
	v_mfma_f32_16x16x32_bf16 v[74:77], v[6:9], v[46:49], v[74:77]
	v_mfma_f32_16x16x32_bf16 v[78:81], v[14:17], v[46:49], v[78:81]
	v_mfma_f32_16x16x32_bf16 v[82:85], v[6:9], v[54:57], v[82:85]
	v_mfma_f32_16x16x32_bf16 v[104:107], v[14:17], v[62:65], v[86:89]
	v_mfma_f32_16x16x32_bf16 v[86:89], v[18:21], v[34:37], 0
	v_mfma_f32_16x16x32_bf16 v[34:37], v[26:29], v[34:37], 0
	v_mfma_f32_16x16x32_bf16 v[116:119], v[30:33], v[38:41], v[34:37]
	v_mfma_f32_16x16x32_bf16 v[34:37], v[18:21], v[42:45], 0
	v_mfma_f32_16x16x32_bf16 v[132:135], v[22:25], v[46:49], v[34:37]
	v_mfma_f32_16x16x32_bf16 v[34:37], v[26:29], v[42:45], 0
	v_mfma_f32_16x16x32_bf16 v[108:111], v[22:25], v[38:41], v[86:89]
	v_mfma_f32_16x16x32_bf16 v[40:43], v[30:33], v[46:49], v[34:37]
	v_mfma_f32_16x16x32_bf16 v[34:37], v[18:21], v[50:53], 0
	v_mfma_f32_16x16x32_bf16 v[44:47], v[22:25], v[54:57], v[34:37]
	v_mfma_f32_16x16x32_bf16 v[34:37], v[26:29], v[50:53], 0
	v_mfma_f32_16x16x32_bf16 v[48:51], v[30:33], v[54:57], v[34:37]
	v_mfma_f32_16x16x32_bf16 v[34:37], v[18:21], v[58:61], 0
	v_mfma_f32_16x16x32_bf16 v[52:55], v[22:25], v[62:65], v[34:37]
	v_mfma_f32_16x16x32_bf16 v[34:37], v[26:29], v[58:61], 0
	v_mfma_f32_16x16x32_bf16 v[60:63], v[30:33], v[62:65], v[34:37]
	s_barrier
	s_mov_b32 m0, s92
	s_nop 3
	ds_read_b128 v[34:37], v149 offset:16384
	ds_read_b128 v[56:59], v149 offset:17408
	ds_read_b128 v[86:89], v149 offset:18432
	ds_read_b128 v[100:103], v149 offset:19456
	ds_read_b128 v[112:115], v149 offset:20480
	ds_read_b128 v[120:123], v149 offset:21504
	ds_read_b128 v[124:127], v149 offset:22528
	ds_read_b128 v[128:131], v149 offset:23552
	buffer_load_dwordx4 v145, s[4:7], s10 offen lds
	s_mov_b32 m0, s93
	s_nop 0
	buffer_load_dwordx4 v147, s[4:7], s10 offen lds
	s_or_b32 s10, s69, 0x40100
	s_mov_b32 m0, s94
	s_nop 0
	buffer_load_dwordx4 v145, s[4:7], s10 offen lds
	s_mov_b32 m0, s95
	s_nop 0
	buffer_load_dwordx4 v147, s[4:7], s10 offen lds
	s_mov_b32 m0, s44
	s_nop 0
	buffer_load_dwordx4 v144, s[0:3], s9 offen lds
	s_mov_b32 m0, s36
	s_nop 0
	buffer_load_dwordx4 v146, s[0:3], s9 offen lds
	s_waitcnt vmcnt(24)
	s_waitcnt lgkmcnt(0)
	s_barrier
	v_mfma_f32_16x16x32_bf16 v[136:139], v[2:5], v[34:37], 0
	v_mfma_f32_16x16x32_bf16 v[154:157], v[2:5], v[86:89], 0
	v_mfma_f32_16x16x32_bf16 v[162:165], v[2:5], v[112:115], 0
	v_mfma_f32_16x16x32_bf16 v[2:5], v[2:5], v[124:127], 0
	v_mfma_f32_16x16x32_bf16 v[136:139], v[6:9], v[56:59], v[136:139]
	v_mfma_f32_16x16x32_bf16 v[140:143], v[10:13], v[34:37], 0
	v_mfma_f32_16x16x32_bf16 v[154:157], v[6:9], v[100:103], v[154:157]
	v_mfma_f32_16x16x32_bf16 v[158:161], v[10:13], v[86:89], 0
	v_mfma_f32_16x16x32_bf16 v[162:165], v[6:9], v[120:123], v[162:165]
	v_mfma_f32_16x16x32_bf16 v[166:169], v[10:13], v[112:115], 0
	v_mfma_f32_16x16x32_bf16 v[2:5], v[6:9], v[128:131], v[2:5]
	v_mfma_f32_16x16x32_bf16 v[6:9], v[10:13], v[124:127], 0
	v_mfma_f32_16x16x32_bf16 v[140:143], v[14:17], v[56:59], v[140:143]
	v_mfma_f32_16x16x32_bf16 v[158:161], v[14:17], v[100:103], v[158:161]
	v_mfma_f32_16x16x32_bf16 v[166:169], v[14:17], v[120:123], v[166:169]
	v_mfma_f32_16x16x32_bf16 v[170:173], v[14:17], v[128:131], v[6:9]
	v_mfma_f32_16x16x32_bf16 v[6:9], v[18:21], v[34:37], 0
	v_mfma_f32_16x16x32_bf16 v[174:177], v[22:25], v[56:59], v[6:9]
	v_mfma_f32_16x16x32_bf16 v[6:9], v[26:29], v[34:37], 0
	v_mfma_f32_16x16x32_bf16 v[178:181], v[30:33], v[56:59], v[6:9]
	v_mfma_f32_16x16x32_bf16 v[6:9], v[18:21], v[86:89], 0
	v_mfma_f32_16x16x32_bf16 v[182:185], v[22:25], v[100:103], v[6:9]
	v_mfma_f32_16x16x32_bf16 v[6:9], v[26:29], v[86:89], 0
	v_mfma_f32_16x16x32_bf16 v[186:189], v[30:33], v[100:103], v[6:9]
	v_mfma_f32_16x16x32_bf16 v[6:9], v[18:21], v[112:115], 0
	v_mfma_f32_16x16x32_bf16 v[190:193], v[22:25], v[120:123], v[6:9]
	v_mfma_f32_16x16x32_bf16 v[6:9], v[26:29], v[112:115], 0
	v_mfma_f32_16x16x32_bf16 v[212:215], v[30:33], v[120:123], v[6:9]
	v_mfma_f32_16x16x32_bf16 v[6:9], v[18:21], v[124:127], 0
	v_mfma_f32_16x16x32_bf16 v[20:23], v[22:25], v[128:131], v[6:9]
	v_mfma_f32_16x16x32_bf16 v[6:9], v[26:29], v[124:127], 0
	v_mfma_f32_16x16x32_bf16 v[216:219], v[30:33], v[128:131], v[6:9]
	s_barrier
; #define PG8_WAIT_V(n) asm volatile("s_waitcnt vmcnt(" #n ")" ::: "memory")
; template <class Epi, bool ALIGN_EPI, bool SP2, class Hook>
; __device__ __forceinline__ void gemm_phase(LAS unsigned char* lds, const Gemm g, const StaticOrder& S, const Epi& E, Acc& acc, const bool fresh, const Hook& H, const int wave_id) {
;     ...
;         if constexpr (SP2 && Epi::NSTORE > 0) {
;             const Src a1 = cA + kstep, a2 = cA + 2 * kstep, b2 = cB + 2 * kstep, a3 = a2 + kstep, b3 = b2 + kstep;
;             if constexpr (Epi::NSTORE == 16) PG8_TRIP_SP2(PG8_WAIT_V(24)); else PG8_TRIP_SP2(PG8_WAIT_V(16));
;             t0 = 2;
	s_nop 4
	ds_read_b128 v[6:9], v152
	ds_read_b128 v[24:27], v152 offset:1024
	ds_read_b128 v[228:231], v152 offset:2048
	ds_read_b128 v[232:235], v152 offset:3072
	ds_read_b128 v[236:239], v153
	ds_read_b128 v[240:243], v153 offset:1024
	ds_read_b128 v[244:247], v153 offset:2048
	ds_read_b128 v[150:153], v153 offset:3072
	s_or_b32 s9, s68, 0x40100
	s_mov_b32 m0, s37
	ds_read_b128 v[10:13], v149 offset:32768
	ds_read_b128 v[14:17], v149 offset:33792
	ds_read_b128 v[32:35], v149 offset:34816
	ds_read_b128 v[194:197], v149 offset:35840
	ds_read_b128 v[208:211], v149 offset:36864
	ds_read_b128 v[200:203], v149 offset:37888
	ds_read_b128 v[204:207], v149 offset:38912
	ds_read_b128 v[220:223], v149 offset:39936
	buffer_load_dwordx4 v144, s[0:3], s9 offen lds
	s_mov_b32 m0, s38
	s_nop 0
	buffer_load_dwordx4 v146, s[0:3], s9 offen lds
	s_waitcnt vmcnt(8)
	s_waitcnt lgkmcnt(0)
	s_barrier
	v_mfma_f32_16x16x32_bf16 v[28:31], v[6:9], v[10:13], v[66:69]
	v_mfma_f32_16x16x32_bf16 v[120:123], v[24:27], v[14:17], v[28:31]
	v_mfma_f32_16x16x32_bf16 v[28:31], v[228:231], v[10:13], v[70:73]
	v_mfma_f32_16x16x32_bf16 v[112:115], v[232:235], v[14:17], v[28:31]
	v_mfma_f32_16x16x32_bf16 v[28:31], v[6:9], v[32:35], v[74:77]
	v_mfma_f32_16x16x32_bf16 v[100:103], v[24:27], v[194:197], v[28:31]
	v_mfma_f32_16x16x32_bf16 v[28:31], v[228:231], v[32:35], v[78:81]
	v_mfma_f32_16x16x32_bf16 v[88:91], v[232:235], v[194:197], v[28:31]
	v_mfma_f32_16x16x32_bf16 v[28:31], v[6:9], v[208:211], v[82:85]
	v_mfma_f32_16x16x32_bf16 v[68:71], v[24:27], v[200:203], v[28:31]
	v_mfma_f32_16x16x32_bf16 v[28:31], v[228:231], v[208:211], v[92:95]
	v_mfma_f32_16x16x32_bf16 v[56:59], v[232:235], v[200:203], v[28:31]
	v_mfma_f32_16x16x32_bf16 v[28:31], v[6:9], v[204:207], v[96:99]
	v_mfma_f32_16x16x32_bf16 v[36:39], v[24:27], v[220:223], v[28:31]
	v_mfma_f32_16x16x32_bf16 v[28:31], v[228:231], v[204:207], v[104:107]
	v_mfma_f32_16x16x32_bf16 v[28:31], v[232:235], v[220:223], v[28:31]
	v_mfma_f32_16x16x32_bf16 v[64:67], v[236:239], v[10:13], v[108:111]
	v_mfma_f32_16x16x32_bf16 v[10:13], v[244:247], v[10:13], v[116:119]
	v_mfma_f32_16x16x32_bf16 v[124:127], v[150:153], v[14:17], v[10:13]
	v_mfma_f32_16x16x32_bf16 v[10:13], v[236:239], v[32:35], v[132:135]
	v_mfma_f32_16x16x32_bf16 v[116:119], v[240:243], v[194:197], v[10:13]
	v_mfma_f32_16x16x32_bf16 v[10:13], v[244:247], v[32:35], v[40:43]
	v_mfma_f32_16x16x32_bf16 v[108:111], v[150:153], v[194:197], v[10:13]
	v_mfma_f32_16x16x32_bf16 v[10:13], v[236:239], v[208:211], v[44:47]
	v_mfma_f32_16x16x32_bf16 v[92:95], v[240:243], v[200:203], v[10:13]
	v_mfma_f32_16x16x32_bf16 v[10:13], v[244:247], v[208:211], v[48:51]
	v_mfma_f32_16x16x32_bf16 v[80:83], v[150:153], v[200:203], v[10:13]
	v_mfma_f32_16x16x32_bf16 v[10:13], v[236:239], v[204:207], v[52:55]
	v_mfma_f32_16x16x32_bf16 v[128:131], v[240:243], v[14:17], v[64:67]
	v_mfma_f32_16x16x32_bf16 v[64:67], v[240:243], v[220:223], v[10:13]
	v_mfma_f32_16x16x32_bf16 v[10:13], v[244:247], v[204:207], v[60:63]
	v_mfma_f32_16x16x32_bf16 v[48:51], v[150:153], v[220:223], v[10:13]
	s_barrier
	s_mov_b32 m0, s39
	s_or_b32 s9, s69, 0x180
	ds_read_b128 v[44:47], v149 offset:49152
	ds_read_b128 v[52:55], v149 offset:50176
	ds_read_b128 v[76:79], v149 offset:51200
	ds_read_b128 v[132:135], v149 offset:52224
	ds_read_b128 v[194:197], v149 offset:53248
	ds_read_b128 v[200:203], v149 offset:54272
	ds_read_b128 v[204:207], v149 offset:55296
	ds_read_b128 v[208:211], v149 offset:56320
	buffer_load_dwordx4 v145, s[4:7], s9 offen lds
	s_mov_b32 m0, s40
	s_nop 0
	buffer_load_dwordx4 v147, s[4:7], s9 offen lds
	s_or_b32 s9, s69, 0x40180
	s_mov_b32 m0, s43
	s_nop 0
	buffer_load_dwordx4 v145, s[4:7], s9 offen lds
	s_mov_b32 m0, s42
	s_nop 0
	buffer_load_dwordx4 v147, s[4:7], s9 offen lds
	s_mov_b32 m0, s41
	s_nop 0
	buffer_load_dwordx4 v144, s[0:3], s8 offen lds
	s_mov_b32 m0, s33
	s_nop 0
	buffer_load_dwordx4 v146, s[0:3], s8 offen lds
	s_waitcnt vmcnt(8)
	s_waitcnt lgkmcnt(0)
	s_barrier
	v_mfma_f32_16x16x32_bf16 v[10:13], v[6:9], v[44:47], v[136:139]
	v_mfma_f32_16x16x32_bf16 v[72:75], v[24:27], v[52:55], v[10:13]
	v_mfma_f32_16x16x32_bf16 v[10:13], v[228:231], v[44:47], v[140:143]
	v_mfma_f32_16x16x32_bf16 v[60:63], v[232:235], v[52:55], v[10:13]
	v_mfma_f32_16x16x32_bf16 v[10:13], v[6:9], v[76:79], v[154:157]
	v_mfma_f32_16x16x32_bf16 v[40:43], v[24:27], v[132:135], v[10:13]
	v_mfma_f32_16x16x32_bf16 v[10:13], v[228:231], v[76:79], v[158:161]
	v_mfma_f32_16x16x32_bf16 v[32:35], v[232:235], v[132:135], v[10:13]
	v_mfma_f32_16x16x32_bf16 v[10:13], v[6:9], v[194:197], v[162:165]
	v_mfma_f32_16x16x32_bf16 v[16:19], v[24:27], v[200:203], v[10:13]
	v_mfma_f32_16x16x32_bf16 v[10:13], v[228:231], v[194:197], v[166:169]
	v_mfma_f32_16x16x32_bf16 v[2:5], v[6:9], v[204:207], v[2:5]
	v_mfma_f32_16x16x32_bf16 v[12:15], v[232:235], v[200:203], v[10:13]
	v_mfma_f32_16x16x32_bf16 v[8:11], v[24:27], v[208:211], v[2:5]
	v_mfma_f32_16x16x32_bf16 v[2:5], v[228:231], v[204:207], v[170:173]
	v_mfma_f32_16x16x32_bf16 v[4:7], v[232:235], v[208:211], v[2:5]
	v_mfma_f32_16x16x32_bf16 v[24:27], v[236:239], v[44:47], v[174:177]
	v_mfma_f32_16x16x32_bf16 v[96:99], v[240:243], v[52:55], v[24:27]
	v_mfma_f32_16x16x32_bf16 v[24:27], v[244:247], v[44:47], v[178:181]
	v_mfma_f32_16x16x32_bf16 v[104:107], v[150:153], v[52:55], v[24:27]
	v_mfma_f32_16x16x32_bf16 v[24:27], v[236:239], v[76:79], v[182:185]
	v_mfma_f32_16x16x32_bf16 v[84:87], v[240:243], v[132:135], v[24:27]
	v_mfma_f32_16x16x32_bf16 v[24:27], v[244:247], v[76:79], v[186:189]
	v_mfma_f32_16x16x32_bf16 v[76:79], v[150:153], v[132:135], v[24:27]
	v_mfma_f32_16x16x32_bf16 v[24:27], v[236:239], v[194:197], v[190:193]
	v_mfma_f32_16x16x32_bf16 v[52:55], v[240:243], v[200:203], v[24:27]
	v_mfma_f32_16x16x32_bf16 v[24:27], v[244:247], v[194:197], v[212:215]
	v_mfma_f32_16x16x32_bf16 v[20:23], v[236:239], v[204:207], v[20:23]
	v_mfma_f32_16x16x32_bf16 v[44:47], v[150:153], v[200:203], v[24:27]
	v_mfma_f32_16x16x32_bf16 v[24:27], v[240:243], v[208:211], v[20:23]
	v_mfma_f32_16x16x32_bf16 v[20:23], v[244:247], v[204:207], v[216:219]
	v_mfma_f32_16x16x32_bf16 v[20:23], v[150:153], v[208:211], v[20:23]
	s_barrier
	s_mov_b64 s[8:9], 0
	v_mov_b64_e32 v[234:235], v[198:199]
	v_mov_b64_e32 v[236:237], v[226:227]
	v_mov_b32_e32 v198, v0
	v_mov_b32_e32 v226, v225
	v_mov_b64_e32 v[244:245], 0x100
	v_mov_b64_e32 v[246:247], 0xff

; #define PG8_WAIT_V(n) asm volatile("s_waitcnt vmcnt(" #n ")" ::: "memory")
; template <class Epi, bool ALIGN_EPI, bool SP2, class Hook>
; __device__ __forceinline__ void gemm_phase(LAS unsigned char* lds, const Gemm g, const StaticOrder& S, const Epi& E, Acc& acc, const bool fresh, const Hook& H, const int wave_id) {
;     ...
;         for (int t = t0; t < nt; t += 2) {
;             const bool last = (t == nt - 2);
;             const Src a1 = cA + (size_t)(t + 1) * kstep;
;             const Src a2 = last ? nA : cA + (size_t)(t + 2) * kstep, b2 = last ? nB : cB + (size_t)(t + 2) * kstep;
;             const Src a3 = a2 + kstep, b3 = b2 + kstep;
;             if (last && has_next) H(nxt);
;             if constexpr (SP2) {
;             PG8_TRIP_SP2(PG8_WAIT_V(8));
.LBB0_391:
	v_add_u32_e32 v150, 0x10000, v148
	v_add_u32_e32 v151, 0x14000, v148
	ds_read_b128 v[132:135], v150
	ds_read_b128 v[136:139], v150 offset:1024
	ds_read_b128 v[140:143], v150 offset:2048
	ds_read_b128 v[152:155], v150 offset:3072
	ds_read_b128 v[156:159], v151
	ds_read_b128 v[160:163], v151 offset:1024
	ds_read_b128 v[164:167], v151 offset:2048
	ds_read_b128 v[168:171], v151 offset:3072
	s_add_i32 s12, s56, 0xfffc0080
	s_cmp_eq_u32 s29, 12
	s_cselect_b32 s60, s68, s12
	s_cselect_b32 s13, s5, s77
	s_cselect_b32 s12, s4, s76
	s_cselect_b32 s15, s7, s55
	s_cselect_b32 s14, s6, s54
	s_cselect_b32 s58, s69, s57
	s_cselect_b32 s16, s0, s8
	s_cselect_b32 s17, s1, s9
	s_cselect_b32 s18, s2, s10
	s_cselect_b32 s19, s3, s11
	s_or_b32 s59, s60, 0x80
	s_mov_b32 m0, s45
	ds_read_b128 v[172:175], v149
	ds_read_b128 v[176:179], v149 offset:1024
	ds_read_b128 v[180:183], v149 offset:2048
	ds_read_b128 v[184:187], v149 offset:3072
	ds_read_b128 v[188:191], v149 offset:4096
	ds_read_b128 v[212:215], v149 offset:5120
	ds_read_b128 v[216:219], v149 offset:6144
	ds_read_b128 v[228:231], v149 offset:7168
	buffer_load_dwordx4 v144, s[8:11], s56 offen lds
	s_mov_b32 m0, s46
	s_nop 0
	buffer_load_dwordx4 v146, s[8:11], s56 offen lds
	s_waitcnt vmcnt(8)
	s_waitcnt lgkmcnt(0)
	s_barrier
	v_mfma_f32_16x16x32_bf16 v[120:123], v[132:135], v[172:175], v[120:123]
	v_mfma_f32_16x16x32_bf16 v[112:115], v[140:143], v[172:175], v[112:115]
	v_mfma_f32_16x16x32_bf16 v[100:103], v[132:135], v[180:183], v[100:103]
	v_mfma_f32_16x16x32_bf16 v[88:91], v[140:143], v[180:183], v[88:91]
	v_mfma_f32_16x16x32_bf16 v[68:71], v[132:135], v[188:191], v[68:71]
	v_mfma_f32_16x16x32_bf16 v[56:59], v[140:143], v[188:191], v[56:59]
	v_mfma_f32_16x16x32_bf16 v[36:39], v[132:135], v[216:219], v[36:39]
	v_mfma_f32_16x16x32_bf16 v[28:31], v[140:143], v[216:219], v[28:31]
	v_mfma_f32_16x16x32_bf16 v[120:123], v[136:139], v[176:179], v[120:123]
	v_mfma_f32_16x16x32_bf16 v[112:115], v[152:155], v[176:179], v[112:115]
	v_mfma_f32_16x16x32_bf16 v[100:103], v[136:139], v[184:187], v[100:103]
	v_mfma_f32_16x16x32_bf16 v[88:91], v[152:155], v[184:187], v[88:91]
	v_mfma_f32_16x16x32_bf16 v[68:71], v[136:139], v[212:215], v[68:71]
	v_mfma_f32_16x16x32_bf16 v[56:59], v[152:155], v[212:215], v[56:59]
	v_mfma_f32_16x16x32_bf16 v[36:39], v[136:139], v[228:231], v[36:39]
	v_mfma_f32_16x16x32_bf16 v[28:31], v[152:155], v[228:231], v[28:31]
	v_mfma_f32_16x16x32_bf16 v[128:131], v[156:159], v[172:175], v[128:131]
	v_mfma_f32_16x16x32_bf16 v[124:127], v[164:167], v[172:175], v[124:127]
	v_mfma_f32_16x16x32_bf16 v[116:119], v[156:159], v[180:183], v[116:119]
	v_mfma_f32_16x16x32_bf16 v[108:111], v[164:167], v[180:183], v[108:111]
	v_mfma_f32_16x16x32_bf16 v[92:95], v[156:159], v[188:191], v[92:95]
	v_mfma_f32_16x16x32_bf16 v[80:83], v[164:167], v[188:191], v[80:83]
	v_mfma_f32_16x16x32_bf16 v[64:67], v[156:159], v[216:219], v[64:67]
	v_mfma_f32_16x16x32_bf16 v[48:51], v[164:167], v[216:219], v[48:51]
	v_mfma_f32_16x16x32_bf16 v[128:131], v[160:163], v[176:179], v[128:131]
	v_mfma_f32_16x16x32_bf16 v[124:127], v[168:171], v[176:179], v[124:127]
	v_mfma_f32_16x16x32_bf16 v[116:119], v[160:163], v[184:187], v[116:119]
	v_mfma_f32_16x16x32_bf16 v[108:111], v[168:171], v[184:187], v[108:111]
	v_mfma_f32_16x16x32_bf16 v[92:95], v[160:163], v[212:215], v[92:95]
	v_mfma_f32_16x16x32_bf16 v[80:83], v[168:171], v[212:215], v[80:83]
	v_mfma_f32_16x16x32_bf16 v[64:67], v[160:163], v[228:231], v[64:67]
	v_mfma_f32_16x16x32_bf16 v[48:51], v[168:171], v[228:231], v[48:51]
	s_barrier
	s_mov_b32 m0, s92
	ds_read_b128 v[172:175], v149 offset:16384
	ds_read_b128 v[176:179], v149 offset:17408
	ds_read_b128 v[180:183], v149 offset:18432
	ds_read_b128 v[184:187], v149 offset:19456
	ds_read_b128 v[188:191], v149 offset:20480
	ds_read_b128 v[212:215], v149 offset:21504
	ds_read_b128 v[216:219], v149 offset:22528
	ds_read_b128 v[228:231], v149 offset:23552
	buffer_load_dwordx4 v145, s[12:15], s58 offen lds
	s_mov_b32 m0, s93
	s_add_i32 s61, s58, 0x40000
	buffer_load_dwordx4 v147, s[12:15], s58 offen lds
	s_mov_b32 m0, s94
	s_nop 0
	buffer_load_dwordx4 v145, s[12:15], s61 offen lds
	s_mov_b32 m0, s95
	s_nop 0
	buffer_load_dwordx4 v147, s[12:15], s61 offen lds
	s_mov_b32 m0, s44
	s_nop 0
	buffer_load_dwordx4 v144, s[16:19], s60 offen lds
	s_mov_b32 m0, s36
	s_nop 0
	buffer_load_dwordx4 v146, s[16:19], s60 offen lds
	s_waitcnt vmcnt(8)
	s_waitcnt lgkmcnt(0)
	s_barrier
	v_mfma_f32_16x16x32_bf16 v[72:75], v[132:135], v[172:175], v[72:75]
	v_mfma_f32_16x16x32_bf16 v[60:63], v[140:143], v[172:175], v[60:63]
	v_mfma_f32_16x16x32_bf16 v[40:43], v[132:135], v[180:183], v[40:43]
	v_mfma_f32_16x16x32_bf16 v[32:35], v[140:143], v[180:183], v[32:35]
	v_mfma_f32_16x16x32_bf16 v[16:19], v[132:135], v[188:191], v[16:19]
	v_mfma_f32_16x16x32_bf16 v[12:15], v[140:143], v[188:191], v[12:15]
	v_mfma_f32_16x16x32_bf16 v[8:11], v[132:135], v[216:219], v[8:11]
	v_mfma_f32_16x16x32_bf16 v[2:5], v[140:143], v[216:219], v[4:7]
	v_mfma_f32_16x16x32_bf16 v[72:75], v[136:139], v[176:179], v[72:75]
	v_mfma_f32_16x16x32_bf16 v[60:63], v[152:155], v[176:179], v[60:63]
	v_mfma_f32_16x16x32_bf16 v[40:43], v[136:139], v[184:187], v[40:43]
	v_mfma_f32_16x16x32_bf16 v[32:35], v[152:155], v[184:187], v[32:35]
	v_mfma_f32_16x16x32_bf16 v[16:19], v[136:139], v[212:215], v[16:19]
	v_mfma_f32_16x16x32_bf16 v[12:15], v[152:155], v[212:215], v[12:15]
	v_mfma_f32_16x16x32_bf16 v[8:11], v[136:139], v[228:231], v[8:11]
	v_mfma_f32_16x16x32_bf16 v[2:5], v[152:155], v[228:231], v[2:5]
	v_mfma_f32_16x16x32_bf16 v[96:99], v[156:159], v[172:175], v[96:99]
	v_mfma_f32_16x16x32_bf16 v[104:107], v[164:167], v[172:175], v[104:107]
	v_mfma_f32_16x16x32_bf16 v[84:87], v[156:159], v[180:183], v[84:87]
	v_mfma_f32_16x16x32_bf16 v[76:79], v[164:167], v[180:183], v[76:79]
	v_mfma_f32_16x16x32_bf16 v[52:55], v[156:159], v[188:191], v[52:55]
	v_mfma_f32_16x16x32_bf16 v[44:47], v[164:167], v[188:191], v[44:47]
	v_mfma_f32_16x16x32_bf16 v[24:27], v[156:159], v[216:219], v[24:27]
	v_mfma_f32_16x16x32_bf16 v[20:23], v[164:167], v[216:219], v[20:23]
	v_mfma_f32_16x16x32_bf16 v[96:99], v[160:163], v[176:179], v[96:99]
	v_mfma_f32_16x16x32_bf16 v[104:107], v[168:171], v[176:179], v[104:107]
	v_mfma_f32_16x16x32_bf16 v[84:87], v[160:163], v[184:187], v[84:87]
	v_mfma_f32_16x16x32_bf16 v[76:79], v[168:171], v[184:187], v[76:79]
	v_mfma_f32_16x16x32_bf16 v[52:55], v[160:163], v[212:215], v[52:55]
	v_mfma_f32_16x16x32_bf16 v[44:47], v[168:171], v[212:215], v[44:47]
	v_mfma_f32_16x16x32_bf16 v[24:27], v[160:163], v[228:231], v[24:27]
	v_mfma_f32_16x16x32_bf16 v[20:23], v[168:171], v[228:231], v[20:23]
	s_barrier
; #define PG8_WAIT_V(n) asm volatile("s_waitcnt vmcnt(" #n ")" ::: "memory")
; template <class Epi, bool ALIGN_EPI, bool SP2, class Hook>
; __device__ __forceinline__ void gemm_phase(LAS unsigned char* lds, const Gemm g, const StaticOrder& S, const Epi& E, Acc& acc, const bool fresh, const Hook& H, const int wave_id) {
;     ...
;         for (int t = t0; t < nt; t += 2) {
;             const bool last = (t == nt - 2);
;             const Src a1 = cA + (size_t)(t + 1) * kstep;
;             const Src a2 = last ? nA : cA + (size_t)(t + 2) * kstep, b2 = last ? nB : cB + (size_t)(t + 2) * kstep;
;             const Src a3 = a2 + kstep, b3 = b2 + kstep;
;             if (last && has_next) H(nxt);
;             if constexpr (SP2) {
;             PG8_TRIP_SP2(PG8_WAIT_V(8));
	v_add_u32_e32 v152, 0x18000, v148
	v_add_u32_e32 v153, 0x1c000, v148
	ds_read_b128 v[132:135], v152
	ds_read_b128 v[136:139], v152 offset:1024
	ds_read_b128 v[140:143], v152 offset:2048
	ds_read_b128 v[154:157], v152 offset:3072
	ds_read_b128 v[158:161], v153
	ds_read_b128 v[162:165], v153 offset:1024
	ds_read_b128 v[166:169], v153 offset:2048
	ds_read_b128 v[170:173], v153 offset:3072
	s_add_i32 s60, s60, 0x40000
	s_mov_b32 m0, s37
	ds_read_b128 v[174:177], v149 offset:32768
	ds_read_b128 v[178:181], v149 offset:33792
	ds_read_b128 v[182:185], v149 offset:34816
	ds_read_b128 v[186:189], v149 offset:35840
	ds_read_b128 v[190:193], v149 offset:36864
	ds_read_b128 v[212:215], v149 offset:37888
	ds_read_b128 v[216:219], v149 offset:38912
	ds_read_b128 v[228:231], v149 offset:39936
	buffer_load_dwordx4 v144, s[16:19], s60 offen lds
	s_mov_b32 m0, s38
	s_nop 0
	buffer_load_dwordx4 v146, s[16:19], s60 offen lds
	s_waitcnt vmcnt(8)
	s_waitcnt lgkmcnt(0)
	s_barrier
	v_mfma_f32_16x16x32_bf16 v[120:123], v[132:135], v[174:177], v[120:123]
	v_mfma_f32_16x16x32_bf16 v[112:115], v[140:143], v[174:177], v[112:115]
	v_mfma_f32_16x16x32_bf16 v[100:103], v[132:135], v[182:185], v[100:103]
	v_mfma_f32_16x16x32_bf16 v[88:91], v[140:143], v[182:185], v[88:91]
	v_mfma_f32_16x16x32_bf16 v[68:71], v[132:135], v[190:193], v[68:71]
	v_mfma_f32_16x16x32_bf16 v[56:59], v[140:143], v[190:193], v[56:59]
	v_mfma_f32_16x16x32_bf16 v[36:39], v[132:135], v[216:219], v[36:39]
	v_mfma_f32_16x16x32_bf16 v[28:31], v[140:143], v[216:219], v[28:31]
	v_mfma_f32_16x16x32_bf16 v[120:123], v[136:139], v[178:181], v[120:123]
	v_mfma_f32_16x16x32_bf16 v[112:115], v[154:157], v[178:181], v[112:115]
	v_mfma_f32_16x16x32_bf16 v[100:103], v[136:139], v[186:189], v[100:103]
	v_mfma_f32_16x16x32_bf16 v[88:91], v[154:157], v[186:189], v[88:91]
	v_mfma_f32_16x16x32_bf16 v[68:71], v[136:139], v[212:215], v[68:71]
	v_mfma_f32_16x16x32_bf16 v[56:59], v[154:157], v[212:215], v[56:59]
	v_mfma_f32_16x16x32_bf16 v[36:39], v[136:139], v[228:231], v[36:39]
	v_mfma_f32_16x16x32_bf16 v[28:31], v[154:157], v[228:231], v[28:31]
	v_mfma_f32_16x16x32_bf16 v[128:131], v[158:161], v[174:177], v[128:131]
	v_mfma_f32_16x16x32_bf16 v[124:127], v[166:169], v[174:177], v[124:127]
	v_mfma_f32_16x16x32_bf16 v[116:119], v[158:161], v[182:185], v[116:119]
	v_mfma_f32_16x16x32_bf16 v[108:111], v[166:169], v[182:185], v[108:111]
	v_mfma_f32_16x16x32_bf16 v[92:95], v[158:161], v[190:193], v[92:95]
	v_mfma_f32_16x16x32_bf16 v[80:83], v[166:169], v[190:193], v[80:83]
	v_mfma_f32_16x16x32_bf16 v[64:67], v[158:161], v[216:219], v[64:67]
	v_mfma_f32_16x16x32_bf16 v[48:51], v[166:169], v[216:219], v[48:51]
	v_mfma_f32_16x16x32_bf16 v[128:131], v[162:165], v[178:181], v[128:131]
	v_mfma_f32_16x16x32_bf16 v[124:127], v[170:173], v[178:181], v[124:127]
	v_mfma_f32_16x16x32_bf16 v[116:119], v[162:165], v[186:189], v[116:119]
	v_mfma_f32_16x16x32_bf16 v[108:111], v[170:173], v[186:189], v[108:111]
	v_mfma_f32_16x16x32_bf16 v[92:95], v[162:165], v[212:215], v[92:95]
	v_mfma_f32_16x16x32_bf16 v[80:83], v[170:173], v[212:215], v[80:83]
	v_mfma_f32_16x16x32_bf16 v[64:67], v[162:165], v[228:231], v[64:67]
	v_mfma_f32_16x16x32_bf16 v[48:51], v[170:173], v[228:231], v[48:51]
	s_barrier
	s_mov_b32 m0, s39
	s_or_b32 s60, s58, 0x80
	ds_read_b128 v[174:177], v149 offset:49152
	ds_read_b128 v[178:181], v149 offset:50176
	ds_read_b128 v[182:185], v149 offset:51200
	ds_read_b128 v[186:189], v149 offset:52224
	ds_read_b128 v[190:193], v149 offset:53248
	ds_read_b128 v[212:215], v149 offset:54272
	ds_read_b128 v[216:219], v149 offset:55296
	ds_read_b128 v[228:231], v149 offset:56320
	buffer_load_dwordx4 v145, s[12:15], s60 offen lds
	s_mov_b32 m0, s40
	s_add_i32 s58, s58, 0x40080
	buffer_load_dwordx4 v147, s[12:15], s60 offen lds
	s_mov_b32 m0, s43
	s_nop 0
	buffer_load_dwordx4 v145, s[12:15], s58 offen lds
	s_mov_b32 m0, s42
	s_nop 0
	buffer_load_dwordx4 v147, s[12:15], s58 offen lds
	s_mov_b32 m0, s41
	s_nop 0
	buffer_load_dwordx4 v144, s[16:19], s59 offen lds
	s_mov_b32 m0, s33
	s_nop 0
	buffer_load_dwordx4 v146, s[16:19], s59 offen lds
	s_waitcnt vmcnt(8)
	s_waitcnt lgkmcnt(0)
	s_barrier
	v_mfma_f32_16x16x32_bf16 v[72:75], v[132:135], v[174:177], v[72:75]
	v_mfma_f32_16x16x32_bf16 v[60:63], v[140:143], v[174:177], v[60:63]
	v_mfma_f32_16x16x32_bf16 v[40:43], v[132:135], v[182:185], v[40:43]
	v_mfma_f32_16x16x32_bf16 v[32:35], v[140:143], v[182:185], v[32:35]
	v_mfma_f32_16x16x32_bf16 v[16:19], v[132:135], v[190:193], v[16:19]
	v_mfma_f32_16x16x32_bf16 v[12:15], v[140:143], v[190:193], v[12:15]
	v_mfma_f32_16x16x32_bf16 v[6:9], v[132:135], v[216:219], v[8:11]
	v_mfma_f32_16x16x32_bf16 v[2:5], v[140:143], v[216:219], v[2:5]
	v_mfma_f32_16x16x32_bf16 v[72:75], v[136:139], v[178:181], v[72:75]
	v_mfma_f32_16x16x32_bf16 v[60:63], v[154:157], v[178:181], v[60:63]
	v_mfma_f32_16x16x32_bf16 v[40:43], v[136:139], v[186:189], v[40:43]
	v_mfma_f32_16x16x32_bf16 v[32:35], v[154:157], v[186:189], v[32:35]
	v_mfma_f32_16x16x32_bf16 v[16:19], v[136:139], v[212:215], v[16:19]
	v_mfma_f32_16x16x32_bf16 v[12:15], v[154:157], v[212:215], v[12:15]
	v_mfma_f32_16x16x32_bf16 v[8:11], v[136:139], v[228:231], v[6:9]
	v_mfma_f32_16x16x32_bf16 v[4:7], v[154:157], v[228:231], v[2:5]
	v_mfma_f32_16x16x32_bf16 v[96:99], v[158:161], v[174:177], v[96:99]
	v_mfma_f32_16x16x32_bf16 v[104:107], v[166:169], v[174:177], v[104:107]
	v_mfma_f32_16x16x32_bf16 v[84:87], v[158:161], v[182:185], v[84:87]
	v_mfma_f32_16x16x32_bf16 v[76:79], v[166:169], v[182:185], v[76:79]
	v_mfma_f32_16x16x32_bf16 v[52:55], v[158:161], v[190:193], v[52:55]
	v_mfma_f32_16x16x32_bf16 v[44:47], v[166:169], v[190:193], v[44:47]
	v_mfma_f32_16x16x32_bf16 v[24:27], v[158:161], v[216:219], v[24:27]
	v_mfma_f32_16x16x32_bf16 v[20:23], v[166:169], v[216:219], v[20:23]
	v_mfma_f32_16x16x32_bf16 v[96:99], v[162:165], v[178:181], v[96:99]
	v_mfma_f32_16x16x32_bf16 v[104:107], v[170:173], v[178:181], v[104:107]
	v_mfma_f32_16x16x32_bf16 v[84:87], v[162:165], v[186:189], v[84:87]
	v_mfma_f32_16x16x32_bf16 v[76:79], v[170:173], v[186:189], v[76:79]
	v_mfma_f32_16x16x32_bf16 v[52:55], v[162:165], v[212:215], v[52:55]
	v_mfma_f32_16x16x32_bf16 v[44:47], v[170:173], v[212:215], v[44:47]
	v_mfma_f32_16x16x32_bf16 v[24:27], v[162:165], v[228:231], v[24:27]
	v_mfma_f32_16x16x32_bf16 v[20:23], v[170:173], v[228:231], v[20:23]
	s_barrier
	s_add_i32 s29, s29, 2
	s_addk_i32 s56, 0x100
	s_addk_i32 s57, 0x100
	s_cmp_gt_u32 s29, 13
	s_cbranch_scc0 .LBB0_391
	v_readlane_b32 s8, v251, 45
	v_readlane_b32 s9, v251, 46
	s_and_b64 vcc, exec, s[8:9]
	s_cbranch_vccz .LBB0_394
	s_barrier

; #define PG8_WAIT_V(n) asm volatile("s_waitcnt vmcnt(" #n ")" ::: "memory")
; template <class Epi, bool ALIGN_EPI, bool SP2, class Hook>
; __device__ __forceinline__ void gemm_phase(LAS unsigned char* lds, const Gemm g, const StaticOrder& S, const Epi& E, Acc& acc, const bool fresh, const Hook& H, const int wave_id) {
;     ...
;         for (int t = t0; t < nt; t += 2) {
;             const bool last = (t == nt - 2);
;             const Src a1 = cA + (size_t)(t + 1) * kstep;
;             const Src a2 = last ? nA : cA + (size_t)(t + 2) * kstep, b2 = last ? nB : cB + (size_t)(t + 2) * kstep;
;             const Src a3 = a2 + kstep, b3 = b2 + kstep;
;             if (last && has_next) H(nxt);
;             if constexpr (SP2) {
;             PG8_TRIP_SP2(PG8_WAIT_V(8));
.LBB0_702:
	v_add_u32_e32 v70, 0x10000, v216
	v_add_u32_e32 v118, 0x14000, v216
	ds_read_b128 v[34:37], v70
	ds_read_b128 v[46:49], v70 offset:1024
	ds_read_b128 v[58:61], v70 offset:2048
	ds_read_b128 v[70:73], v70 offset:3072
	ds_read_b128 v[82:85], v118
	ds_read_b128 v[94:97], v118 offset:1024
	ds_read_b128 v[106:109], v118 offset:2048
	ds_read_b128 v[118:121], v118 offset:3072
	s_add_i32 s12, s55, 0xfffe0080
	s_cmp_eq_u32 s57, 4
	s_cselect_b32 s60, s53, s12
	s_cselect_b32 s13, s29, s77
	s_cselect_b32 s12, s28, s76
	s_cselect_b32 s15, s31, s35
	s_cselect_b32 s14, s30, s34
	s_cselect_b32 s58, s54, s56
	s_cselect_b32 s16, s2, s8
	s_cselect_b32 s17, s3, s9
	s_cselect_b32 s18, s26, s10
	s_cselect_b32 s19, s27, s11
	s_or_b32 s59, s60, 0x80
	s_mov_b32 m0, s45
	s_waitcnt vmcnt(14)
	ds_read_b128 v[130:133], v217
	ds_read_b128 v[142:145], v217 offset:1024
	ds_read_b128 v[154:157], v217 offset:2048
	ds_read_b128 v[166:169], v217 offset:3072
	ds_read_b128 v[174:177], v217 offset:4096
	ds_read_b128 v[182:185], v217 offset:5120
	ds_read_b128 v[186:189], v217 offset:6144
	ds_read_b128 v[190:193], v217 offset:7168
	buffer_load_dwordx4 v0, s[8:11], s55 offen lds
	s_mov_b32 m0, s46
	s_nop 0
	buffer_load_dwordx4 v214, s[8:11], s55 offen lds
	s_waitcnt vmcnt(8)
	s_waitcnt lgkmcnt(0)
	s_barrier
	v_mfma_f32_16x16x32_bf16 v[178:181], v[34:37], v[130:133], v[178:181]
	v_mfma_f32_16x16x32_bf16 v[170:173], v[58:61], v[130:133], v[170:173]
	v_mfma_f32_16x16x32_bf16 v[150:153], v[34:37], v[154:157], v[150:153]
	v_mfma_f32_16x16x32_bf16 v[146:149], v[58:61], v[154:157], v[146:149]
	v_mfma_f32_16x16x32_bf16 v[126:129], v[34:37], v[174:177], v[126:129]
	v_mfma_f32_16x16x32_bf16 v[122:125], v[58:61], v[174:177], v[122:125]
	v_mfma_f32_16x16x32_bf16 v[102:105], v[34:37], v[186:189], v[102:105]
	v_mfma_f32_16x16x32_bf16 v[98:101], v[58:61], v[186:189], v[98:101]
	v_mfma_f32_16x16x32_bf16 v[178:181], v[46:49], v[142:145], v[178:181]
	v_mfma_f32_16x16x32_bf16 v[170:173], v[70:73], v[142:145], v[170:173]
	v_mfma_f32_16x16x32_bf16 v[150:153], v[46:49], v[166:169], v[150:153]
	v_mfma_f32_16x16x32_bf16 v[146:149], v[70:73], v[166:169], v[146:149]
	v_mfma_f32_16x16x32_bf16 v[126:129], v[46:49], v[182:185], v[126:129]
	v_mfma_f32_16x16x32_bf16 v[122:125], v[70:73], v[182:185], v[122:125]
	v_mfma_f32_16x16x32_bf16 v[102:105], v[46:49], v[190:193], v[102:105]
	v_mfma_f32_16x16x32_bf16 v[98:101], v[70:73], v[190:193], v[98:101]
	v_mfma_f32_16x16x32_bf16 v[162:165], v[82:85], v[130:133], v[162:165]
	v_mfma_f32_16x16x32_bf16 v[138:141], v[82:85], v[154:157], v[138:141]
	v_mfma_f32_16x16x32_bf16 v[134:137], v[106:109], v[154:157], v[134:137]
	v_mfma_f32_16x16x32_bf16 v[114:117], v[82:85], v[174:177], v[114:117]
	v_mfma_f32_16x16x32_bf16 v[110:113], v[106:109], v[174:177], v[110:113]
	v_mfma_f32_16x16x32_bf16 v[90:93], v[82:85], v[186:189], v[90:93]
	v_mfma_f32_16x16x32_bf16 v[86:89], v[106:109], v[186:189], v[86:89]
	v_mfma_f32_16x16x32_bf16 v[162:165], v[94:97], v[142:145], v[162:165]
	v_mfma_f32_16x16x32_bf16 v[130:133], v[106:109], v[130:133], v[158:161]
	v_mfma_f32_16x16x32_bf16 v[138:141], v[94:97], v[166:169], v[138:141]
	v_mfma_f32_16x16x32_bf16 v[134:137], v[118:121], v[166:169], v[134:137]
	v_mfma_f32_16x16x32_bf16 v[114:117], v[94:97], v[182:185], v[114:117]
	v_mfma_f32_16x16x32_bf16 v[110:113], v[118:121], v[182:185], v[110:113]
	v_mfma_f32_16x16x32_bf16 v[90:93], v[94:97], v[190:193], v[90:93]
	v_mfma_f32_16x16x32_bf16 v[86:89], v[118:121], v[190:193], v[86:89]
	v_mfma_f32_16x16x32_bf16 v[130:133], v[118:121], v[142:145], v[130:133]
	s_barrier
	s_mov_b32 m0, s92
	ds_read_b128 v[142:145], v217 offset:16384
	ds_read_b128 v[154:157], v217 offset:17408
	ds_read_b128 v[158:161], v217 offset:18432
	ds_read_b128 v[166:169], v217 offset:19456
	ds_read_b128 v[174:177], v217 offset:20480
	ds_read_b128 v[182:185], v217 offset:21504
	ds_read_b128 v[186:189], v217 offset:22528
	ds_read_b128 v[190:193], v217 offset:23552
	buffer_load_dwordx4 v199, s[12:15], s58 offen lds
	s_mov_b32 m0, s93
	s_add_i32 s61, s58, 0x20000
	buffer_load_dwordx4 v215, s[12:15], s58 offen lds
	s_mov_b32 m0, s94
	s_nop 0
	buffer_load_dwordx4 v199, s[12:15], s61 offen lds
	s_mov_b32 m0, s95
	s_nop 0
	buffer_load_dwordx4 v215, s[12:15], s61 offen lds
	s_mov_b32 m0, s44
	s_nop 0
	buffer_load_dwordx4 v0, s[16:19], s60 offen lds
	s_mov_b32 m0, s36
	s_nop 0
	buffer_load_dwordx4 v214, s[16:19], s60 offen lds
	s_waitcnt vmcnt(8)
	s_waitcnt lgkmcnt(0)
	s_barrier
	v_mfma_f32_16x16x32_bf16 v[78:81], v[34:37], v[142:145], v[78:81]
	v_mfma_f32_16x16x32_bf16 v[74:77], v[58:61], v[142:145], v[74:77]
	v_mfma_f32_16x16x32_bf16 v[54:57], v[34:37], v[158:161], v[54:57]
	v_mfma_f32_16x16x32_bf16 v[50:53], v[58:61], v[158:161], v[50:53]
	v_mfma_f32_16x16x32_bf16 v[30:33], v[34:37], v[174:177], v[30:33]
	v_mfma_f32_16x16x32_bf16 v[26:29], v[58:61], v[174:177], v[26:29]
	v_mfma_f32_16x16x32_bf16 v[14:17], v[34:37], v[186:189], v[14:17]
	v_mfma_f32_16x16x32_bf16 v[10:13], v[58:61], v[186:189], v[10:13]
	v_mfma_f32_16x16x32_bf16 v[78:81], v[46:49], v[154:157], v[78:81]
	v_mfma_f32_16x16x32_bf16 v[74:77], v[70:73], v[154:157], v[74:77]
	v_mfma_f32_16x16x32_bf16 v[54:57], v[46:49], v[166:169], v[54:57]
	v_mfma_f32_16x16x32_bf16 v[50:53], v[70:73], v[166:169], v[50:53]
	v_mfma_f32_16x16x32_bf16 v[30:33], v[46:49], v[182:185], v[30:33]
	v_mfma_f32_16x16x32_bf16 v[26:29], v[70:73], v[182:185], v[26:29]
	v_mfma_f32_16x16x32_bf16 v[14:17], v[46:49], v[190:193], v[14:17]
	v_mfma_f32_16x16x32_bf16 v[10:13], v[70:73], v[190:193], v[10:13]
	v_mfma_f32_16x16x32_bf16 v[42:45], v[82:85], v[158:161], v[42:45]
	v_mfma_f32_16x16x32_bf16 v[38:41], v[106:109], v[158:161], v[38:41]
	v_mfma_f32_16x16x32_bf16 v[22:25], v[82:85], v[174:177], v[22:25]
	v_mfma_f32_16x16x32_bf16 v[18:21], v[106:109], v[174:177], v[18:21]
	v_mfma_f32_16x16x32_bf16 v[6:9], v[82:85], v[186:189], v[6:9]
	v_mfma_f32_16x16x32_bf16 v[2:5], v[106:109], v[186:189], v[2:5]
	v_mfma_f32_16x16x32_bf16 v[34:37], v[82:85], v[142:145], v[66:69]
	v_mfma_f32_16x16x32_bf16 v[46:49], v[106:109], v[142:145], v[62:65]
	v_mfma_f32_16x16x32_bf16 v[42:45], v[94:97], v[166:169], v[42:45]
	v_mfma_f32_16x16x32_bf16 v[38:41], v[118:121], v[166:169], v[38:41]
	v_mfma_f32_16x16x32_bf16 v[22:25], v[94:97], v[182:185], v[22:25]
	v_mfma_f32_16x16x32_bf16 v[18:21], v[118:121], v[182:185], v[18:21]
	v_mfma_f32_16x16x32_bf16 v[6:9], v[94:97], v[190:193], v[6:9]
	v_mfma_f32_16x16x32_bf16 v[2:5], v[118:121], v[190:193], v[2:5]
	v_mfma_f32_16x16x32_bf16 v[34:37], v[94:97], v[154:157], v[34:37]
	v_mfma_f32_16x16x32_bf16 v[46:49], v[118:121], v[154:157], v[46:49]
	s_barrier
; #define PG8_WAIT_V(n) asm volatile("s_waitcnt vmcnt(" #n ")" ::: "memory")
; template <class Epi, bool ALIGN_EPI, bool SP2, class Hook>
; __device__ __forceinline__ void gemm_phase(LAS unsigned char* lds, const Gemm g, const StaticOrder& S, const Epi& E, Acc& acc, const bool fresh, const Hook& H, const int wave_id) {
;     ...
;         for (int t = t0; t < nt; t += 2) {
;             const bool last = (t == nt - 2);
;             const Src a1 = cA + (size_t)(t + 1) * kstep;
;             const Src a2 = last ? nA : cA + (size_t)(t + 2) * kstep, b2 = last ? nB : cB + (size_t)(t + 2) * kstep;
;             const Src a3 = a2 + kstep, b3 = b2 + kstep;
;             if (last && has_next) H(nxt);
;             if constexpr (SP2) {
;             PG8_TRIP_SP2(PG8_WAIT_V(8));
	v_add_u32_e32 v70, 0x18000, v216
	v_add_u32_e32 v118, 0x1c000, v216
	ds_read_b128 v[58:61], v70
	ds_read_b128 v[62:65], v70 offset:1024
	ds_read_b128 v[66:69], v70 offset:2048
	ds_read_b128 v[70:73], v70 offset:3072
	ds_read_b128 v[82:85], v118
	ds_read_b128 v[94:97], v118 offset:1024
	ds_read_b128 v[106:109], v118 offset:2048
	ds_read_b128 v[118:121], v118 offset:3072
	s_add_i32 s60, s60, 0x20000
	s_mov_b32 m0, s37
	ds_read_b128 v[142:145], v217 offset:32768
	ds_read_b128 v[154:157], v217 offset:33792
	ds_read_b128 v[166:169], v217 offset:34816
	ds_read_b128 v[174:177], v217 offset:35840
	ds_read_b128 v[182:185], v217 offset:36864
	ds_read_b128 v[186:189], v217 offset:37888
	ds_read_b128 v[190:193], v217 offset:38912
	ds_read_b128 v[194:197], v217 offset:39936
	buffer_load_dwordx4 v0, s[16:19], s60 offen lds
	s_mov_b32 m0, s38
	s_nop 0
	buffer_load_dwordx4 v214, s[16:19], s60 offen lds
	s_waitcnt vmcnt(8)
	s_waitcnt lgkmcnt(0)
	s_barrier
	v_mfma_f32_16x16x32_bf16 v[158:161], v[58:61], v[142:145], v[178:181]
	v_mfma_f32_16x16x32_bf16 v[178:181], v[62:65], v[154:157], v[158:161]
	v_mfma_f32_16x16x32_bf16 v[158:161], v[66:69], v[142:145], v[170:173]
	v_mfma_f32_16x16x32_bf16 v[150:153], v[58:61], v[166:169], v[150:153]
	v_mfma_f32_16x16x32_bf16 v[146:149], v[66:69], v[166:169], v[146:149]
	v_mfma_f32_16x16x32_bf16 v[126:129], v[58:61], v[182:185], v[126:129]
	v_mfma_f32_16x16x32_bf16 v[122:125], v[66:69], v[182:185], v[122:125]
	v_mfma_f32_16x16x32_bf16 v[102:105], v[58:61], v[190:193], v[102:105]
	v_mfma_f32_16x16x32_bf16 v[98:101], v[66:69], v[190:193], v[98:101]
	v_mfma_f32_16x16x32_bf16 v[170:173], v[70:73], v[154:157], v[158:161]
	v_mfma_f32_16x16x32_bf16 v[150:153], v[62:65], v[174:177], v[150:153]
	v_mfma_f32_16x16x32_bf16 v[146:149], v[70:73], v[174:177], v[146:149]
	v_mfma_f32_16x16x32_bf16 v[126:129], v[62:65], v[186:189], v[126:129]
	v_mfma_f32_16x16x32_bf16 v[122:125], v[70:73], v[186:189], v[122:125]
	v_mfma_f32_16x16x32_bf16 v[102:105], v[62:65], v[194:197], v[102:105]
	v_mfma_f32_16x16x32_bf16 v[98:101], v[70:73], v[194:197], v[98:101]
	v_mfma_f32_16x16x32_bf16 v[158:161], v[82:85], v[142:145], v[162:165]
	v_mfma_f32_16x16x32_bf16 v[130:133], v[106:109], v[142:145], v[130:133]
	v_mfma_f32_16x16x32_bf16 v[162:165], v[94:97], v[154:157], v[158:161]
	v_mfma_f32_16x16x32_bf16 v[158:161], v[118:121], v[154:157], v[130:133]
	v_mfma_f32_16x16x32_bf16 v[130:133], v[82:85], v[166:169], v[138:141]
	v_mfma_f32_16x16x32_bf16 v[138:141], v[94:97], v[174:177], v[130:133]
	v_mfma_f32_16x16x32_bf16 v[130:133], v[106:109], v[166:169], v[134:137]
	v_mfma_f32_16x16x32_bf16 v[114:117], v[82:85], v[182:185], v[114:117]
	v_mfma_f32_16x16x32_bf16 v[110:113], v[106:109], v[182:185], v[110:113]
	v_mfma_f32_16x16x32_bf16 v[90:93], v[82:85], v[190:193], v[90:93]
	v_mfma_f32_16x16x32_bf16 v[86:89], v[106:109], v[190:193], v[86:89]
	v_mfma_f32_16x16x32_bf16 v[134:137], v[118:121], v[174:177], v[130:133]
	v_mfma_f32_16x16x32_bf16 v[114:117], v[94:97], v[186:189], v[114:117]
	v_mfma_f32_16x16x32_bf16 v[110:113], v[118:121], v[186:189], v[110:113]
	v_mfma_f32_16x16x32_bf16 v[90:93], v[94:97], v[194:197], v[90:93]
	v_mfma_f32_16x16x32_bf16 v[86:89], v[118:121], v[194:197], v[86:89]
	s_barrier
	s_mov_b32 m0, s39
	s_or_b32 s60, s58, 0x80
	ds_read_b128 v[130:133], v217 offset:49152
	ds_read_b128 v[142:145], v217 offset:50176
	ds_read_b128 v[154:157], v217 offset:51200
	ds_read_b128 v[166:169], v217 offset:52224
	ds_read_b128 v[174:177], v217 offset:53248
	ds_read_b128 v[182:185], v217 offset:54272
	ds_read_b128 v[186:189], v217 offset:55296
	ds_read_b128 v[190:193], v217 offset:56320
	buffer_load_dwordx4 v199, s[12:15], s60 offen lds
	s_mov_b32 m0, s40
	s_add_i32 s58, s58, 0x20080
	buffer_load_dwordx4 v215, s[12:15], s60 offen lds
	s_mov_b32 m0, s43
	s_nop 0
	buffer_load_dwordx4 v199, s[12:15], s58 offen lds
	s_mov_b32 m0, s42
	s_nop 0
	buffer_load_dwordx4 v215, s[12:15], s58 offen lds
	s_mov_b32 m0, s41
	s_nop 0
	buffer_load_dwordx4 v0, s[16:19], s59 offen lds
	s_mov_b32 m0, s33
	s_nop 0
	buffer_load_dwordx4 v214, s[16:19], s59 offen lds
	s_waitcnt vmcnt(8)
	s_waitcnt lgkmcnt(0)
	s_barrier
	v_mfma_f32_16x16x32_bf16 v[78:81], v[58:61], v[130:133], v[78:81]
	v_mfma_f32_16x16x32_bf16 v[74:77], v[66:69], v[130:133], v[74:77]
	v_mfma_f32_16x16x32_bf16 v[54:57], v[58:61], v[154:157], v[54:57]
	v_mfma_f32_16x16x32_bf16 v[50:53], v[66:69], v[154:157], v[50:53]
	v_mfma_f32_16x16x32_bf16 v[30:33], v[58:61], v[174:177], v[30:33]
	v_mfma_f32_16x16x32_bf16 v[26:29], v[66:69], v[174:177], v[26:29]
	v_mfma_f32_16x16x32_bf16 v[14:17], v[58:61], v[186:189], v[14:17]
	v_mfma_f32_16x16x32_bf16 v[10:13], v[66:69], v[186:189], v[10:13]
	v_mfma_f32_16x16x32_bf16 v[78:81], v[62:65], v[142:145], v[78:81]
	v_mfma_f32_16x16x32_bf16 v[74:77], v[70:73], v[142:145], v[74:77]
	v_mfma_f32_16x16x32_bf16 v[54:57], v[62:65], v[166:169], v[54:57]
	v_mfma_f32_16x16x32_bf16 v[50:53], v[70:73], v[166:169], v[50:53]
	v_mfma_f32_16x16x32_bf16 v[30:33], v[62:65], v[182:185], v[30:33]
	v_mfma_f32_16x16x32_bf16 v[26:29], v[70:73], v[182:185], v[26:29]
	v_mfma_f32_16x16x32_bf16 v[14:17], v[62:65], v[190:193], v[14:17]
	v_mfma_f32_16x16x32_bf16 v[10:13], v[70:73], v[190:193], v[10:13]
	v_mfma_f32_16x16x32_bf16 v[34:37], v[82:85], v[130:133], v[34:37]
	v_mfma_f32_16x16x32_bf16 v[66:69], v[94:97], v[142:145], v[34:37]
	v_mfma_f32_16x16x32_bf16 v[34:37], v[106:109], v[130:133], v[46:49]
	v_mfma_f32_16x16x32_bf16 v[62:65], v[118:121], v[142:145], v[34:37]
	v_mfma_f32_16x16x32_bf16 v[34:37], v[82:85], v[154:157], v[42:45]
	v_mfma_f32_16x16x32_bf16 v[42:45], v[94:97], v[166:169], v[34:37]
	v_mfma_f32_16x16x32_bf16 v[34:37], v[106:109], v[154:157], v[38:41]
	v_mfma_f32_16x16x32_bf16 v[22:25], v[82:85], v[174:177], v[22:25]
	v_mfma_f32_16x16x32_bf16 v[18:21], v[106:109], v[174:177], v[18:21]
	v_mfma_f32_16x16x32_bf16 v[6:9], v[82:85], v[186:189], v[6:9]
	v_mfma_f32_16x16x32_bf16 v[2:5], v[106:109], v[186:189], v[2:5]
	v_mfma_f32_16x16x32_bf16 v[38:41], v[118:121], v[166:169], v[34:37]
	v_mfma_f32_16x16x32_bf16 v[22:25], v[94:97], v[182:185], v[22:25]
	v_mfma_f32_16x16x32_bf16 v[18:21], v[118:121], v[182:185], v[18:21]
	v_mfma_f32_16x16x32_bf16 v[6:9], v[94:97], v[190:193], v[6:9]
	v_mfma_f32_16x16x32_bf16 v[2:5], v[118:121], v[190:193], v[2:5]
	s_barrier
	s_add_i32 s57, s57, 2
	s_addk_i32 s55, 0x100
	s_addk_i32 s56, 0x100
	s_cmp_gt_u32 s57, 5
	s_cbranch_scc0 .LBB0_702
	v_readlane_b32 s8, v251, 45
	v_readlane_b32 s9, v251, 46
	s_and_b64 vcc, exec, s[8:9]
	s_cbranch_vccz .LBB0_705
	s_barrier

; #define PG8_WAIT_V(n) asm volatile("s_waitcnt vmcnt(" #n ")" ::: "memory")
; template <class Epi, bool ALIGN_EPI, bool SP2, class Hook>
; __device__ __forceinline__ void gemm_phase(LAS unsigned char* lds, const Gemm g, const StaticOrder& S, const Epi& E, Acc& acc, const bool fresh, const Hook& H, const int wave_id) {
;     ...
;         for (int t = t0; t < nt; t += 2) {
;             const bool last = (t == nt - 2);
;             const Src a1 = cA + (size_t)(t + 1) * kstep;
;             const Src a2 = last ? nA : cA + (size_t)(t + 2) * kstep, b2 = last ? nB : cB + (size_t)(t + 2) * kstep;
;             const Src a3 = a2 + kstep, b3 = b2 + kstep;
;             if (last && has_next) H(nxt);
;             if constexpr (SP2) {
;             PG8_TRIP_SP2(PG8_WAIT_V(8));
.LBB0_779:
	v_add_u32_e32 v0, 0x10000, v230
	s_waitcnt vmcnt(0)
	ds_read_b128 v[130:133], v0
	ds_read_b128 v[134:137], v0 offset:1024
	ds_read_b128 v[138:141], v0 offset:2048
	ds_read_b128 v[142:145], v0 offset:3072
	v_add_u32_e32 v0, 0x14000, v230
	ds_read_b128 v[146:149], v0
	ds_read_b128 v[150:153], v0 offset:1024
	ds_read_b128 v[154:157], v0 offset:2048
	ds_read_b128 v[158:161], v0 offset:3072
	s_add_i32 s12, s2, 0xfffe0080
	s_cmp_eq_u32 s63, 4
	s_cselect_b32 s66, s60, s12
	s_cselect_b32 s13, s53, s77
	s_cselect_b32 s12, s52, s76
	s_cselect_b32 s15, s55, s7
	s_cselect_b32 s14, s54, s6
	s_cselect_b32 s64, s61, s3
	s_cselect_b32 s16, s34, s8
	s_cselect_b32 s17, s35, s9
	s_cselect_b32 s18, s50, s10
	s_cselect_b32 s19, s51, s11
	s_or_b32 s65, s66, 0x80
	s_mov_b32 m0, s45
	ds_read_b128 v[162:165], v231
	ds_read_b128 v[166:169], v231 offset:1024
	ds_read_b128 v[170:173], v231 offset:2048
	ds_read_b128 v[174:177], v231 offset:3072
	ds_read_b128 v[178:181], v231 offset:4096
	ds_read_b128 v[182:185], v231 offset:5120
	ds_read_b128 v[186:189], v231 offset:6144
	ds_read_b128 v[190:193], v231 offset:7168
	buffer_load_dwordx4 v199, s[8:11], s2 offen lds
	s_mov_b32 m0, s46
	s_nop 0
	buffer_load_dwordx4 v228, s[8:11], s2 offen lds
	s_waitcnt vmcnt(8)
	s_waitcnt lgkmcnt(0)
	s_barrier
	v_mfma_f32_16x16x32_bf16 v[126:129], v[130:133], v[162:165], v[126:129]
	v_mfma_f32_16x16x32_bf16 v[122:125], v[138:141], v[162:165], v[122:125]
	v_mfma_f32_16x16x32_bf16 v[118:121], v[130:133], v[170:173], v[118:121]
	v_mfma_f32_16x16x32_bf16 v[114:117], v[138:141], v[170:173], v[114:117]
	v_mfma_f32_16x16x32_bf16 v[110:113], v[130:133], v[178:181], v[110:113]
	v_mfma_f32_16x16x32_bf16 v[106:109], v[138:141], v[178:181], v[106:109]
	v_mfma_f32_16x16x32_bf16 v[102:105], v[130:133], v[186:189], v[102:105]
	v_mfma_f32_16x16x32_bf16 v[98:101], v[138:141], v[186:189], v[98:101]
	v_mfma_f32_16x16x32_bf16 v[126:129], v[134:137], v[166:169], v[126:129]
	v_mfma_f32_16x16x32_bf16 v[122:125], v[142:145], v[166:169], v[122:125]
	v_mfma_f32_16x16x32_bf16 v[118:121], v[134:137], v[174:177], v[118:121]
	v_mfma_f32_16x16x32_bf16 v[114:117], v[142:145], v[174:177], v[114:117]
	v_mfma_f32_16x16x32_bf16 v[110:113], v[134:137], v[182:185], v[110:113]
	v_mfma_f32_16x16x32_bf16 v[106:109], v[142:145], v[182:185], v[106:109]
	v_mfma_f32_16x16x32_bf16 v[102:105], v[134:137], v[190:193], v[102:105]
	v_mfma_f32_16x16x32_bf16 v[98:101], v[142:145], v[190:193], v[98:101]
	v_mfma_f32_16x16x32_bf16 v[94:97], v[146:149], v[162:165], v[94:97]
	v_mfma_f32_16x16x32_bf16 v[90:93], v[154:157], v[162:165], v[90:93]
	v_mfma_f32_16x16x32_bf16 v[86:89], v[146:149], v[170:173], v[86:89]
	v_mfma_f32_16x16x32_bf16 v[82:85], v[154:157], v[170:173], v[82:85]
	v_mfma_f32_16x16x32_bf16 v[78:81], v[146:149], v[178:181], v[78:81]
	v_mfma_f32_16x16x32_bf16 v[74:77], v[154:157], v[178:181], v[74:77]
	v_mfma_f32_16x16x32_bf16 v[70:73], v[146:149], v[186:189], v[70:73]
	v_mfma_f32_16x16x32_bf16 v[66:69], v[154:157], v[186:189], v[66:69]
	v_mfma_f32_16x16x32_bf16 v[94:97], v[150:153], v[166:169], v[94:97]
	v_mfma_f32_16x16x32_bf16 v[90:93], v[158:161], v[166:169], v[90:93]
	v_mfma_f32_16x16x32_bf16 v[86:89], v[150:153], v[174:177], v[86:89]
	v_mfma_f32_16x16x32_bf16 v[82:85], v[158:161], v[174:177], v[82:85]
	v_mfma_f32_16x16x32_bf16 v[78:81], v[150:153], v[182:185], v[78:81]
	v_mfma_f32_16x16x32_bf16 v[74:77], v[158:161], v[182:185], v[74:77]
	v_mfma_f32_16x16x32_bf16 v[70:73], v[150:153], v[190:193], v[70:73]
	v_mfma_f32_16x16x32_bf16 v[66:69], v[158:161], v[190:193], v[66:69]
	s_barrier
	s_mov_b32 m0, s92
	ds_read_b128 v[162:165], v231 offset:16384
	ds_read_b128 v[166:169], v231 offset:17408
	ds_read_b128 v[170:173], v231 offset:18432
	ds_read_b128 v[174:177], v231 offset:19456
	ds_read_b128 v[178:181], v231 offset:20480
	ds_read_b128 v[182:185], v231 offset:21504
	ds_read_b128 v[186:189], v231 offset:22528
	ds_read_b128 v[190:193], v231 offset:23552
	buffer_load_dwordx4 v227, s[12:15], s64 offen lds
	s_mov_b32 m0, s93
	s_add_i32 s67, s64, 0x20000
	buffer_load_dwordx4 v229, s[12:15], s64 offen lds
	s_mov_b32 m0, s94
	s_nop 0
	buffer_load_dwordx4 v227, s[12:15], s67 offen lds
	s_mov_b32 m0, s95
	s_nop 0
	buffer_load_dwordx4 v229, s[12:15], s67 offen lds
	s_mov_b32 m0, s44
	s_nop 0
	buffer_load_dwordx4 v199, s[16:19], s66 offen lds
	s_mov_b32 m0, s36
	s_nop 0
	buffer_load_dwordx4 v228, s[16:19], s66 offen lds
	s_waitcnt vmcnt(8)
	s_waitcnt lgkmcnt(0)
	s_barrier
	v_mfma_f32_16x16x32_bf16 v[62:65], v[130:133], v[162:165], v[62:65]
	v_mfma_f32_16x16x32_bf16 v[58:61], v[138:141], v[162:165], v[58:61]
	v_mfma_f32_16x16x32_bf16 v[54:57], v[130:133], v[170:173], v[54:57]
	v_mfma_f32_16x16x32_bf16 v[50:53], v[138:141], v[170:173], v[50:53]
	v_mfma_f32_16x16x32_bf16 v[46:49], v[130:133], v[178:181], v[46:49]
	v_mfma_f32_16x16x32_bf16 v[42:45], v[138:141], v[178:181], v[42:45]
	v_mfma_f32_16x16x32_bf16 v[38:41], v[130:133], v[186:189], v[38:41]
	v_mfma_f32_16x16x32_bf16 v[34:37], v[138:141], v[186:189], v[34:37]
	v_mfma_f32_16x16x32_bf16 v[62:65], v[134:137], v[166:169], v[62:65]
	v_mfma_f32_16x16x32_bf16 v[58:61], v[142:145], v[166:169], v[58:61]
	v_mfma_f32_16x16x32_bf16 v[54:57], v[134:137], v[174:177], v[54:57]
	v_mfma_f32_16x16x32_bf16 v[50:53], v[142:145], v[174:177], v[50:53]
	v_mfma_f32_16x16x32_bf16 v[46:49], v[134:137], v[182:185], v[46:49]
	v_mfma_f32_16x16x32_bf16 v[42:45], v[142:145], v[182:185], v[42:45]
	v_mfma_f32_16x16x32_bf16 v[38:41], v[134:137], v[190:193], v[38:41]
	v_mfma_f32_16x16x32_bf16 v[34:37], v[142:145], v[190:193], v[34:37]
	v_mfma_f32_16x16x32_bf16 v[30:33], v[146:149], v[162:165], v[30:33]
	v_mfma_f32_16x16x32_bf16 v[26:29], v[154:157], v[162:165], v[26:29]
	v_mfma_f32_16x16x32_bf16 v[22:25], v[146:149], v[170:173], v[22:25]
	v_mfma_f32_16x16x32_bf16 v[18:21], v[154:157], v[170:173], v[18:21]
	v_mfma_f32_16x16x32_bf16 v[14:17], v[146:149], v[178:181], v[14:17]
	v_mfma_f32_16x16x32_bf16 v[10:13], v[154:157], v[178:181], v[10:13]
	v_mfma_f32_16x16x32_bf16 v[6:9], v[146:149], v[186:189], v[6:9]
	v_mfma_f32_16x16x32_bf16 v[2:5], v[154:157], v[186:189], v[2:5]
	v_mfma_f32_16x16x32_bf16 v[30:33], v[150:153], v[166:169], v[30:33]
	v_mfma_f32_16x16x32_bf16 v[26:29], v[158:161], v[166:169], v[26:29]
	v_mfma_f32_16x16x32_bf16 v[22:25], v[150:153], v[174:177], v[22:25]
	v_mfma_f32_16x16x32_bf16 v[18:21], v[158:161], v[174:177], v[18:21]
	v_mfma_f32_16x16x32_bf16 v[14:17], v[150:153], v[182:185], v[14:17]
	v_mfma_f32_16x16x32_bf16 v[10:13], v[158:161], v[182:185], v[10:13]
	v_mfma_f32_16x16x32_bf16 v[6:9], v[150:153], v[190:193], v[6:9]
	v_mfma_f32_16x16x32_bf16 v[2:5], v[158:161], v[190:193], v[2:5]
	s_barrier
; #define PG8_WAIT_V(n) asm volatile("s_waitcnt vmcnt(" #n ")" ::: "memory")
; template <class Epi, bool ALIGN_EPI, bool SP2, class Hook>
; __device__ __forceinline__ void gemm_phase(LAS unsigned char* lds, const Gemm g, const StaticOrder& S, const Epi& E, Acc& acc, const bool fresh, const Hook& H, const int wave_id) {
;     ...
;         for (int t = t0; t < nt; t += 2) {
;             const bool last = (t == nt - 2);
;             const Src a1 = cA + (size_t)(t + 1) * kstep;
;             const Src a2 = last ? nA : cA + (size_t)(t + 2) * kstep, b2 = last ? nB : cB + (size_t)(t + 2) * kstep;
;             const Src a3 = a2 + kstep, b3 = b2 + kstep;
;             if (last && has_next) H(nxt);
;             if constexpr (SP2) {
;             PG8_TRIP_SP2(PG8_WAIT_V(8));
	v_add_u32_e32 v0, 0x18000, v230
	ds_read_b128 v[130:133], v0
	ds_read_b128 v[134:137], v0 offset:1024
	ds_read_b128 v[138:141], v0 offset:2048
	ds_read_b128 v[142:145], v0 offset:3072
	v_add_u32_e32 v0, 0x1c000, v230
	ds_read_b128 v[146:149], v0
	ds_read_b128 v[150:153], v0 offset:1024
	ds_read_b128 v[154:157], v0 offset:2048
	ds_read_b128 v[158:161], v0 offset:3072
	s_add_i32 s66, s66, 0x20000
	s_mov_b32 m0, s37
	ds_read_b128 v[162:165], v231 offset:32768
	ds_read_b128 v[166:169], v231 offset:33792
	ds_read_b128 v[170:173], v231 offset:34816
	ds_read_b128 v[174:177], v231 offset:35840
	ds_read_b128 v[178:181], v231 offset:36864
	ds_read_b128 v[182:185], v231 offset:37888
	ds_read_b128 v[186:189], v231 offset:38912
	ds_read_b128 v[190:193], v231 offset:39936
	buffer_load_dwordx4 v199, s[16:19], s66 offen lds
	s_mov_b32 m0, s38
	s_nop 0
	buffer_load_dwordx4 v228, s[16:19], s66 offen lds
	s_waitcnt vmcnt(8)
	s_waitcnt lgkmcnt(0)
	s_barrier
	v_mfma_f32_16x16x32_bf16 v[126:129], v[130:133], v[162:165], v[126:129]
	v_mfma_f32_16x16x32_bf16 v[122:125], v[138:141], v[162:165], v[122:125]
	v_mfma_f32_16x16x32_bf16 v[118:121], v[130:133], v[170:173], v[118:121]
	v_mfma_f32_16x16x32_bf16 v[114:117], v[138:141], v[170:173], v[114:117]
	v_mfma_f32_16x16x32_bf16 v[110:113], v[130:133], v[178:181], v[110:113]
	v_mfma_f32_16x16x32_bf16 v[106:109], v[138:141], v[178:181], v[106:109]
	v_mfma_f32_16x16x32_bf16 v[102:105], v[130:133], v[186:189], v[102:105]
	v_mfma_f32_16x16x32_bf16 v[98:101], v[138:141], v[186:189], v[98:101]
	v_mfma_f32_16x16x32_bf16 v[126:129], v[134:137], v[166:169], v[126:129]
	v_mfma_f32_16x16x32_bf16 v[122:125], v[142:145], v[166:169], v[122:125]
	v_mfma_f32_16x16x32_bf16 v[118:121], v[134:137], v[174:177], v[118:121]
	v_mfma_f32_16x16x32_bf16 v[114:117], v[142:145], v[174:177], v[114:117]
	v_mfma_f32_16x16x32_bf16 v[110:113], v[134:137], v[182:185], v[110:113]
	v_mfma_f32_16x16x32_bf16 v[106:109], v[142:145], v[182:185], v[106:109]
	v_mfma_f32_16x16x32_bf16 v[102:105], v[134:137], v[190:193], v[102:105]
	v_mfma_f32_16x16x32_bf16 v[98:101], v[142:145], v[190:193], v[98:101]
	v_mfma_f32_16x16x32_bf16 v[94:97], v[146:149], v[162:165], v[94:97]
	v_mfma_f32_16x16x32_bf16 v[90:93], v[154:157], v[162:165], v[90:93]
	v_mfma_f32_16x16x32_bf16 v[86:89], v[146:149], v[170:173], v[86:89]
	v_mfma_f32_16x16x32_bf16 v[82:85], v[154:157], v[170:173], v[82:85]
	v_mfma_f32_16x16x32_bf16 v[78:81], v[146:149], v[178:181], v[78:81]
	v_mfma_f32_16x16x32_bf16 v[74:77], v[154:157], v[178:181], v[74:77]
	v_mfma_f32_16x16x32_bf16 v[70:73], v[146:149], v[186:189], v[70:73]
	v_mfma_f32_16x16x32_bf16 v[66:69], v[154:157], v[186:189], v[66:69]
	v_mfma_f32_16x16x32_bf16 v[94:97], v[150:153], v[166:169], v[94:97]
	v_mfma_f32_16x16x32_bf16 v[90:93], v[158:161], v[166:169], v[90:93]
	v_mfma_f32_16x16x32_bf16 v[86:89], v[150:153], v[174:177], v[86:89]
	v_mfma_f32_16x16x32_bf16 v[82:85], v[158:161], v[174:177], v[82:85]
	v_mfma_f32_16x16x32_bf16 v[78:81], v[150:153], v[182:185], v[78:81]
	v_mfma_f32_16x16x32_bf16 v[74:77], v[158:161], v[182:185], v[74:77]
	v_mfma_f32_16x16x32_bf16 v[70:73], v[150:153], v[190:193], v[70:73]
	v_mfma_f32_16x16x32_bf16 v[66:69], v[158:161], v[190:193], v[66:69]
	s_barrier
	s_mov_b32 m0, s39
	s_or_b32 s66, s64, 0x80
	ds_read_b128 v[162:165], v231 offset:49152
	ds_read_b128 v[166:169], v231 offset:50176
	ds_read_b128 v[170:173], v231 offset:51200
	ds_read_b128 v[174:177], v231 offset:52224
	ds_read_b128 v[178:181], v231 offset:53248
	ds_read_b128 v[182:185], v231 offset:54272
	ds_read_b128 v[186:189], v231 offset:55296
	ds_read_b128 v[190:193], v231 offset:56320
	buffer_load_dwordx4 v227, s[12:15], s66 offen lds
	s_mov_b32 m0, s40
	s_add_i32 s64, s64, 0x20080
	buffer_load_dwordx4 v229, s[12:15], s66 offen lds
	s_mov_b32 m0, s43
	s_nop 0
	buffer_load_dwordx4 v227, s[12:15], s64 offen lds
	s_mov_b32 m0, s42
	s_nop 0
	buffer_load_dwordx4 v229, s[12:15], s64 offen lds
	s_mov_b32 m0, s41
	s_nop 0
	buffer_load_dwordx4 v199, s[16:19], s65 offen lds
	s_mov_b32 m0, s33
	s_nop 0
	buffer_load_dwordx4 v228, s[16:19], s65 offen lds
	s_waitcnt vmcnt(8)
	s_waitcnt lgkmcnt(0)
	s_barrier
	v_mfma_f32_16x16x32_bf16 v[62:65], v[130:133], v[162:165], v[62:65]
	v_mfma_f32_16x16x32_bf16 v[58:61], v[138:141], v[162:165], v[58:61]
	v_mfma_f32_16x16x32_bf16 v[54:57], v[130:133], v[170:173], v[54:57]
	v_mfma_f32_16x16x32_bf16 v[50:53], v[138:141], v[170:173], v[50:53]
	v_mfma_f32_16x16x32_bf16 v[46:49], v[130:133], v[178:181], v[46:49]
	v_mfma_f32_16x16x32_bf16 v[42:45], v[138:141], v[178:181], v[42:45]
	v_mfma_f32_16x16x32_bf16 v[38:41], v[130:133], v[186:189], v[38:41]
	v_mfma_f32_16x16x32_bf16 v[34:37], v[138:141], v[186:189], v[34:37]
	v_mfma_f32_16x16x32_bf16 v[62:65], v[134:137], v[166:169], v[62:65]
	v_mfma_f32_16x16x32_bf16 v[58:61], v[142:145], v[166:169], v[58:61]
	v_mfma_f32_16x16x32_bf16 v[54:57], v[134:137], v[174:177], v[54:57]
	v_mfma_f32_16x16x32_bf16 v[50:53], v[142:145], v[174:177], v[50:53]
	v_mfma_f32_16x16x32_bf16 v[46:49], v[134:137], v[182:185], v[46:49]
	v_mfma_f32_16x16x32_bf16 v[42:45], v[142:145], v[182:185], v[42:45]
	v_mfma_f32_16x16x32_bf16 v[38:41], v[134:137], v[190:193], v[38:41]
	v_mfma_f32_16x16x32_bf16 v[34:37], v[142:145], v[190:193], v[34:37]
	v_mfma_f32_16x16x32_bf16 v[30:33], v[146:149], v[162:165], v[30:33]
	v_mfma_f32_16x16x32_bf16 v[26:29], v[154:157], v[162:165], v[26:29]
	v_mfma_f32_16x16x32_bf16 v[22:25], v[146:149], v[170:173], v[22:25]
	v_mfma_f32_16x16x32_bf16 v[18:21], v[154:157], v[170:173], v[18:21]
	v_mfma_f32_16x16x32_bf16 v[14:17], v[146:149], v[178:181], v[14:17]
	v_mfma_f32_16x16x32_bf16 v[10:13], v[154:157], v[178:181], v[10:13]
	v_mfma_f32_16x16x32_bf16 v[6:9], v[146:149], v[186:189], v[6:9]
	v_mfma_f32_16x16x32_bf16 v[2:5], v[154:157], v[186:189], v[2:5]
	v_mfma_f32_16x16x32_bf16 v[30:33], v[150:153], v[166:169], v[30:33]
	v_mfma_f32_16x16x32_bf16 v[26:29], v[158:161], v[166:169], v[26:29]
	v_mfma_f32_16x16x32_bf16 v[22:25], v[150:153], v[174:177], v[22:25]
	v_mfma_f32_16x16x32_bf16 v[18:21], v[158:161], v[174:177], v[18:21]
	v_mfma_f32_16x16x32_bf16 v[14:17], v[150:153], v[182:185], v[14:17]
	v_mfma_f32_16x16x32_bf16 v[10:13], v[158:161], v[182:185], v[10:13]
	v_mfma_f32_16x16x32_bf16 v[6:9], v[150:153], v[190:193], v[6:9]
	v_mfma_f32_16x16x32_bf16 v[2:5], v[158:161], v[190:193], v[2:5]
	s_barrier
	s_add_i32 s63, s63, 2
	s_addk_i32 s2, 0x100
	s_addk_i32 s3, 0x100
	s_cmp_gt_u32 s63, 5
	s_cbranch_scc0 .LBB0_779
	v_readlane_b32 s2, v251, 45
	v_readlane_b32 s3, v251, 46
	s_and_b64 vcc, exec, s[2:3]
	s_cbranch_vccz .LBB0_782
	s_barrier

; #define PG8_WAIT_V(n) asm volatile("s_waitcnt vmcnt(" #n ")" ::: "memory")
; template <class Epi, bool ALIGN_EPI, bool SP2, class Hook>
; __device__ __forceinline__ void gemm_phase(LAS unsigned char* lds, const Gemm g, const StaticOrder& S, const Epi& E, Acc& acc, const bool fresh, const Hook& H, const int wave_id) {
;     ...
;         for (int t = t0; t < nt; t += 2) {
;             const bool last = (t == nt - 2);
;             const Src a1 = cA + (size_t)(t + 1) * kstep;
;             const Src a2 = last ? nA : cA + (size_t)(t + 2) * kstep, b2 = last ? nB : cB + (size_t)(t + 2) * kstep;
;             const Src a3 = a2 + kstep, b3 = b2 + kstep;
;             if (last && has_next) H(nxt);
;             if constexpr (SP2) {
;             PG8_TRIP_SP2(PG8_WAIT_V(8));
.LBB0_903:
	v_add_u32_e32 v70, 0x10000, v216
	v_add_u32_e32 v118, 0x14000, v216
	ds_read_b128 v[34:37], v70
	ds_read_b128 v[46:49], v70 offset:1024
	ds_read_b128 v[58:61], v70 offset:2048
	ds_read_b128 v[70:73], v70 offset:3072
	ds_read_b128 v[82:85], v118
	ds_read_b128 v[94:97], v118 offset:1024
	ds_read_b128 v[106:109], v118 offset:2048
	ds_read_b128 v[118:121], v118 offset:3072
	s_add_i32 s12, s55, 0xfffe0080
	s_cmp_eq_u32 s57, 4
	s_cselect_b32 s60, s53, s12
	s_cselect_b32 s13, s29, s77
	s_cselect_b32 s12, s28, s76
	s_cselect_b32 s15, s31, s35
	s_cselect_b32 s14, s30, s34
	s_cselect_b32 s58, s54, s56
	s_cselect_b32 s16, s2, s8
	s_cselect_b32 s17, s3, s9
	s_cselect_b32 s18, s26, s10
	s_cselect_b32 s19, s27, s11
	s_or_b32 s59, s60, 0x80
	s_mov_b32 m0, s45
	ds_read_b128 v[130:133], v217
	ds_read_b128 v[142:145], v217 offset:1024
	ds_read_b128 v[154:157], v217 offset:2048
	ds_read_b128 v[166:169], v217 offset:3072
	ds_read_b128 v[174:177], v217 offset:4096
	ds_read_b128 v[182:185], v217 offset:5120
	ds_read_b128 v[186:189], v217 offset:6144
	ds_read_b128 v[190:193], v217 offset:7168
	buffer_load_dwordx4 v0, s[8:11], s55 offen lds
	s_mov_b32 m0, s46
	s_nop 0
	buffer_load_dwordx4 v214, s[8:11], s55 offen lds
	s_waitcnt vmcnt(8)
	s_waitcnt lgkmcnt(0)
	s_barrier
	v_mfma_f32_16x16x32_bf16 v[178:181], v[34:37], v[130:133], v[178:181]
	v_mfma_f32_16x16x32_bf16 v[170:173], v[58:61], v[130:133], v[170:173]
	v_mfma_f32_16x16x32_bf16 v[150:153], v[34:37], v[154:157], v[150:153]
	v_mfma_f32_16x16x32_bf16 v[146:149], v[58:61], v[154:157], v[146:149]
	v_mfma_f32_16x16x32_bf16 v[126:129], v[34:37], v[174:177], v[126:129]
	v_mfma_f32_16x16x32_bf16 v[122:125], v[58:61], v[174:177], v[122:125]
	v_mfma_f32_16x16x32_bf16 v[102:105], v[34:37], v[186:189], v[102:105]
	v_mfma_f32_16x16x32_bf16 v[98:101], v[58:61], v[186:189], v[98:101]
	v_mfma_f32_16x16x32_bf16 v[178:181], v[46:49], v[142:145], v[178:181]
	v_mfma_f32_16x16x32_bf16 v[170:173], v[70:73], v[142:145], v[170:173]
	v_mfma_f32_16x16x32_bf16 v[150:153], v[46:49], v[166:169], v[150:153]
	v_mfma_f32_16x16x32_bf16 v[146:149], v[70:73], v[166:169], v[146:149]
	v_mfma_f32_16x16x32_bf16 v[126:129], v[46:49], v[182:185], v[126:129]
	v_mfma_f32_16x16x32_bf16 v[122:125], v[70:73], v[182:185], v[122:125]
	v_mfma_f32_16x16x32_bf16 v[102:105], v[46:49], v[190:193], v[102:105]
	v_mfma_f32_16x16x32_bf16 v[98:101], v[70:73], v[190:193], v[98:101]
	v_mfma_f32_16x16x32_bf16 v[162:165], v[82:85], v[130:133], v[162:165]
	v_mfma_f32_16x16x32_bf16 v[138:141], v[82:85], v[154:157], v[138:141]
	v_mfma_f32_16x16x32_bf16 v[134:137], v[106:109], v[154:157], v[134:137]
	v_mfma_f32_16x16x32_bf16 v[114:117], v[82:85], v[174:177], v[114:117]
	v_mfma_f32_16x16x32_bf16 v[110:113], v[106:109], v[174:177], v[110:113]
	v_mfma_f32_16x16x32_bf16 v[90:93], v[82:85], v[186:189], v[90:93]
	v_mfma_f32_16x16x32_bf16 v[86:89], v[106:109], v[186:189], v[86:89]
	v_mfma_f32_16x16x32_bf16 v[162:165], v[94:97], v[142:145], v[162:165]
	v_mfma_f32_16x16x32_bf16 v[130:133], v[106:109], v[130:133], v[158:161]
	v_mfma_f32_16x16x32_bf16 v[138:141], v[94:97], v[166:169], v[138:141]
	v_mfma_f32_16x16x32_bf16 v[134:137], v[118:121], v[166:169], v[134:137]
	v_mfma_f32_16x16x32_bf16 v[114:117], v[94:97], v[182:185], v[114:117]
	v_mfma_f32_16x16x32_bf16 v[110:113], v[118:121], v[182:185], v[110:113]
	v_mfma_f32_16x16x32_bf16 v[90:93], v[94:97], v[190:193], v[90:93]
	v_mfma_f32_16x16x32_bf16 v[86:89], v[118:121], v[190:193], v[86:89]
	v_mfma_f32_16x16x32_bf16 v[130:133], v[118:121], v[142:145], v[130:133]
	s_barrier
	s_mov_b32 m0, s92
	ds_read_b128 v[142:145], v217 offset:16384
	ds_read_b128 v[154:157], v217 offset:17408
	ds_read_b128 v[158:161], v217 offset:18432
	ds_read_b128 v[166:169], v217 offset:19456
	ds_read_b128 v[174:177], v217 offset:20480
	ds_read_b128 v[182:185], v217 offset:21504
	ds_read_b128 v[186:189], v217 offset:22528
	ds_read_b128 v[190:193], v217 offset:23552
	buffer_load_dwordx4 v199, s[12:15], s58 offen lds
	s_mov_b32 m0, s93
	s_add_i32 s61, s58, 0x20000
	buffer_load_dwordx4 v215, s[12:15], s58 offen lds
	s_mov_b32 m0, s94
	s_nop 0
	buffer_load_dwordx4 v199, s[12:15], s61 offen lds
	s_mov_b32 m0, s95
	s_nop 0
	buffer_load_dwordx4 v215, s[12:15], s61 offen lds
	s_mov_b32 m0, s44
	s_nop 0
	buffer_load_dwordx4 v0, s[16:19], s60 offen lds
	s_mov_b32 m0, s36
	s_nop 0
	buffer_load_dwordx4 v214, s[16:19], s60 offen lds
	s_waitcnt vmcnt(8)
	s_waitcnt lgkmcnt(0)
	s_barrier
	v_mfma_f32_16x16x32_bf16 v[78:81], v[34:37], v[142:145], v[78:81]
	v_mfma_f32_16x16x32_bf16 v[74:77], v[58:61], v[142:145], v[74:77]
	v_mfma_f32_16x16x32_bf16 v[54:57], v[34:37], v[158:161], v[54:57]
	v_mfma_f32_16x16x32_bf16 v[50:53], v[58:61], v[158:161], v[50:53]
	v_mfma_f32_16x16x32_bf16 v[30:33], v[34:37], v[174:177], v[30:33]
	v_mfma_f32_16x16x32_bf16 v[26:29], v[58:61], v[174:177], v[26:29]
	v_mfma_f32_16x16x32_bf16 v[14:17], v[34:37], v[186:189], v[14:17]
	v_mfma_f32_16x16x32_bf16 v[10:13], v[58:61], v[186:189], v[10:13]
	v_mfma_f32_16x16x32_bf16 v[78:81], v[46:49], v[154:157], v[78:81]
	v_mfma_f32_16x16x32_bf16 v[74:77], v[70:73], v[154:157], v[74:77]
	v_mfma_f32_16x16x32_bf16 v[54:57], v[46:49], v[166:169], v[54:57]
	v_mfma_f32_16x16x32_bf16 v[50:53], v[70:73], v[166:169], v[50:53]
	v_mfma_f32_16x16x32_bf16 v[30:33], v[46:49], v[182:185], v[30:33]
	v_mfma_f32_16x16x32_bf16 v[26:29], v[70:73], v[182:185], v[26:29]
	v_mfma_f32_16x16x32_bf16 v[14:17], v[46:49], v[190:193], v[14:17]
	v_mfma_f32_16x16x32_bf16 v[10:13], v[70:73], v[190:193], v[10:13]
	v_mfma_f32_16x16x32_bf16 v[42:45], v[82:85], v[158:161], v[42:45]
	v_mfma_f32_16x16x32_bf16 v[38:41], v[106:109], v[158:161], v[38:41]
	v_mfma_f32_16x16x32_bf16 v[22:25], v[82:85], v[174:177], v[22:25]
	v_mfma_f32_16x16x32_bf16 v[18:21], v[106:109], v[174:177], v[18:21]
	v_mfma_f32_16x16x32_bf16 v[6:9], v[82:85], v[186:189], v[6:9]
	v_mfma_f32_16x16x32_bf16 v[2:5], v[106:109], v[186:189], v[2:5]
	v_mfma_f32_16x16x32_bf16 v[34:37], v[82:85], v[142:145], v[66:69]
	v_mfma_f32_16x16x32_bf16 v[46:49], v[106:109], v[142:145], v[62:65]
	v_mfma_f32_16x16x32_bf16 v[42:45], v[94:97], v[166:169], v[42:45]
	v_mfma_f32_16x16x32_bf16 v[38:41], v[118:121], v[166:169], v[38:41]
	v_mfma_f32_16x16x32_bf16 v[22:25], v[94:97], v[182:185], v[22:25]
	v_mfma_f32_16x16x32_bf16 v[18:21], v[118:121], v[182:185], v[18:21]
	v_mfma_f32_16x16x32_bf16 v[6:9], v[94:97], v[190:193], v[6:9]
	v_mfma_f32_16x16x32_bf16 v[2:5], v[118:121], v[190:193], v[2:5]
	v_mfma_f32_16x16x32_bf16 v[34:37], v[94:97], v[154:157], v[34:37]
	v_mfma_f32_16x16x32_bf16 v[46:49], v[118:121], v[154:157], v[46:49]
	s_barrier
; #define PG8_WAIT_V(n) asm volatile("s_waitcnt vmcnt(" #n ")" ::: "memory")
; template <class Epi, bool ALIGN_EPI, bool SP2, class Hook>
; __device__ __forceinline__ void gemm_phase(LAS unsigned char* lds, const Gemm g, const StaticOrder& S, const Epi& E, Acc& acc, const bool fresh, const Hook& H, const int wave_id) {
;     ...
;         for (int t = t0; t < nt; t += 2) {
;             const bool last = (t == nt - 2);
;             const Src a1 = cA + (size_t)(t + 1) * kstep;
;             const Src a2 = last ? nA : cA + (size_t)(t + 2) * kstep, b2 = last ? nB : cB + (size_t)(t + 2) * kstep;
;             const Src a3 = a2 + kstep, b3 = b2 + kstep;
;             if (last && has_next) H(nxt);
;             if constexpr (SP2) {
;             PG8_TRIP_SP2(PG8_WAIT_V(8));
	v_add_u32_e32 v70, 0x18000, v216
	v_add_u32_e32 v118, 0x1c000, v216
	ds_read_b128 v[58:61], v70
	ds_read_b128 v[62:65], v70 offset:1024
	ds_read_b128 v[66:69], v70 offset:2048
	ds_read_b128 v[70:73], v70 offset:3072
	ds_read_b128 v[82:85], v118
	ds_read_b128 v[94:97], v118 offset:1024
	ds_read_b128 v[106:109], v118 offset:2048
	ds_read_b128 v[118:121], v118 offset:3072
	s_add_i32 s60, s60, 0x20000
	s_mov_b32 m0, s37
	ds_read_b128 v[142:145], v217 offset:32768
	ds_read_b128 v[154:157], v217 offset:33792
	ds_read_b128 v[166:169], v217 offset:34816
	ds_read_b128 v[174:177], v217 offset:35840
	ds_read_b128 v[182:185], v217 offset:36864
	ds_read_b128 v[186:189], v217 offset:37888
	ds_read_b128 v[190:193], v217 offset:38912
	ds_read_b128 v[194:197], v217 offset:39936
	buffer_load_dwordx4 v0, s[16:19], s60 offen lds
	s_mov_b32 m0, s38
	s_nop 0
	buffer_load_dwordx4 v214, s[16:19], s60 offen lds
	s_waitcnt vmcnt(8)
	s_waitcnt lgkmcnt(0)
	s_barrier
	v_mfma_f32_16x16x32_bf16 v[158:161], v[58:61], v[142:145], v[178:181]
	v_mfma_f32_16x16x32_bf16 v[178:181], v[62:65], v[154:157], v[158:161]
	v_mfma_f32_16x16x32_bf16 v[158:161], v[66:69], v[142:145], v[170:173]
	v_mfma_f32_16x16x32_bf16 v[150:153], v[58:61], v[166:169], v[150:153]
	v_mfma_f32_16x16x32_bf16 v[146:149], v[66:69], v[166:169], v[146:149]
	v_mfma_f32_16x16x32_bf16 v[126:129], v[58:61], v[182:185], v[126:129]
	v_mfma_f32_16x16x32_bf16 v[122:125], v[66:69], v[182:185], v[122:125]
	v_mfma_f32_16x16x32_bf16 v[102:105], v[58:61], v[190:193], v[102:105]
	v_mfma_f32_16x16x32_bf16 v[98:101], v[66:69], v[190:193], v[98:101]
	v_mfma_f32_16x16x32_bf16 v[170:173], v[70:73], v[154:157], v[158:161]
	v_mfma_f32_16x16x32_bf16 v[150:153], v[62:65], v[174:177], v[150:153]
	v_mfma_f32_16x16x32_bf16 v[146:149], v[70:73], v[174:177], v[146:149]
	v_mfma_f32_16x16x32_bf16 v[126:129], v[62:65], v[186:189], v[126:129]
	v_mfma_f32_16x16x32_bf16 v[122:125], v[70:73], v[186:189], v[122:125]
	v_mfma_f32_16x16x32_bf16 v[102:105], v[62:65], v[194:197], v[102:105]
	v_mfma_f32_16x16x32_bf16 v[98:101], v[70:73], v[194:197], v[98:101]
	v_mfma_f32_16x16x32_bf16 v[158:161], v[82:85], v[142:145], v[162:165]
	v_mfma_f32_16x16x32_bf16 v[130:133], v[106:109], v[142:145], v[130:133]
	v_mfma_f32_16x16x32_bf16 v[162:165], v[94:97], v[154:157], v[158:161]
	v_mfma_f32_16x16x32_bf16 v[158:161], v[118:121], v[154:157], v[130:133]
	v_mfma_f32_16x16x32_bf16 v[130:133], v[82:85], v[166:169], v[138:141]
	v_mfma_f32_16x16x32_bf16 v[138:141], v[94:97], v[174:177], v[130:133]
	v_mfma_f32_16x16x32_bf16 v[130:133], v[106:109], v[166:169], v[134:137]
	v_mfma_f32_16x16x32_bf16 v[114:117], v[82:85], v[182:185], v[114:117]
	v_mfma_f32_16x16x32_bf16 v[110:113], v[106:109], v[182:185], v[110:113]
	v_mfma_f32_16x16x32_bf16 v[90:93], v[82:85], v[190:193], v[90:93]
	v_mfma_f32_16x16x32_bf16 v[86:89], v[106:109], v[190:193], v[86:89]
	v_mfma_f32_16x16x32_bf16 v[134:137], v[118:121], v[174:177], v[130:133]
	v_mfma_f32_16x16x32_bf16 v[114:117], v[94:97], v[186:189], v[114:117]
	v_mfma_f32_16x16x32_bf16 v[110:113], v[118:121], v[186:189], v[110:113]
	v_mfma_f32_16x16x32_bf16 v[90:93], v[94:97], v[194:197], v[90:93]
	v_mfma_f32_16x16x32_bf16 v[86:89], v[118:121], v[194:197], v[86:89]
	s_barrier
	s_mov_b32 m0, s39
	s_or_b32 s60, s58, 0x80
	ds_read_b128 v[130:133], v217 offset:49152
	ds_read_b128 v[142:145], v217 offset:50176
	ds_read_b128 v[154:157], v217 offset:51200
	ds_read_b128 v[166:169], v217 offset:52224
	ds_read_b128 v[174:177], v217 offset:53248
	ds_read_b128 v[182:185], v217 offset:54272
	ds_read_b128 v[186:189], v217 offset:55296
	ds_read_b128 v[190:193], v217 offset:56320
	buffer_load_dwordx4 v199, s[12:15], s60 offen lds
	s_mov_b32 m0, s40
	s_add_i32 s58, s58, 0x20080
	buffer_load_dwordx4 v215, s[12:15], s60 offen lds
	s_mov_b32 m0, s43
	s_nop 0
	buffer_load_dwordx4 v199, s[12:15], s58 offen lds
	s_mov_b32 m0, s42
	s_nop 0
	buffer_load_dwordx4 v215, s[12:15], s58 offen lds
	s_mov_b32 m0, s41
	s_nop 0
	buffer_load_dwordx4 v0, s[16:19], s59 offen lds
	s_mov_b32 m0, s33
	s_nop 0
	buffer_load_dwordx4 v214, s[16:19], s59 offen lds
	s_waitcnt vmcnt(8)
	s_waitcnt lgkmcnt(0)
	s_barrier
	v_mfma_f32_16x16x32_bf16 v[78:81], v[58:61], v[130:133], v[78:81]
	v_mfma_f32_16x16x32_bf16 v[74:77], v[66:69], v[130:133], v[74:77]
	v_mfma_f32_16x16x32_bf16 v[54:57], v[58:61], v[154:157], v[54:57]
	v_mfma_f32_16x16x32_bf16 v[50:53], v[66:69], v[154:157], v[50:53]
	v_mfma_f32_16x16x32_bf16 v[30:33], v[58:61], v[174:177], v[30:33]
	v_mfma_f32_16x16x32_bf16 v[26:29], v[66:69], v[174:177], v[26:29]
	v_mfma_f32_16x16x32_bf16 v[14:17], v[58:61], v[186:189], v[14:17]
	v_mfma_f32_16x16x32_bf16 v[10:13], v[66:69], v[186:189], v[10:13]
	v_mfma_f32_16x16x32_bf16 v[78:81], v[62:65], v[142:145], v[78:81]
	v_mfma_f32_16x16x32_bf16 v[74:77], v[70:73], v[142:145], v[74:77]
	v_mfma_f32_16x16x32_bf16 v[54:57], v[62:65], v[166:169], v[54:57]
	v_mfma_f32_16x16x32_bf16 v[50:53], v[70:73], v[166:169], v[50:53]
	v_mfma_f32_16x16x32_bf16 v[30:33], v[62:65], v[182:185], v[30:33]
	v_mfma_f32_16x16x32_bf16 v[26:29], v[70:73], v[182:185], v[26:29]
	v_mfma_f32_16x16x32_bf16 v[14:17], v[62:65], v[190:193], v[14:17]
	v_mfma_f32_16x16x32_bf16 v[10:13], v[70:73], v[190:193], v[10:13]
	v_mfma_f32_16x16x32_bf16 v[34:37], v[82:85], v[130:133], v[34:37]
	v_mfma_f32_16x16x32_bf16 v[66:69], v[94:97], v[142:145], v[34:37]
	v_mfma_f32_16x16x32_bf16 v[34:37], v[106:109], v[130:133], v[46:49]
	v_mfma_f32_16x16x32_bf16 v[62:65], v[118:121], v[142:145], v[34:37]
	v_mfma_f32_16x16x32_bf16 v[34:37], v[82:85], v[154:157], v[42:45]
	v_mfma_f32_16x16x32_bf16 v[42:45], v[94:97], v[166:169], v[34:37]
	v_mfma_f32_16x16x32_bf16 v[34:37], v[106:109], v[154:157], v[38:41]
	v_mfma_f32_16x16x32_bf16 v[22:25], v[82:85], v[174:177], v[22:25]
	v_mfma_f32_16x16x32_bf16 v[18:21], v[106:109], v[174:177], v[18:21]
	v_mfma_f32_16x16x32_bf16 v[6:9], v[82:85], v[186:189], v[6:9]
	v_mfma_f32_16x16x32_bf16 v[2:5], v[106:109], v[186:189], v[2:5]
	v_mfma_f32_16x16x32_bf16 v[38:41], v[118:121], v[166:169], v[34:37]
	v_mfma_f32_16x16x32_bf16 v[22:25], v[94:97], v[182:185], v[22:25]
	v_mfma_f32_16x16x32_bf16 v[18:21], v[118:121], v[182:185], v[18:21]
	v_mfma_f32_16x16x32_bf16 v[6:9], v[94:97], v[190:193], v[6:9]
	v_mfma_f32_16x16x32_bf16 v[2:5], v[118:121], v[190:193], v[2:5]
	s_barrier
	s_add_i32 s57, s57, 2
	s_addk_i32 s55, 0x100
	s_addk_i32 s56, 0x100
	s_cmp_gt_u32 s57, 5
	s_cbranch_scc0 .LBB0_903
	v_readlane_b32 s8, v251, 45
	v_readlane_b32 s9, v251, 46
	s_and_b64 vcc, exec, s[8:9]
	s_cbranch_vccz .LBB0_906
	s_barrier

.LBB0_1029:
.LBB0_1030:
	v_add_u32_e32 v0, 0x10000, v230
	s_waitcnt vmcnt(0)
	ds_read_b128 v[130:133], v0
	ds_read_b128 v[134:137], v0 offset:1024
	ds_read_b128 v[138:141], v0 offset:2048
	ds_read_b128 v[142:145], v0 offset:3072
	v_add_u32_e32 v0, 0x14000, v230
	ds_read_b128 v[146:149], v0
	ds_read_b128 v[150:153], v0 offset:1024
	ds_read_b128 v[154:157], v0 offset:2048
	ds_read_b128 v[158:161], v0 offset:3072
	s_lshl_b32 s55, s20, 7
	s_add_i32 s18, s73, s55
	s_and_b64 s[12:13], s[16:17], exec
	s_cselect_b32 s13, s31, s9
	s_cselect_b32 s12, s30, s8
	s_cselect_b32 s15, s35, s11
	s_cselect_b32 s14, s34, s10
	s_cselect_b32 s56, s68, s18
	s_add_i32 s21, s74, s55
	s_and_b64 s[16:17], s[16:17], exec
	s_cselect_b32 s54, s69, s21
	s_cselect_b32 s17, s51, s77
	s_cselect_b32 s16, s50, s76
	s_cselect_b32 s19, s53, s7
	s_cselect_b32 s18, s52, s6
	s_or_b32 s21, s56, 0x80
	s_or_b32 s57, s54, 0x80
	s_add_i32 s55, s55, s75
	s_mov_b32 m0, s45
	ds_read_b128 v[162:165], v231
	ds_read_b128 v[166:169], v231 offset:1024
	ds_read_b128 v[170:173], v231 offset:2048
	ds_read_b128 v[174:177], v231 offset:3072
	ds_read_b128 v[178:181], v231 offset:4096
	ds_read_b128 v[182:185], v231 offset:5120
	ds_read_b128 v[186:189], v231 offset:6144
	ds_read_b128 v[190:193], v231 offset:7168
	buffer_load_dwordx4 v199, s[8:11], s55 offen lds
	s_mov_b32 m0, s46
	s_nop 0
	buffer_load_dwordx4 v228, s[8:11], s55 offen lds
	s_waitcnt vmcnt(8)
	s_waitcnt lgkmcnt(0)
	s_barrier
	v_mfma_f32_16x16x32_bf16 v[126:129], v[130:133], v[162:165], v[126:129]
	v_mfma_f32_16x16x32_bf16 v[122:125], v[138:141], v[162:165], v[122:125]
	v_mfma_f32_16x16x32_bf16 v[118:121], v[130:133], v[170:173], v[118:121]
	v_mfma_f32_16x16x32_bf16 v[114:117], v[138:141], v[170:173], v[114:117]
	v_mfma_f32_16x16x32_bf16 v[110:113], v[130:133], v[178:181], v[110:113]
	v_mfma_f32_16x16x32_bf16 v[106:109], v[138:141], v[178:181], v[106:109]
	v_mfma_f32_16x16x32_bf16 v[102:105], v[130:133], v[186:189], v[102:105]
	v_mfma_f32_16x16x32_bf16 v[98:101], v[138:141], v[186:189], v[98:101]
	v_mfma_f32_16x16x32_bf16 v[126:129], v[134:137], v[166:169], v[126:129]
	v_mfma_f32_16x16x32_bf16 v[122:125], v[142:145], v[166:169], v[122:125]
	v_mfma_f32_16x16x32_bf16 v[118:121], v[134:137], v[174:177], v[118:121]
	v_mfma_f32_16x16x32_bf16 v[114:117], v[142:145], v[174:177], v[114:117]
	v_mfma_f32_16x16x32_bf16 v[110:113], v[134:137], v[182:185], v[110:113]
	v_mfma_f32_16x16x32_bf16 v[106:109], v[142:145], v[182:185], v[106:109]
	v_mfma_f32_16x16x32_bf16 v[102:105], v[134:137], v[190:193], v[102:105]
	v_mfma_f32_16x16x32_bf16 v[98:101], v[142:145], v[190:193], v[98:101]
	v_mfma_f32_16x16x32_bf16 v[94:97], v[146:149], v[162:165], v[94:97]
	v_mfma_f32_16x16x32_bf16 v[90:93], v[154:157], v[162:165], v[90:93]
	v_mfma_f32_16x16x32_bf16 v[86:89], v[146:149], v[170:173], v[86:89]
	v_mfma_f32_16x16x32_bf16 v[82:85], v[154:157], v[170:173], v[82:85]
	v_mfma_f32_16x16x32_bf16 v[78:81], v[146:149], v[178:181], v[78:81]
	v_mfma_f32_16x16x32_bf16 v[74:77], v[154:157], v[178:181], v[74:77]
	v_mfma_f32_16x16x32_bf16 v[70:73], v[146:149], v[186:189], v[70:73]
	v_mfma_f32_16x16x32_bf16 v[66:69], v[154:157], v[186:189], v[66:69]
	v_mfma_f32_16x16x32_bf16 v[94:97], v[150:153], v[166:169], v[94:97]
	v_mfma_f32_16x16x32_bf16 v[90:93], v[158:161], v[166:169], v[90:93]
	v_mfma_f32_16x16x32_bf16 v[86:89], v[150:153], v[174:177], v[86:89]
	v_mfma_f32_16x16x32_bf16 v[82:85], v[158:161], v[174:177], v[82:85]
	v_mfma_f32_16x16x32_bf16 v[78:81], v[150:153], v[182:185], v[78:81]
	v_mfma_f32_16x16x32_bf16 v[74:77], v[158:161], v[182:185], v[74:77]
	v_mfma_f32_16x16x32_bf16 v[70:73], v[150:153], v[190:193], v[70:73]
	v_mfma_f32_16x16x32_bf16 v[66:69], v[158:161], v[190:193], v[66:69]
	s_barrier
	s_mov_b32 m0, s92
	ds_read_b128 v[162:165], v231 offset:16384
	ds_read_b128 v[166:169], v231 offset:17408
	ds_read_b128 v[170:173], v231 offset:18432
	ds_read_b128 v[174:177], v231 offset:19456
	ds_read_b128 v[178:181], v231 offset:20480
	ds_read_b128 v[182:185], v231 offset:21504
	ds_read_b128 v[186:189], v231 offset:22528
	ds_read_b128 v[190:193], v231 offset:23552
	buffer_load_dwordx4 v227, s[16:19], s54 offen lds
	s_mov_b32 m0, s93
	s_add_i32 s55, s54, 0x20000
	buffer_load_dwordx4 v229, s[16:19], s54 offen lds
	s_mov_b32 m0, s94
	s_nop 0
	buffer_load_dwordx4 v227, s[16:19], s55 offen lds
	s_mov_b32 m0, s95
	s_nop 0
	buffer_load_dwordx4 v229, s[16:19], s55 offen lds
	s_mov_b32 m0, s44
	s_nop 0
	buffer_load_dwordx4 v199, s[12:15], s56 offen lds
	s_mov_b32 m0, s36
	s_nop 0
	buffer_load_dwordx4 v228, s[12:15], s56 offen lds
	s_waitcnt vmcnt(8)
	s_waitcnt lgkmcnt(0)
	s_barrier
	v_mfma_f32_16x16x32_bf16 v[62:65], v[130:133], v[162:165], v[62:65]
	v_mfma_f32_16x16x32_bf16 v[58:61], v[138:141], v[162:165], v[58:61]
	v_mfma_f32_16x16x32_bf16 v[54:57], v[130:133], v[170:173], v[54:57]
	v_mfma_f32_16x16x32_bf16 v[50:53], v[138:141], v[170:173], v[50:53]
	v_mfma_f32_16x16x32_bf16 v[46:49], v[130:133], v[178:181], v[46:49]
	v_mfma_f32_16x16x32_bf16 v[42:45], v[138:141], v[178:181], v[42:45]
	v_mfma_f32_16x16x32_bf16 v[38:41], v[130:133], v[186:189], v[38:41]
	v_mfma_f32_16x16x32_bf16 v[34:37], v[138:141], v[186:189], v[34:37]
	v_mfma_f32_16x16x32_bf16 v[62:65], v[134:137], v[166:169], v[62:65]
	v_mfma_f32_16x16x32_bf16 v[58:61], v[142:145], v[166:169], v[58:61]
	v_mfma_f32_16x16x32_bf16 v[54:57], v[134:137], v[174:177], v[54:57]
	v_mfma_f32_16x16x32_bf16 v[50:53], v[142:145], v[174:177], v[50:53]
	v_mfma_f32_16x16x32_bf16 v[46:49], v[134:137], v[182:185], v[46:49]
	v_mfma_f32_16x16x32_bf16 v[42:45], v[142:145], v[182:185], v[42:45]
	v_mfma_f32_16x16x32_bf16 v[38:41], v[134:137], v[190:193], v[38:41]
	v_mfma_f32_16x16x32_bf16 v[34:37], v[142:145], v[190:193], v[34:37]
	v_mfma_f32_16x16x32_bf16 v[30:33], v[146:149], v[162:165], v[30:33]
	v_mfma_f32_16x16x32_bf16 v[26:29], v[154:157], v[162:165], v[26:29]
	v_mfma_f32_16x16x32_bf16 v[22:25], v[146:149], v[170:173], v[22:25]
	v_mfma_f32_16x16x32_bf16 v[18:21], v[154:157], v[170:173], v[18:21]
	v_mfma_f32_16x16x32_bf16 v[14:17], v[146:149], v[178:181], v[14:17]
	v_mfma_f32_16x16x32_bf16 v[10:13], v[154:157], v[178:181], v[10:13]
	v_mfma_f32_16x16x32_bf16 v[6:9], v[146:149], v[186:189], v[6:9]
	v_mfma_f32_16x16x32_bf16 v[2:5], v[154:157], v[186:189], v[2:5]
	v_mfma_f32_16x16x32_bf16 v[30:33], v[150:153], v[166:169], v[30:33]
	v_mfma_f32_16x16x32_bf16 v[26:29], v[158:161], v[166:169], v[26:29]
	v_mfma_f32_16x16x32_bf16 v[22:25], v[150:153], v[174:177], v[22:25]
	v_mfma_f32_16x16x32_bf16 v[18:21], v[158:161], v[174:177], v[18:21]
	v_mfma_f32_16x16x32_bf16 v[14:17], v[150:153], v[182:185], v[14:17]
	v_mfma_f32_16x16x32_bf16 v[10:13], v[158:161], v[182:185], v[10:13]
	v_mfma_f32_16x16x32_bf16 v[6:9], v[150:153], v[190:193], v[6:9]
	v_mfma_f32_16x16x32_bf16 v[2:5], v[158:161], v[190:193], v[2:5]
	s_barrier
	v_add_u32_e32 v0, 0x18000, v230
	ds_read_b128 v[130:133], v0
	ds_read_b128 v[134:137], v0 offset:1024
	ds_read_b128 v[138:141], v0 offset:2048
	ds_read_b128 v[142:145], v0 offset:3072
	v_add_u32_e32 v0, 0x1c000, v230
	ds_read_b128 v[146:149], v0
	ds_read_b128 v[150:153], v0 offset:1024
	ds_read_b128 v[154:157], v0 offset:2048
	ds_read_b128 v[158:161], v0 offset:3072
	s_add_i32 s56, s56, 0x20000
	s_mov_b32 m0, s37
	ds_read_b128 v[162:165], v231 offset:32768
	ds_read_b128 v[166:169], v231 offset:33792
	ds_read_b128 v[170:173], v231 offset:34816
	ds_read_b128 v[174:177], v231 offset:35840
	ds_read_b128 v[178:181], v231 offset:36864
	ds_read_b128 v[182:185], v231 offset:37888
	ds_read_b128 v[186:189], v231 offset:38912
	ds_read_b128 v[190:193], v231 offset:39936
	buffer_load_dwordx4 v199, s[12:15], s56 offen lds
	s_mov_b32 m0, s38
	s_nop 0
	buffer_load_dwordx4 v228, s[12:15], s56 offen lds
	s_waitcnt vmcnt(8)
	s_waitcnt lgkmcnt(0)
	s_barrier
	v_mfma_f32_16x16x32_bf16 v[126:129], v[130:133], v[162:165], v[126:129]
	v_mfma_f32_16x16x32_bf16 v[122:125], v[138:141], v[162:165], v[122:125]
	v_mfma_f32_16x16x32_bf16 v[118:121], v[130:133], v[170:173], v[118:121]
	v_mfma_f32_16x16x32_bf16 v[114:117], v[138:141], v[170:173], v[114:117]
	v_mfma_f32_16x16x32_bf16 v[110:113], v[130:133], v[178:181], v[110:113]
	v_mfma_f32_16x16x32_bf16 v[106:109], v[138:141], v[178:181], v[106:109]
	v_mfma_f32_16x16x32_bf16 v[102:105], v[130:133], v[186:189], v[102:105]
	v_mfma_f32_16x16x32_bf16 v[98:101], v[138:141], v[186:189], v[98:101]
	v_mfma_f32_16x16x32_bf16 v[126:129], v[134:137], v[166:169], v[126:129]
	v_mfma_f32_16x16x32_bf16 v[122:125], v[142:145], v[166:169], v[122:125]
	v_mfma_f32_16x16x32_bf16 v[118:121], v[134:137], v[174:177], v[118:121]
	v_mfma_f32_16x16x32_bf16 v[114:117], v[142:145], v[174:177], v[114:117]
	v_mfma_f32_16x16x32_bf16 v[110:113], v[134:137], v[182:185], v[110:113]
	v_mfma_f32_16x16x32_bf16 v[106:109], v[142:145], v[182:185], v[106:109]
	v_mfma_f32_16x16x32_bf16 v[102:105], v[134:137], v[190:193], v[102:105]
	v_mfma_f32_16x16x32_bf16 v[98:101], v[142:145], v[190:193], v[98:101]
	v_mfma_f32_16x16x32_bf16 v[94:97], v[146:149], v[162:165], v[94:97]
	v_mfma_f32_16x16x32_bf16 v[90:93], v[154:157], v[162:165], v[90:93]
	v_mfma_f32_16x16x32_bf16 v[86:89], v[146:149], v[170:173], v[86:89]
	v_mfma_f32_16x16x32_bf16 v[82:85], v[154:157], v[170:173], v[82:85]
	v_mfma_f32_16x16x32_bf16 v[78:81], v[146:149], v[178:181], v[78:81]
	v_mfma_f32_16x16x32_bf16 v[74:77], v[154:157], v[178:181], v[74:77]
	v_mfma_f32_16x16x32_bf16 v[70:73], v[146:149], v[186:189], v[70:73]
	v_mfma_f32_16x16x32_bf16 v[66:69], v[154:157], v[186:189], v[66:69]
	v_mfma_f32_16x16x32_bf16 v[94:97], v[150:153], v[166:169], v[94:97]
	v_mfma_f32_16x16x32_bf16 v[90:93], v[158:161], v[166:169], v[90:93]
	v_mfma_f32_16x16x32_bf16 v[86:89], v[150:153], v[174:177], v[86:89]
	v_mfma_f32_16x16x32_bf16 v[82:85], v[158:161], v[174:177], v[82:85]
	v_mfma_f32_16x16x32_bf16 v[78:81], v[150:153], v[182:185], v[78:81]
	v_mfma_f32_16x16x32_bf16 v[74:77], v[158:161], v[182:185], v[74:77]
	v_mfma_f32_16x16x32_bf16 v[70:73], v[150:153], v[190:193], v[70:73]
	v_mfma_f32_16x16x32_bf16 v[66:69], v[158:161], v[190:193], v[66:69]
	s_barrier
; #define PG8_WAIT_V(n) asm volatile("s_waitcnt vmcnt(" #n ")" ::: "memory")
; template <class Epi, bool ALIGN_EPI, bool SP2, class Hook>
; __device__ __forceinline__ void gemm_phase(LAS unsigned char* lds, const Gemm g, const StaticOrder& S, const Epi& E, Acc& acc, const bool fresh, const Hook& H, const int wave_id) {
;     ...
;         for (int t = t0; t < nt; t += 2) {
;             const bool last = (t == nt - 2);
;             const Src a1 = cA + (size_t)(t + 1) * kstep;
;             const Src a2 = last ? nA : cA + (size_t)(t + 2) * kstep, b2 = last ? nB : cB + (size_t)(t + 2) * kstep;
;             const Src a3 = a2 + kstep, b3 = b2 + kstep;
;             if (last && has_next) H(nxt);
;             if constexpr (SP2) {
;             PG8_TRIP_SP2(PG8_WAIT_V(8));
	s_mov_b32 m0, s39
	ds_read_b128 v[162:165], v231 offset:49152
	ds_read_b128 v[166:169], v231 offset:50176
	ds_read_b128 v[170:173], v231 offset:51200
	ds_read_b128 v[174:177], v231 offset:52224
	ds_read_b128 v[178:181], v231 offset:53248
	ds_read_b128 v[182:185], v231 offset:54272
	ds_read_b128 v[186:189], v231 offset:55296
	ds_read_b128 v[190:193], v231 offset:56320
	buffer_load_dwordx4 v227, s[16:19], s57 offen lds
	s_mov_b32 m0, s40
	s_add_i32 s54, s54, 0x20080
	buffer_load_dwordx4 v229, s[16:19], s57 offen lds
	s_mov_b32 m0, s43
	s_nop 0
	buffer_load_dwordx4 v227, s[16:19], s54 offen lds
	s_mov_b32 m0, s42
	s_nop 0
	buffer_load_dwordx4 v229, s[16:19], s54 offen lds
	s_mov_b32 m0, s41
	s_nop 0
	buffer_load_dwordx4 v199, s[12:15], s21 offen lds
	s_mov_b32 m0, s33
	s_nop 0
	buffer_load_dwordx4 v228, s[12:15], s21 offen lds
	s_waitcnt vmcnt(8)
	s_waitcnt lgkmcnt(0)
	s_barrier
	v_mfma_f32_16x16x32_bf16 v[62:65], v[130:133], v[162:165], v[62:65]
	v_mfma_f32_16x16x32_bf16 v[58:61], v[138:141], v[162:165], v[58:61]
	v_mfma_f32_16x16x32_bf16 v[54:57], v[130:133], v[170:173], v[54:57]
	v_mfma_f32_16x16x32_bf16 v[50:53], v[138:141], v[170:173], v[50:53]
	v_mfma_f32_16x16x32_bf16 v[46:49], v[130:133], v[178:181], v[46:49]
	v_mfma_f32_16x16x32_bf16 v[42:45], v[138:141], v[178:181], v[42:45]
	v_mfma_f32_16x16x32_bf16 v[38:41], v[130:133], v[186:189], v[38:41]
	v_mfma_f32_16x16x32_bf16 v[34:37], v[138:141], v[186:189], v[34:37]
	v_mfma_f32_16x16x32_bf16 v[62:65], v[134:137], v[166:169], v[62:65]
	v_mfma_f32_16x16x32_bf16 v[58:61], v[142:145], v[166:169], v[58:61]
	v_mfma_f32_16x16x32_bf16 v[54:57], v[134:137], v[174:177], v[54:57]
	v_mfma_f32_16x16x32_bf16 v[50:53], v[142:145], v[174:177], v[50:53]
	v_mfma_f32_16x16x32_bf16 v[46:49], v[134:137], v[182:185], v[46:49]
	v_mfma_f32_16x16x32_bf16 v[42:45], v[142:145], v[182:185], v[42:45]
	v_mfma_f32_16x16x32_bf16 v[38:41], v[134:137], v[190:193], v[38:41]
	v_mfma_f32_16x16x32_bf16 v[34:37], v[142:145], v[190:193], v[34:37]
	v_mfma_f32_16x16x32_bf16 v[30:33], v[146:149], v[162:165], v[30:33]
	v_mfma_f32_16x16x32_bf16 v[26:29], v[154:157], v[162:165], v[26:29]
	v_mfma_f32_16x16x32_bf16 v[22:25], v[146:149], v[170:173], v[22:25]
	v_mfma_f32_16x16x32_bf16 v[18:21], v[154:157], v[170:173], v[18:21]
	v_mfma_f32_16x16x32_bf16 v[14:17], v[146:149], v[178:181], v[14:17]
	v_mfma_f32_16x16x32_bf16 v[10:13], v[154:157], v[178:181], v[10:13]
	v_mfma_f32_16x16x32_bf16 v[6:9], v[146:149], v[186:189], v[6:9]
	v_mfma_f32_16x16x32_bf16 v[2:5], v[154:157], v[186:189], v[2:5]
	v_mfma_f32_16x16x32_bf16 v[30:33], v[150:153], v[166:169], v[30:33]
	v_mfma_f32_16x16x32_bf16 v[26:29], v[158:161], v[166:169], v[26:29]
	v_mfma_f32_16x16x32_bf16 v[22:25], v[150:153], v[174:177], v[22:25]
	v_mfma_f32_16x16x32_bf16 v[18:21], v[158:161], v[174:177], v[18:21]
	v_mfma_f32_16x16x32_bf16 v[14:17], v[150:153], v[182:185], v[14:17]
	v_mfma_f32_16x16x32_bf16 v[10:13], v[158:161], v[182:185], v[10:13]
	v_mfma_f32_16x16x32_bf16 v[6:9], v[150:153], v[190:193], v[6:9]
	v_mfma_f32_16x16x32_bf16 v[2:5], v[158:161], v[190:193], v[2:5]
	s_barrier
	s_add_i32 s12, s20, 2
	s_cmp_gt_u32 s20, 5
	s_cbranch_scc1 .LBB0_1032
	s_mov_b32 s20, s12
	s_branch .LBB0_951

; #define PG8_WAIT_V(n) asm volatile("s_waitcnt vmcnt(" #n ")" ::: "memory")
; template <class Epi, bool ALIGN_EPI, bool SP2, class Hook>
; __device__ __forceinline__ void gemm_phase(LAS unsigned char* lds, const Gemm g, const StaticOrder& S, const Epi& E, Acc& acc, const bool fresh, const Hook& H, const int wave_id) {
;     ...
;         for (int t = t0; t < nt; t += 2) {
;             const bool last = (t == nt - 2);
;             const Src a1 = cA + (size_t)(t + 1) * kstep;
;             const Src a2 = last ? nA : cA + (size_t)(t + 2) * kstep, b2 = last ? nB : cB + (size_t)(t + 2) * kstep;
;             const Src a3 = a2 + kstep, b3 = b2 + kstep;
;             if (last && has_next) H(nxt);
;             if constexpr (SP2) {
;             PG8_TRIP_SP2(PG8_WAIT_V(8));
.LBB0_1235:
	v_add_u32_e32 v142, 0x10000, v161
	v_add_u32_e32 v163, 0x14000, v161
	ds_read_b128 v[130:133], v142
	ds_read_b128 v[134:137], v142 offset:1024
	ds_read_b128 v[138:141], v142 offset:2048
	ds_read_b128 v[142:145], v142 offset:3072
	ds_read_b128 v[146:149], v163
	ds_read_b128 v[150:153], v163 offset:1024
	ds_read_b128 v[154:157], v163 offset:2048
	ds_read_b128 v[164:167], v163 offset:3072
	s_add_i32 s16, s2, 0xfffc0080
	s_cmp_eq_u32 s59, 12
	s_cselect_b32 s62, s55, s16
	s_cselect_b32 s17, s31, s9
	s_cselect_b32 s16, s30, s8
	s_cselect_b32 s19, s35, s51
	s_cselect_b32 s18, s34, s50
	s_cselect_b32 s60, s56, s3
	s_cselect_b32 s20, s26, s12
	s_cselect_b32 s21, s27, s13
	s_cselect_b32 s22, s28, s14
	s_cselect_b32 s23, s29, s15
	s_or_b32 s61, s62, 0x80
	s_mov_b32 m0, s45
	ds_read_b128 v[168:171], v162
	ds_read_b128 v[172:175], v162 offset:1024
	ds_read_b128 v[176:179], v162 offset:2048
	ds_read_b128 v[180:183], v162 offset:3072
	ds_read_b128 v[184:187], v162 offset:4096
	ds_read_b128 v[188:191], v162 offset:5120
	ds_read_b128 v[192:195], v162 offset:6144
	ds_read_b128 v[200:203], v162 offset:7168
	buffer_load_dwordx4 v0, s[12:15], s2 offen lds
	s_mov_b32 m0, s46
	s_nop 0
	buffer_load_dwordx4 v159, s[12:15], s2 offen lds
	s_waitcnt vmcnt(8)
	s_waitcnt lgkmcnt(0)
	s_barrier
	v_mfma_f32_16x16x32_bf16 v[126:129], v[130:133], v[168:171], v[126:129]
	v_mfma_f32_16x16x32_bf16 v[122:125], v[138:141], v[168:171], v[122:125]
	v_mfma_f32_16x16x32_bf16 v[110:113], v[130:133], v[176:179], v[110:113]
	v_mfma_f32_16x16x32_bf16 v[106:109], v[138:141], v[176:179], v[106:109]
	v_mfma_f32_16x16x32_bf16 v[94:97], v[130:133], v[184:187], v[94:97]
	v_mfma_f32_16x16x32_bf16 v[90:93], v[138:141], v[184:187], v[90:93]
	v_mfma_f32_16x16x32_bf16 v[78:81], v[130:133], v[192:195], v[78:81]
	v_mfma_f32_16x16x32_bf16 v[74:77], v[138:141], v[192:195], v[74:77]
	v_mfma_f32_16x16x32_bf16 v[126:129], v[134:137], v[172:175], v[126:129]
	v_mfma_f32_16x16x32_bf16 v[122:125], v[142:145], v[172:175], v[122:125]
	v_mfma_f32_16x16x32_bf16 v[110:113], v[134:137], v[180:183], v[110:113]
	v_mfma_f32_16x16x32_bf16 v[106:109], v[142:145], v[180:183], v[106:109]
	v_mfma_f32_16x16x32_bf16 v[94:97], v[134:137], v[188:191], v[94:97]
	v_mfma_f32_16x16x32_bf16 v[90:93], v[142:145], v[188:191], v[90:93]
	v_mfma_f32_16x16x32_bf16 v[78:81], v[134:137], v[200:203], v[78:81]
	v_mfma_f32_16x16x32_bf16 v[74:77], v[142:145], v[200:203], v[74:77]
	v_mfma_f32_16x16x32_bf16 v[118:121], v[146:149], v[168:171], v[118:121]
	v_mfma_f32_16x16x32_bf16 v[114:117], v[154:157], v[168:171], v[114:117]
	v_mfma_f32_16x16x32_bf16 v[102:105], v[146:149], v[176:179], v[102:105]
	v_mfma_f32_16x16x32_bf16 v[98:101], v[154:157], v[176:179], v[98:101]
	v_mfma_f32_16x16x32_bf16 v[86:89], v[146:149], v[184:187], v[86:89]
	v_mfma_f32_16x16x32_bf16 v[82:85], v[154:157], v[184:187], v[82:85]
	v_mfma_f32_16x16x32_bf16 v[70:73], v[146:149], v[192:195], v[70:73]
	v_mfma_f32_16x16x32_bf16 v[66:69], v[154:157], v[192:195], v[66:69]
	v_mfma_f32_16x16x32_bf16 v[118:121], v[150:153], v[172:175], v[118:121]
	v_mfma_f32_16x16x32_bf16 v[114:117], v[164:167], v[172:175], v[114:117]
	v_mfma_f32_16x16x32_bf16 v[102:105], v[150:153], v[180:183], v[102:105]
	v_mfma_f32_16x16x32_bf16 v[98:101], v[164:167], v[180:183], v[98:101]
	v_mfma_f32_16x16x32_bf16 v[86:89], v[150:153], v[188:191], v[86:89]
	v_mfma_f32_16x16x32_bf16 v[82:85], v[164:167], v[188:191], v[82:85]
	v_mfma_f32_16x16x32_bf16 v[70:73], v[150:153], v[200:203], v[70:73]
	v_mfma_f32_16x16x32_bf16 v[66:69], v[164:167], v[200:203], v[66:69]
	s_barrier
	s_mov_b32 m0, s92
	ds_read_b128 v[168:171], v162 offset:16384
	ds_read_b128 v[172:175], v162 offset:17408
	ds_read_b128 v[176:179], v162 offset:18432
	ds_read_b128 v[180:183], v162 offset:19456
	ds_read_b128 v[184:187], v162 offset:20480
	ds_read_b128 v[188:191], v162 offset:21504
	ds_read_b128 v[192:195], v162 offset:22528
	ds_read_b128 v[200:203], v162 offset:23552
	buffer_load_dwordx4 v158, s[16:19], s60 offen lds
	s_mov_b32 m0, s93
	s_add_i32 s63, s60, 0x40000
	buffer_load_dwordx4 v160, s[16:19], s60 offen lds
	s_mov_b32 m0, s94
	s_nop 0
	buffer_load_dwordx4 v158, s[16:19], s63 offen lds
	s_mov_b32 m0, s95
	s_nop 0
	buffer_load_dwordx4 v160, s[16:19], s63 offen lds
	s_mov_b32 m0, s44
	s_nop 0
	buffer_load_dwordx4 v0, s[20:23], s62 offen lds
	s_mov_b32 m0, s36
	s_nop 0
	buffer_load_dwordx4 v159, s[20:23], s62 offen lds
	s_waitcnt vmcnt(8)
	s_waitcnt lgkmcnt(0)
	s_barrier
	v_mfma_f32_16x16x32_bf16 v[62:65], v[130:133], v[168:171], v[62:65]
	v_mfma_f32_16x16x32_bf16 v[58:61], v[138:141], v[168:171], v[58:61]
	v_mfma_f32_16x16x32_bf16 v[46:49], v[130:133], v[176:179], v[46:49]
	v_mfma_f32_16x16x32_bf16 v[42:45], v[138:141], v[176:179], v[42:45]
	v_mfma_f32_16x16x32_bf16 v[30:33], v[130:133], v[184:187], v[30:33]
	v_mfma_f32_16x16x32_bf16 v[26:29], v[138:141], v[184:187], v[26:29]
	v_mfma_f32_16x16x32_bf16 v[14:17], v[130:133], v[192:195], v[14:17]
	v_mfma_f32_16x16x32_bf16 v[10:13], v[138:141], v[192:195], v[10:13]
	v_mfma_f32_16x16x32_bf16 v[62:65], v[134:137], v[172:175], v[62:65]
	v_mfma_f32_16x16x32_bf16 v[58:61], v[142:145], v[172:175], v[58:61]
	v_mfma_f32_16x16x32_bf16 v[46:49], v[134:137], v[180:183], v[46:49]
	v_mfma_f32_16x16x32_bf16 v[42:45], v[142:145], v[180:183], v[42:45]
	v_mfma_f32_16x16x32_bf16 v[30:33], v[134:137], v[188:191], v[30:33]
	v_mfma_f32_16x16x32_bf16 v[26:29], v[142:145], v[188:191], v[26:29]
	v_mfma_f32_16x16x32_bf16 v[14:17], v[134:137], v[200:203], v[14:17]
	v_mfma_f32_16x16x32_bf16 v[10:13], v[142:145], v[200:203], v[10:13]
	v_mfma_f32_16x16x32_bf16 v[54:57], v[146:149], v[168:171], v[54:57]
	v_mfma_f32_16x16x32_bf16 v[50:53], v[154:157], v[168:171], v[50:53]
	v_mfma_f32_16x16x32_bf16 v[38:41], v[146:149], v[176:179], v[38:41]
	v_mfma_f32_16x16x32_bf16 v[34:37], v[154:157], v[176:179], v[34:37]
	v_mfma_f32_16x16x32_bf16 v[22:25], v[146:149], v[184:187], v[22:25]
	v_mfma_f32_16x16x32_bf16 v[18:21], v[154:157], v[184:187], v[18:21]
	v_mfma_f32_16x16x32_bf16 v[6:9], v[146:149], v[192:195], v[6:9]
	v_mfma_f32_16x16x32_bf16 v[2:5], v[154:157], v[192:195], v[2:5]
	v_mfma_f32_16x16x32_bf16 v[54:57], v[150:153], v[172:175], v[54:57]
	v_mfma_f32_16x16x32_bf16 v[50:53], v[164:167], v[172:175], v[50:53]
	v_mfma_f32_16x16x32_bf16 v[38:41], v[150:153], v[180:183], v[38:41]
	v_mfma_f32_16x16x32_bf16 v[34:37], v[164:167], v[180:183], v[34:37]
	v_mfma_f32_16x16x32_bf16 v[22:25], v[150:153], v[188:191], v[22:25]
	v_mfma_f32_16x16x32_bf16 v[18:21], v[164:167], v[188:191], v[18:21]
	v_mfma_f32_16x16x32_bf16 v[6:9], v[150:153], v[200:203], v[6:9]
	v_mfma_f32_16x16x32_bf16 v[2:5], v[164:167], v[200:203], v[2:5]
	s_barrier
; #define PG8_WAIT_V(n) asm volatile("s_waitcnt vmcnt(" #n ")" ::: "memory")
; template <class Epi, bool ALIGN_EPI, bool SP2, class Hook>
; __device__ __forceinline__ void gemm_phase(LAS unsigned char* lds, const Gemm g, const StaticOrder& S, const Epi& E, Acc& acc, const bool fresh, const Hook& H, const int wave_id) {
;     ...
;         for (int t = t0; t < nt; t += 2) {
;             const bool last = (t == nt - 2);
;             const Src a1 = cA + (size_t)(t + 1) * kstep;
;             const Src a2 = last ? nA : cA + (size_t)(t + 2) * kstep, b2 = last ? nB : cB + (size_t)(t + 2) * kstep;
;             const Src a3 = a2 + kstep, b3 = b2 + kstep;
;             if (last && has_next) H(nxt);
;             if constexpr (SP2) {
;             PG8_TRIP_SP2(PG8_WAIT_V(8));
	v_add_u32_e32 v142, 0x18000, v161
	v_add_u32_e32 v163, 0x1c000, v161
	ds_read_b128 v[130:133], v142
	ds_read_b128 v[134:137], v142 offset:1024
	ds_read_b128 v[138:141], v142 offset:2048
	ds_read_b128 v[142:145], v142 offset:3072
	ds_read_b128 v[146:149], v163
	ds_read_b128 v[150:153], v163 offset:1024
	ds_read_b128 v[154:157], v163 offset:2048
	ds_read_b128 v[164:167], v163 offset:3072
	s_add_i32 s62, s62, 0x40000
	s_mov_b32 m0, s37
	ds_read_b128 v[168:171], v162 offset:32768
	ds_read_b128 v[172:175], v162 offset:33792
	ds_read_b128 v[176:179], v162 offset:34816
	ds_read_b128 v[180:183], v162 offset:35840
	ds_read_b128 v[184:187], v162 offset:36864
	ds_read_b128 v[188:191], v162 offset:37888
	ds_read_b128 v[192:195], v162 offset:38912
	ds_read_b128 v[200:203], v162 offset:39936
	buffer_load_dwordx4 v0, s[20:23], s62 offen lds
	s_mov_b32 m0, s38
	s_nop 0
	buffer_load_dwordx4 v159, s[20:23], s62 offen lds
	s_waitcnt vmcnt(8)
	s_waitcnt lgkmcnt(0)
	s_barrier
	v_mfma_f32_16x16x32_bf16 v[126:129], v[130:133], v[168:171], v[126:129]
	v_mfma_f32_16x16x32_bf16 v[122:125], v[138:141], v[168:171], v[122:125]
	v_mfma_f32_16x16x32_bf16 v[110:113], v[130:133], v[176:179], v[110:113]
	v_mfma_f32_16x16x32_bf16 v[106:109], v[138:141], v[176:179], v[106:109]
	v_mfma_f32_16x16x32_bf16 v[94:97], v[130:133], v[184:187], v[94:97]
	v_mfma_f32_16x16x32_bf16 v[90:93], v[138:141], v[184:187], v[90:93]
	v_mfma_f32_16x16x32_bf16 v[78:81], v[130:133], v[192:195], v[78:81]
	v_mfma_f32_16x16x32_bf16 v[74:77], v[138:141], v[192:195], v[74:77]
	v_mfma_f32_16x16x32_bf16 v[126:129], v[134:137], v[172:175], v[126:129]
	v_mfma_f32_16x16x32_bf16 v[122:125], v[142:145], v[172:175], v[122:125]
	v_mfma_f32_16x16x32_bf16 v[110:113], v[134:137], v[180:183], v[110:113]
	v_mfma_f32_16x16x32_bf16 v[106:109], v[142:145], v[180:183], v[106:109]
	v_mfma_f32_16x16x32_bf16 v[94:97], v[134:137], v[188:191], v[94:97]
	v_mfma_f32_16x16x32_bf16 v[90:93], v[142:145], v[188:191], v[90:93]
	v_mfma_f32_16x16x32_bf16 v[78:81], v[134:137], v[200:203], v[78:81]
	v_mfma_f32_16x16x32_bf16 v[74:77], v[142:145], v[200:203], v[74:77]
	v_mfma_f32_16x16x32_bf16 v[118:121], v[146:149], v[168:171], v[118:121]
	v_mfma_f32_16x16x32_bf16 v[114:117], v[154:157], v[168:171], v[114:117]
	v_mfma_f32_16x16x32_bf16 v[102:105], v[146:149], v[176:179], v[102:105]
	v_mfma_f32_16x16x32_bf16 v[98:101], v[154:157], v[176:179], v[98:101]
	v_mfma_f32_16x16x32_bf16 v[86:89], v[146:149], v[184:187], v[86:89]
	v_mfma_f32_16x16x32_bf16 v[82:85], v[154:157], v[184:187], v[82:85]
	v_mfma_f32_16x16x32_bf16 v[70:73], v[146:149], v[192:195], v[70:73]
	v_mfma_f32_16x16x32_bf16 v[66:69], v[154:157], v[192:195], v[66:69]
	v_mfma_f32_16x16x32_bf16 v[118:121], v[150:153], v[172:175], v[118:121]
	v_mfma_f32_16x16x32_bf16 v[114:117], v[164:167], v[172:175], v[114:117]
	v_mfma_f32_16x16x32_bf16 v[102:105], v[150:153], v[180:183], v[102:105]
	v_mfma_f32_16x16x32_bf16 v[98:101], v[164:167], v[180:183], v[98:101]
	v_mfma_f32_16x16x32_bf16 v[86:89], v[150:153], v[188:191], v[86:89]
	v_mfma_f32_16x16x32_bf16 v[82:85], v[164:167], v[188:191], v[82:85]
	v_mfma_f32_16x16x32_bf16 v[70:73], v[150:153], v[200:203], v[70:73]
	v_mfma_f32_16x16x32_bf16 v[66:69], v[164:167], v[200:203], v[66:69]
	s_barrier
	s_mov_b32 m0, s39
	s_or_b32 s62, s60, 0x80
	ds_read_b128 v[168:171], v162 offset:49152
	ds_read_b128 v[172:175], v162 offset:50176
	ds_read_b128 v[176:179], v162 offset:51200
	ds_read_b128 v[180:183], v162 offset:52224
	ds_read_b128 v[184:187], v162 offset:53248
	ds_read_b128 v[188:191], v162 offset:54272
	ds_read_b128 v[192:195], v162 offset:55296
	ds_read_b128 v[200:203], v162 offset:56320
	buffer_load_dwordx4 v158, s[16:19], s62 offen lds
	s_mov_b32 m0, s40
	s_add_i32 s60, s60, 0x40080
	buffer_load_dwordx4 v160, s[16:19], s62 offen lds
	s_mov_b32 m0, s43
	s_nop 0
	buffer_load_dwordx4 v158, s[16:19], s60 offen lds
	s_mov_b32 m0, s42
	s_nop 0
	buffer_load_dwordx4 v160, s[16:19], s60 offen lds
	s_mov_b32 m0, s41
	s_nop 0
	buffer_load_dwordx4 v0, s[20:23], s61 offen lds
	s_mov_b32 m0, s33
	s_nop 0
	buffer_load_dwordx4 v159, s[20:23], s61 offen lds
	s_waitcnt vmcnt(8)
	s_waitcnt lgkmcnt(0)
	s_barrier
	v_mfma_f32_16x16x32_bf16 v[62:65], v[130:133], v[168:171], v[62:65]
	v_mfma_f32_16x16x32_bf16 v[58:61], v[138:141], v[168:171], v[58:61]
	v_mfma_f32_16x16x32_bf16 v[46:49], v[130:133], v[176:179], v[46:49]
	v_mfma_f32_16x16x32_bf16 v[42:45], v[138:141], v[176:179], v[42:45]
	v_mfma_f32_16x16x32_bf16 v[30:33], v[130:133], v[184:187], v[30:33]
	v_mfma_f32_16x16x32_bf16 v[26:29], v[138:141], v[184:187], v[26:29]
	v_mfma_f32_16x16x32_bf16 v[14:17], v[130:133], v[192:195], v[14:17]
	v_mfma_f32_16x16x32_bf16 v[10:13], v[138:141], v[192:195], v[10:13]
	v_mfma_f32_16x16x32_bf16 v[62:65], v[134:137], v[172:175], v[62:65]
	v_mfma_f32_16x16x32_bf16 v[58:61], v[142:145], v[172:175], v[58:61]
	v_mfma_f32_16x16x32_bf16 v[46:49], v[134:137], v[180:183], v[46:49]
	v_mfma_f32_16x16x32_bf16 v[42:45], v[142:145], v[180:183], v[42:45]
	v_mfma_f32_16x16x32_bf16 v[30:33], v[134:137], v[188:191], v[30:33]
	v_mfma_f32_16x16x32_bf16 v[26:29], v[142:145], v[188:191], v[26:29]
	v_mfma_f32_16x16x32_bf16 v[14:17], v[134:137], v[200:203], v[14:17]
	v_mfma_f32_16x16x32_bf16 v[10:13], v[142:145], v[200:203], v[10:13]
	v_mfma_f32_16x16x32_bf16 v[54:57], v[146:149], v[168:171], v[54:57]
	v_mfma_f32_16x16x32_bf16 v[50:53], v[154:157], v[168:171], v[50:53]
	v_mfma_f32_16x16x32_bf16 v[38:41], v[146:149], v[176:179], v[38:41]
	v_mfma_f32_16x16x32_bf16 v[34:37], v[154:157], v[176:179], v[34:37]
	v_mfma_f32_16x16x32_bf16 v[22:25], v[146:149], v[184:187], v[22:25]
	v_mfma_f32_16x16x32_bf16 v[18:21], v[154:157], v[184:187], v[18:21]
	v_mfma_f32_16x16x32_bf16 v[6:9], v[146:149], v[192:195], v[6:9]
	v_mfma_f32_16x16x32_bf16 v[2:5], v[154:157], v[192:195], v[2:5]
	v_mfma_f32_16x16x32_bf16 v[54:57], v[150:153], v[172:175], v[54:57]
	v_mfma_f32_16x16x32_bf16 v[50:53], v[164:167], v[172:175], v[50:53]
	v_mfma_f32_16x16x32_bf16 v[38:41], v[150:153], v[180:183], v[38:41]
	v_mfma_f32_16x16x32_bf16 v[34:37], v[164:167], v[180:183], v[34:37]
	v_mfma_f32_16x16x32_bf16 v[22:25], v[150:153], v[188:191], v[22:25]
	v_mfma_f32_16x16x32_bf16 v[18:21], v[164:167], v[188:191], v[18:21]
	v_mfma_f32_16x16x32_bf16 v[6:9], v[150:153], v[200:203], v[6:9]
	v_mfma_f32_16x16x32_bf16 v[2:5], v[164:167], v[200:203], v[2:5]
	s_barrier
	s_add_i32 s59, s59, 2
	s_addk_i32 s2, 0x100
	s_addk_i32 s3, 0x100
	s_cmp_gt_u32 s59, 13
	s_cbranch_scc0 .LBB0_1235
	v_readlane_b32 s2, v251, 45
	v_readlane_b32 s3, v251, 46
	s_and_b64 vcc, exec, s[2:3]
	s_cbranch_vccz .LBB0_1238
	s_barrier

; #define PG8_WAIT_V(n) asm volatile("s_waitcnt vmcnt(" #n ")" ::: "memory")
; template <class Epi, bool ALIGN_EPI, bool SP2, class Hook>
; __device__ __forceinline__ void gemm_phase(LAS unsigned char* lds, const Gemm g, const StaticOrder& S, const Epi& E, Acc& acc, const bool fresh, const Hook& H, const int wave_id) {
;     ...
;         if constexpr (SP2 && Epi::NSTORE > 0) {
;             const Src a1 = cA + kstep, a2 = cA + 2 * kstep, b2 = cB + 2 * kstep, a3 = a2 + kstep, b3 = b2 + kstep;
;             if constexpr (Epi::NSTORE == 16) PG8_TRIP_SP2(PG8_WAIT_V(24)); else PG8_TRIP_SP2(PG8_WAIT_V(16));
.LBB0_1452:
	ds_read_b128 v[2:5], v138
	ds_read_b128 v[6:9], v138 offset:1024
	ds_read_b128 v[10:13], v138 offset:2048
	ds_read_b128 v[14:17], v138 offset:3072
	ds_read_b128 v[18:21], v139
	ds_read_b128 v[22:25], v139 offset:1024
	ds_read_b128 v[26:29], v139 offset:2048
	ds_read_b128 v[30:33], v139 offset:3072
	s_or_b32 s3, s50, 0x100
	s_or_b32 s2, s50, 0x180
	s_or_b32 s12, s51, 0x100
	s_or_b32 s13, s50, 0x40080
	s_mov_b32 m0, s45
	ds_read_b128 v[34:37], v137
	ds_read_b128 v[38:41], v137 offset:1024
	ds_read_b128 v[42:45], v137 offset:2048
	ds_read_b128 v[46:49], v137 offset:3072
	ds_read_b128 v[50:53], v137 offset:4096
	ds_read_b128 v[54:57], v137 offset:5120
	ds_read_b128 v[58:61], v137 offset:6144
	ds_read_b128 v[62:65], v137 offset:7168
	buffer_load_dwordx4 v132, s[4:7], s13 offen lds
	s_mov_b32 m0, s46
	s_nop 0
	buffer_load_dwordx4 v134, s[4:7], s13 offen lds
	s_waitcnt vmcnt(16)
	s_waitcnt lgkmcnt(0)
	s_barrier
	v_mfma_f32_16x16x32_bf16 v[90:93], v[2:5], v[58:61], 0
	v_mfma_f32_16x16x32_bf16 v[66:69], v[2:5], v[34:37], 0
	v_mfma_f32_16x16x32_bf16 v[70:73], v[10:13], v[34:37], 0
	v_mfma_f32_16x16x32_bf16 v[74:77], v[2:5], v[42:45], 0
	v_mfma_f32_16x16x32_bf16 v[78:81], v[10:13], v[42:45], 0
	v_mfma_f32_16x16x32_bf16 v[82:85], v[2:5], v[50:53], 0
	v_mfma_f32_16x16x32_bf16 v[86:89], v[10:13], v[50:53], 0
	v_mfma_f32_16x16x32_bf16 v[96:99], v[6:9], v[62:65], v[90:93]
	v_mfma_f32_16x16x32_bf16 v[90:93], v[10:13], v[58:61], 0
	v_mfma_f32_16x16x32_bf16 v[66:69], v[6:9], v[38:41], v[66:69]
	v_mfma_f32_16x16x32_bf16 v[70:73], v[14:17], v[38:41], v[70:73]
	v_mfma_f32_16x16x32_bf16 v[74:77], v[6:9], v[46:49], v[74:77]
	v_mfma_f32_16x16x32_bf16 v[78:81], v[14:17], v[46:49], v[78:81]
	v_mfma_f32_16x16x32_bf16 v[82:85], v[6:9], v[54:57], v[82:85]
	v_mfma_f32_16x16x32_bf16 v[86:89], v[14:17], v[54:57], v[86:89]
	v_mfma_f32_16x16x32_bf16 v[104:107], v[14:17], v[62:65], v[90:93]
	v_mfma_f32_16x16x32_bf16 v[90:93], v[18:21], v[34:37], 0
	v_mfma_f32_16x16x32_bf16 v[34:37], v[26:29], v[34:37], 0
	v_mfma_f32_16x16x32_bf16 v[112:115], v[22:25], v[38:41], v[90:93]
	v_mfma_f32_16x16x32_bf16 v[34:37], v[30:33], v[38:41], v[34:37]
	v_mfma_f32_16x16x32_bf16 v[38:41], v[18:21], v[42:45], 0
	v_mfma_f32_16x16x32_bf16 v[42:45], v[26:29], v[42:45], 0
	v_mfma_f32_16x16x32_bf16 v[38:41], v[22:25], v[46:49], v[38:41]
	v_mfma_f32_16x16x32_bf16 v[42:45], v[30:33], v[46:49], v[42:45]
	v_mfma_f32_16x16x32_bf16 v[46:49], v[18:21], v[50:53], 0
	v_mfma_f32_16x16x32_bf16 v[50:53], v[26:29], v[50:53], 0
	v_mfma_f32_16x16x32_bf16 v[46:49], v[22:25], v[54:57], v[46:49]
	v_mfma_f32_16x16x32_bf16 v[50:53], v[30:33], v[54:57], v[50:53]
	v_mfma_f32_16x16x32_bf16 v[54:57], v[18:21], v[58:61], 0
	v_mfma_f32_16x16x32_bf16 v[58:61], v[26:29], v[58:61], 0
	v_mfma_f32_16x16x32_bf16 v[54:57], v[22:25], v[62:65], v[54:57]
	v_mfma_f32_16x16x32_bf16 v[58:61], v[30:33], v[62:65], v[58:61]
	s_barrier
	s_mov_b32 m0, s92
	ds_read_b128 v[62:65], v137 offset:16384
	ds_read_b128 v[90:93], v137 offset:17408
	ds_read_b128 v[100:103], v137 offset:18432
	ds_read_b128 v[108:111], v137 offset:19456
	ds_read_b128 v[116:119], v137 offset:20480
	ds_read_b128 v[120:123], v137 offset:21504
	ds_read_b128 v[124:127], v137 offset:22528
	ds_read_b128 v[128:131], v137 offset:23552
	buffer_load_dwordx4 v133, s[8:11], s12 offen lds
	s_mov_b32 m0, s93
	s_nop 0
	buffer_load_dwordx4 v135, s[8:11], s12 offen lds
	s_or_b32 s12, s51, 0x40100
	s_mov_b32 m0, s94
	s_nop 0
	buffer_load_dwordx4 v133, s[8:11], s12 offen lds
	s_mov_b32 m0, s95
	s_nop 0
	buffer_load_dwordx4 v135, s[8:11], s12 offen lds
	s_mov_b32 m0, s44
	s_nop 0
	buffer_load_dwordx4 v132, s[4:7], s3 offen lds
	s_mov_b32 m0, s36
	s_nop 0
	buffer_load_dwordx4 v134, s[4:7], s3 offen lds
	s_waitcnt vmcnt(16)
	s_waitcnt lgkmcnt(0)
	s_barrier
	v_mfma_f32_16x16x32_bf16 v[142:145], v[2:5], v[62:65], 0
	v_mfma_f32_16x16x32_bf16 v[150:153], v[2:5], v[100:103], 0
	v_mfma_f32_16x16x32_bf16 v[158:161], v[2:5], v[116:119], 0
	v_mfma_f32_16x16x32_bf16 v[2:5], v[2:5], v[124:127], 0
	v_mfma_f32_16x16x32_bf16 v[142:145], v[6:9], v[90:93], v[142:145]
	v_mfma_f32_16x16x32_bf16 v[150:153], v[6:9], v[108:111], v[150:153]
	v_mfma_f32_16x16x32_bf16 v[158:161], v[6:9], v[120:123], v[158:161]
	v_mfma_f32_16x16x32_bf16 v[2:5], v[6:9], v[128:131], v[2:5]
	v_mfma_f32_16x16x32_bf16 v[6:9], v[10:13], v[124:127], 0
	v_mfma_f32_16x16x32_bf16 v[146:149], v[10:13], v[62:65], 0
	v_mfma_f32_16x16x32_bf16 v[154:157], v[10:13], v[100:103], 0
	v_mfma_f32_16x16x32_bf16 v[162:165], v[10:13], v[116:119], 0
	v_mfma_f32_16x16x32_bf16 v[6:9], v[14:17], v[128:131], v[6:9]
	v_mfma_f32_16x16x32_bf16 v[146:149], v[14:17], v[90:93], v[146:149]
	v_mfma_f32_16x16x32_bf16 v[154:157], v[14:17], v[108:111], v[154:157]
	v_mfma_f32_16x16x32_bf16 v[162:165], v[14:17], v[120:123], v[162:165]
	v_mfma_f32_16x16x32_bf16 v[10:13], v[18:21], v[62:65], 0
	v_mfma_f32_16x16x32_bf16 v[166:169], v[22:25], v[90:93], v[10:13]
	v_mfma_f32_16x16x32_bf16 v[10:13], v[26:29], v[62:65], 0
	v_mfma_f32_16x16x32_bf16 v[170:173], v[30:33], v[90:93], v[10:13]
	v_mfma_f32_16x16x32_bf16 v[10:13], v[18:21], v[100:103], 0
	v_mfma_f32_16x16x32_bf16 v[174:177], v[22:25], v[108:111], v[10:13]
	v_mfma_f32_16x16x32_bf16 v[10:13], v[26:29], v[100:103], 0
	v_mfma_f32_16x16x32_bf16 v[178:181], v[30:33], v[108:111], v[10:13]
	v_mfma_f32_16x16x32_bf16 v[10:13], v[18:21], v[116:119], 0
	v_mfma_f32_16x16x32_bf16 v[182:185], v[22:25], v[120:123], v[10:13]
	v_mfma_f32_16x16x32_bf16 v[10:13], v[26:29], v[116:119], 0
	v_mfma_f32_16x16x32_bf16 v[186:189], v[30:33], v[120:123], v[10:13]
	v_mfma_f32_16x16x32_bf16 v[10:13], v[18:21], v[124:127], 0
	v_mfma_f32_16x16x32_bf16 v[16:19], v[22:25], v[128:131], v[10:13]
	v_mfma_f32_16x16x32_bf16 v[10:13], v[26:29], v[124:127], 0
	v_mfma_f32_16x16x32_bf16 v[190:193], v[30:33], v[128:131], v[10:13]
	s_barrier
; #define PG8_WAIT_V(n) asm volatile("s_waitcnt vmcnt(" #n ")" ::: "memory")
; template <class Epi, bool ALIGN_EPI, bool SP2, class Hook>
; __device__ __forceinline__ void gemm_phase(LAS unsigned char* lds, const Gemm g, const StaticOrder& S, const Epi& E, Acc& acc, const bool fresh, const Hook& H, const int wave_id) {
;     ...
;         if constexpr (SP2 && Epi::NSTORE > 0) {
;             const Src a1 = cA + kstep, a2 = cA + 2 * kstep, b2 = cB + 2 * kstep, a3 = a2 + kstep, b3 = b2 + kstep;
;             if constexpr (Epi::NSTORE == 16) PG8_TRIP_SP2(PG8_WAIT_V(24)); else PG8_TRIP_SP2(PG8_WAIT_V(16));
;             t0 = 2;
	s_nop 4
	ds_read_b128 v[10:13], v140
	ds_read_b128 v[24:27], v140 offset:1024
	ds_read_b128 v[194:197], v140 offset:2048
	ds_read_b128 v[200:203], v140 offset:3072
	ds_read_b128 v[204:207], v141
	ds_read_b128 v[208:211], v141 offset:1024
	ds_read_b128 v[212:215], v141 offset:2048
	ds_read_b128 v[138:141], v141 offset:3072
	s_or_b32 s3, s50, 0x40100
	s_mov_b32 m0, s37
	ds_read_b128 v[20:23], v137 offset:32768
	ds_read_b128 v[28:31], v137 offset:33792
	ds_read_b128 v[216:219], v137 offset:34816
	ds_read_b128 v[220:223], v137 offset:35840
	ds_read_b128 v[228:231], v137 offset:36864
	ds_read_b128 v[232:235], v137 offset:37888
	ds_read_b128 v[236:239], v137 offset:38912
	ds_read_b128 v[240:243], v137 offset:39936
	buffer_load_dwordx4 v132, s[4:7], s3 offen lds
	s_mov_b32 m0, s38
	s_nop 0
	buffer_load_dwordx4 v134, s[4:7], s3 offen lds
	s_waitcnt vmcnt(8)
	s_waitcnt lgkmcnt(0)
	s_barrier
	v_mfma_f32_16x16x32_bf16 v[62:65], v[10:13], v[20:23], v[66:69]
	v_mfma_f32_16x16x32_bf16 v[124:127], v[24:27], v[28:31], v[62:65]
	v_mfma_f32_16x16x32_bf16 v[62:65], v[194:197], v[20:23], v[70:73]
	v_mfma_f32_16x16x32_bf16 v[116:119], v[200:203], v[28:31], v[62:65]
	v_mfma_f32_16x16x32_bf16 v[62:65], v[10:13], v[216:219], v[74:77]
	v_mfma_f32_16x16x32_bf16 v[108:111], v[24:27], v[220:223], v[62:65]
	v_mfma_f32_16x16x32_bf16 v[62:65], v[194:197], v[216:219], v[78:81]
	v_mfma_f32_16x16x32_bf16 v[100:103], v[200:203], v[220:223], v[62:65]
	v_mfma_f32_16x16x32_bf16 v[62:65], v[10:13], v[228:231], v[82:85]
	v_mfma_f32_16x16x32_bf16 v[92:95], v[24:27], v[232:235], v[62:65]
	v_mfma_f32_16x16x32_bf16 v[62:65], v[194:197], v[228:231], v[86:89]
	v_mfma_f32_16x16x32_bf16 v[84:87], v[200:203], v[232:235], v[62:65]
	v_mfma_f32_16x16x32_bf16 v[62:65], v[10:13], v[236:239], v[96:99]
	v_mfma_f32_16x16x32_bf16 v[76:79], v[24:27], v[240:243], v[62:65]
	v_mfma_f32_16x16x32_bf16 v[62:65], v[194:197], v[236:239], v[104:107]
	v_mfma_f32_16x16x32_bf16 v[64:67], v[200:203], v[240:243], v[62:65]
	v_mfma_f32_16x16x32_bf16 v[68:71], v[204:207], v[20:23], v[112:115]
	v_mfma_f32_16x16x32_bf16 v[20:23], v[212:215], v[20:23], v[34:37]
	v_mfma_f32_16x16x32_bf16 v[120:123], v[138:141], v[28:31], v[20:23]
	v_mfma_f32_16x16x32_bf16 v[20:23], v[204:207], v[216:219], v[38:41]
	v_mfma_f32_16x16x32_bf16 v[112:115], v[208:211], v[220:223], v[20:23]
	v_mfma_f32_16x16x32_bf16 v[20:23], v[212:215], v[216:219], v[42:45]
	v_mfma_f32_16x16x32_bf16 v[104:107], v[138:141], v[220:223], v[20:23]
	v_mfma_f32_16x16x32_bf16 v[20:23], v[204:207], v[228:231], v[46:49]
	v_mfma_f32_16x16x32_bf16 v[96:99], v[208:211], v[232:235], v[20:23]
	v_mfma_f32_16x16x32_bf16 v[20:23], v[212:215], v[228:231], v[50:53]
	v_mfma_f32_16x16x32_bf16 v[88:91], v[138:141], v[232:235], v[20:23]
	v_mfma_f32_16x16x32_bf16 v[20:23], v[204:207], v[236:239], v[54:57]
	v_mfma_f32_16x16x32_bf16 v[80:83], v[208:211], v[240:243], v[20:23]
	v_mfma_f32_16x16x32_bf16 v[20:23], v[212:215], v[236:239], v[58:61]
	v_mfma_f32_16x16x32_bf16 v[128:131], v[208:211], v[28:31], v[68:71]
	v_mfma_f32_16x16x32_bf16 v[68:71], v[138:141], v[240:243], v[20:23]
	s_barrier
	s_mov_b32 m0, s39
	s_or_b32 s3, s51, 0x180
	ds_read_b128 v[32:35], v137 offset:49152
	ds_read_b128 v[40:43], v137 offset:50176
	ds_read_b128 v[216:219], v137 offset:51200
	ds_read_b128 v[220:223], v137 offset:52224
	ds_read_b128 v[228:231], v137 offset:53248
	ds_read_b128 v[232:235], v137 offset:54272
	ds_read_b128 v[236:239], v137 offset:55296
	ds_read_b128 v[240:243], v137 offset:56320
	buffer_load_dwordx4 v133, s[8:11], s3 offen lds
	s_mov_b32 m0, s40
	s_nop 0
	buffer_load_dwordx4 v135, s[8:11], s3 offen lds
	s_or_b32 s3, s51, 0x40180
	s_mov_b32 m0, s43
	s_nop 0
	buffer_load_dwordx4 v133, s[8:11], s3 offen lds
	s_mov_b32 m0, s42
	s_nop 0
	buffer_load_dwordx4 v135, s[8:11], s3 offen lds
	s_mov_b32 m0, s41
	s_nop 0
	buffer_load_dwordx4 v132, s[4:7], s2 offen lds
	s_mov_b32 m0, s33
	s_nop 0
	buffer_load_dwordx4 v134, s[4:7], s2 offen lds
	s_waitcnt vmcnt(8)
	s_waitcnt lgkmcnt(0)
	s_barrier
	v_mfma_f32_16x16x32_bf16 v[20:23], v[10:13], v[32:35], v[142:145]
	v_mfma_f32_16x16x32_bf16 v[60:63], v[24:27], v[40:43], v[20:23]
	v_mfma_f32_16x16x32_bf16 v[20:23], v[194:197], v[32:35], v[146:149]
	v_mfma_f32_16x16x32_bf16 v[52:55], v[200:203], v[40:43], v[20:23]
	v_mfma_f32_16x16x32_bf16 v[20:23], v[10:13], v[216:219], v[150:153]
	v_mfma_f32_16x16x32_bf16 v[44:47], v[24:27], v[220:223], v[20:23]
	v_mfma_f32_16x16x32_bf16 v[20:23], v[194:197], v[216:219], v[154:157]
	v_mfma_f32_16x16x32_bf16 v[36:39], v[200:203], v[220:223], v[20:23]
	v_mfma_f32_16x16x32_bf16 v[20:23], v[10:13], v[228:231], v[158:161]
	v_mfma_f32_16x16x32_bf16 v[2:5], v[10:13], v[236:239], v[2:5]
	v_mfma_f32_16x16x32_bf16 v[28:31], v[24:27], v[232:235], v[20:23]
	v_mfma_f32_16x16x32_bf16 v[20:23], v[194:197], v[228:231], v[162:165]
	v_mfma_f32_16x16x32_bf16 v[12:15], v[24:27], v[240:243], v[2:5]
	v_mfma_f32_16x16x32_bf16 v[2:5], v[194:197], v[236:239], v[6:9]
	v_mfma_f32_16x16x32_bf16 v[20:23], v[200:203], v[232:235], v[20:23]
	v_mfma_f32_16x16x32_bf16 v[4:7], v[200:203], v[240:243], v[2:5]
	v_mfma_f32_16x16x32_bf16 v[8:11], v[204:207], v[32:35], v[166:169]
	v_mfma_f32_16x16x32_bf16 v[72:75], v[208:211], v[40:43], v[8:11]
	v_mfma_f32_16x16x32_bf16 v[8:11], v[212:215], v[32:35], v[170:173]
	v_mfma_f32_16x16x32_bf16 v[56:59], v[138:141], v[40:43], v[8:11]
	v_mfma_f32_16x16x32_bf16 v[8:11], v[204:207], v[216:219], v[174:177]
	v_mfma_f32_16x16x32_bf16 v[48:51], v[208:211], v[220:223], v[8:11]
	v_mfma_f32_16x16x32_bf16 v[8:11], v[212:215], v[216:219], v[178:181]
	v_mfma_f32_16x16x32_bf16 v[40:43], v[138:141], v[220:223], v[8:11]
	v_mfma_f32_16x16x32_bf16 v[8:11], v[204:207], v[228:231], v[182:185]
	v_mfma_f32_16x16x32_bf16 v[32:35], v[208:211], v[232:235], v[8:11]
	v_mfma_f32_16x16x32_bf16 v[8:11], v[212:215], v[228:231], v[186:189]
	v_mfma_f32_16x16x32_bf16 v[24:27], v[138:141], v[232:235], v[8:11]
	v_mfma_f32_16x16x32_bf16 v[8:11], v[204:207], v[236:239], v[16:19]
	v_mfma_f32_16x16x32_bf16 v[16:19], v[208:211], v[240:243], v[8:11]
	v_mfma_f32_16x16x32_bf16 v[8:11], v[212:215], v[236:239], v[190:193]
	v_mfma_f32_16x16x32_bf16 v[8:11], v[138:141], v[240:243], v[8:11]
	s_barrier
	s_mov_b64 s[2:3], 0
	v_mov_b64_e32 v[234:235], v[226:227]
	v_mov_b32_e32 v226, v0
	v_mov_b64_e32 v[236:237], v[198:199]
	v_mov_b32_e32 v198, v225

; #define PG8_WAIT_V(n) asm volatile("s_waitcnt vmcnt(" #n ")" ::: "memory")
; template <class Epi, bool ALIGN_EPI, bool SP2, class Hook>
; __device__ __forceinline__ void gemm_phase(LAS unsigned char* lds, const Gemm g, const StaticOrder& S, const Epi& E, Acc& acc, const bool fresh, const Hook& H, const int wave_id) {
;     ...
;         for (int t = t0; t < nt; t += 2) {
;             const bool last = (t == nt - 2);
;             const Src a1 = cA + (size_t)(t + 1) * kstep;
;             const Src a2 = last ? nA : cA + (size_t)(t + 2) * kstep, b2 = last ? nB : cB + (size_t)(t + 2) * kstep;
;             const Src a3 = a2 + kstep, b3 = b2 + kstep;
;             if (last && has_next) H(nxt);
;             if constexpr (SP2) {
;             PG8_TRIP_SP2(PG8_WAIT_V(8));
.LBB0_1461:
	v_add_u32_e32 v138, 0x10000, v136
	v_add_u32_e32 v139, 0x14000, v136
	ds_read_b128 v[140:143], v138
	ds_read_b128 v[144:147], v138 offset:1024
	ds_read_b128 v[148:151], v138 offset:2048
	ds_read_b128 v[152:155], v138 offset:3072
	ds_read_b128 v[156:159], v139
	ds_read_b128 v[160:163], v139 offset:1024
	ds_read_b128 v[164:167], v139 offset:2048
	ds_read_b128 v[168:171], v139 offset:3072
	s_add_i32 s16, s55, 0xfffc0080
	s_cmp_eq_u32 s54, 12
	s_cselect_b32 s59, s50, s16
	s_cselect_b32 s17, s9, s77
	s_cselect_b32 s16, s8, s76
	s_cselect_b32 s19, s11, s29
	s_cselect_b32 s18, s10, s28
	s_cselect_b32 s57, s51, s56
	s_cselect_b32 s20, s4, s12
	s_cselect_b32 s21, s5, s13
	s_cselect_b32 s22, s6, s14
	s_cselect_b32 s23, s7, s15
	s_or_b32 s58, s59, 0x80
	s_mov_b32 m0, s45
	ds_read_b128 v[172:175], v137
	ds_read_b128 v[176:179], v137 offset:1024
	ds_read_b128 v[180:183], v137 offset:2048
	ds_read_b128 v[184:187], v137 offset:3072
	ds_read_b128 v[188:191], v137 offset:4096
	ds_read_b128 v[192:195], v137 offset:5120
	ds_read_b128 v[200:203], v137 offset:6144
	ds_read_b128 v[204:207], v137 offset:7168
	buffer_load_dwordx4 v132, s[12:15], s55 offen lds
	s_mov_b32 m0, s46
	s_nop 0
	buffer_load_dwordx4 v134, s[12:15], s55 offen lds
	s_waitcnt vmcnt(8)
	s_waitcnt lgkmcnt(0)
	s_barrier
	v_mfma_f32_16x16x32_bf16 v[124:127], v[140:143], v[172:175], v[124:127]
	v_mfma_f32_16x16x32_bf16 v[116:119], v[148:151], v[172:175], v[116:119]
	v_mfma_f32_16x16x32_bf16 v[108:111], v[140:143], v[180:183], v[108:111]
	v_mfma_f32_16x16x32_bf16 v[100:103], v[148:151], v[180:183], v[100:103]
	v_mfma_f32_16x16x32_bf16 v[92:95], v[140:143], v[188:191], v[92:95]
	v_mfma_f32_16x16x32_bf16 v[84:87], v[148:151], v[188:191], v[84:87]
	v_mfma_f32_16x16x32_bf16 v[76:79], v[140:143], v[200:203], v[76:79]
	v_mfma_f32_16x16x32_bf16 v[64:67], v[148:151], v[200:203], v[64:67]
	v_mfma_f32_16x16x32_bf16 v[124:127], v[144:147], v[176:179], v[124:127]
	v_mfma_f32_16x16x32_bf16 v[116:119], v[152:155], v[176:179], v[116:119]
	v_mfma_f32_16x16x32_bf16 v[108:111], v[144:147], v[184:187], v[108:111]
	v_mfma_f32_16x16x32_bf16 v[100:103], v[152:155], v[184:187], v[100:103]
	v_mfma_f32_16x16x32_bf16 v[92:95], v[144:147], v[192:195], v[92:95]
	v_mfma_f32_16x16x32_bf16 v[84:87], v[152:155], v[192:195], v[84:87]
	v_mfma_f32_16x16x32_bf16 v[76:79], v[144:147], v[204:207], v[76:79]
	v_mfma_f32_16x16x32_bf16 v[64:67], v[152:155], v[204:207], v[64:67]
	v_mfma_f32_16x16x32_bf16 v[128:131], v[156:159], v[172:175], v[128:131]
	v_mfma_f32_16x16x32_bf16 v[120:123], v[164:167], v[172:175], v[120:123]
	v_mfma_f32_16x16x32_bf16 v[112:115], v[156:159], v[180:183], v[112:115]
	v_mfma_f32_16x16x32_bf16 v[104:107], v[164:167], v[180:183], v[104:107]
	v_mfma_f32_16x16x32_bf16 v[96:99], v[156:159], v[188:191], v[96:99]
	v_mfma_f32_16x16x32_bf16 v[88:91], v[164:167], v[188:191], v[88:91]
	v_mfma_f32_16x16x32_bf16 v[80:83], v[156:159], v[200:203], v[80:83]
	v_mfma_f32_16x16x32_bf16 v[68:71], v[164:167], v[200:203], v[68:71]
	v_mfma_f32_16x16x32_bf16 v[128:131], v[160:163], v[176:179], v[128:131]
	v_mfma_f32_16x16x32_bf16 v[120:123], v[168:171], v[176:179], v[120:123]
	v_mfma_f32_16x16x32_bf16 v[112:115], v[160:163], v[184:187], v[112:115]
	v_mfma_f32_16x16x32_bf16 v[104:107], v[168:171], v[184:187], v[104:107]
	v_mfma_f32_16x16x32_bf16 v[96:99], v[160:163], v[192:195], v[96:99]
	v_mfma_f32_16x16x32_bf16 v[88:91], v[168:171], v[192:195], v[88:91]
	v_mfma_f32_16x16x32_bf16 v[80:83], v[160:163], v[204:207], v[80:83]
	v_mfma_f32_16x16x32_bf16 v[68:71], v[168:171], v[204:207], v[68:71]
	s_barrier
	s_mov_b32 m0, s92
	ds_read_b128 v[172:175], v137 offset:16384
	ds_read_b128 v[176:179], v137 offset:17408
	ds_read_b128 v[180:183], v137 offset:18432
	ds_read_b128 v[184:187], v137 offset:19456
	ds_read_b128 v[188:191], v137 offset:20480
	ds_read_b128 v[192:195], v137 offset:21504
	ds_read_b128 v[200:203], v137 offset:22528
	ds_read_b128 v[204:207], v137 offset:23552
	buffer_load_dwordx4 v133, s[16:19], s57 offen lds
	s_mov_b32 m0, s93
	s_add_i32 s60, s57, 0x40000
	buffer_load_dwordx4 v135, s[16:19], s57 offen lds
	s_mov_b32 m0, s94
	s_nop 0
	buffer_load_dwordx4 v133, s[16:19], s60 offen lds
	s_mov_b32 m0, s95
	s_nop 0
	buffer_load_dwordx4 v135, s[16:19], s60 offen lds
	s_mov_b32 m0, s44
	s_nop 0
	buffer_load_dwordx4 v132, s[20:23], s59 offen lds
	s_mov_b32 m0, s36
	s_nop 0
	buffer_load_dwordx4 v134, s[20:23], s59 offen lds
	s_waitcnt vmcnt(8)
	s_waitcnt lgkmcnt(0)
	s_barrier
	v_mfma_f32_16x16x32_bf16 v[60:63], v[140:143], v[172:175], v[60:63]
	v_mfma_f32_16x16x32_bf16 v[52:55], v[148:151], v[172:175], v[52:55]
	v_mfma_f32_16x16x32_bf16 v[44:47], v[140:143], v[180:183], v[44:47]
	v_mfma_f32_16x16x32_bf16 v[36:39], v[148:151], v[180:183], v[36:39]
	v_mfma_f32_16x16x32_bf16 v[28:31], v[140:143], v[188:191], v[28:31]
	v_mfma_f32_16x16x32_bf16 v[20:23], v[148:151], v[188:191], v[20:23]
	v_mfma_f32_16x16x32_bf16 v[12:15], v[140:143], v[200:203], v[12:15]
	v_mfma_f32_16x16x32_bf16 v[2:5], v[148:151], v[200:203], v[4:7]
	v_mfma_f32_16x16x32_bf16 v[60:63], v[144:147], v[176:179], v[60:63]
	v_mfma_f32_16x16x32_bf16 v[52:55], v[152:155], v[176:179], v[52:55]
	v_mfma_f32_16x16x32_bf16 v[44:47], v[144:147], v[184:187], v[44:47]
	v_mfma_f32_16x16x32_bf16 v[36:39], v[152:155], v[184:187], v[36:39]
	v_mfma_f32_16x16x32_bf16 v[28:31], v[144:147], v[192:195], v[28:31]
	v_mfma_f32_16x16x32_bf16 v[20:23], v[152:155], v[192:195], v[20:23]
	v_mfma_f32_16x16x32_bf16 v[12:15], v[144:147], v[204:207], v[12:15]
	v_mfma_f32_16x16x32_bf16 v[2:5], v[152:155], v[204:207], v[2:5]
	v_mfma_f32_16x16x32_bf16 v[72:75], v[156:159], v[172:175], v[72:75]
	v_mfma_f32_16x16x32_bf16 v[56:59], v[164:167], v[172:175], v[56:59]
	v_mfma_f32_16x16x32_bf16 v[48:51], v[156:159], v[180:183], v[48:51]
	v_mfma_f32_16x16x32_bf16 v[40:43], v[164:167], v[180:183], v[40:43]
	v_mfma_f32_16x16x32_bf16 v[32:35], v[156:159], v[188:191], v[32:35]
	v_mfma_f32_16x16x32_bf16 v[24:27], v[164:167], v[188:191], v[24:27]
	v_mfma_f32_16x16x32_bf16 v[16:19], v[156:159], v[200:203], v[16:19]
	v_mfma_f32_16x16x32_bf16 v[6:9], v[164:167], v[200:203], v[8:11]
	v_mfma_f32_16x16x32_bf16 v[72:75], v[160:163], v[176:179], v[72:75]
	v_mfma_f32_16x16x32_bf16 v[56:59], v[168:171], v[176:179], v[56:59]
	v_mfma_f32_16x16x32_bf16 v[48:51], v[160:163], v[184:187], v[48:51]
	v_mfma_f32_16x16x32_bf16 v[40:43], v[168:171], v[184:187], v[40:43]
	v_mfma_f32_16x16x32_bf16 v[32:35], v[160:163], v[192:195], v[32:35]
	v_mfma_f32_16x16x32_bf16 v[24:27], v[168:171], v[192:195], v[24:27]
	v_mfma_f32_16x16x32_bf16 v[16:19], v[160:163], v[204:207], v[16:19]
	v_mfma_f32_16x16x32_bf16 v[8:11], v[168:171], v[204:207], v[6:9]
	s_barrier
	v_add_u32_e32 v140, 0x18000, v136
	v_add_u32_e32 v141, 0x1c000, v136
	ds_read_b128 v[142:145], v140
	ds_read_b128 v[146:149], v140 offset:1024
	ds_read_b128 v[150:153], v140 offset:2048
	ds_read_b128 v[154:157], v140 offset:3072
	ds_read_b128 v[158:161], v141
	ds_read_b128 v[162:165], v141 offset:1024
	ds_read_b128 v[166:169], v141 offset:2048
	ds_read_b128 v[170:173], v141 offset:3072
	s_add_i32 s59, s59, 0x40000
	s_mov_b32 m0, s37
	ds_read_b128 v[174:177], v137 offset:32768
	ds_read_b128 v[178:181], v137 offset:33792
	ds_read_b128 v[182:185], v137 offset:34816
	ds_read_b128 v[186:189], v137 offset:35840
	ds_read_b128 v[190:193], v137 offset:36864
	ds_read_b128 v[194:197], v137 offset:37888
	ds_read_b128 v[200:203], v137 offset:38912
	ds_read_b128 v[204:207], v137 offset:39936
	buffer_load_dwordx4 v132, s[20:23], s59 offen lds
	s_mov_b32 m0, s38
	s_nop 0
	buffer_load_dwordx4 v134, s[20:23], s59 offen lds
	s_waitcnt vmcnt(8)
	s_waitcnt lgkmcnt(0)
	s_barrier
	v_mfma_f32_16x16x32_bf16 v[124:127], v[142:145], v[174:177], v[124:127]
	v_mfma_f32_16x16x32_bf16 v[116:119], v[150:153], v[174:177], v[116:119]
	v_mfma_f32_16x16x32_bf16 v[108:111], v[142:145], v[182:185], v[108:111]
	v_mfma_f32_16x16x32_bf16 v[100:103], v[150:153], v[182:185], v[100:103]
	v_mfma_f32_16x16x32_bf16 v[92:95], v[142:145], v[190:193], v[92:95]
	v_mfma_f32_16x16x32_bf16 v[84:87], v[150:153], v[190:193], v[84:87]
	v_mfma_f32_16x16x32_bf16 v[76:79], v[142:145], v[200:203], v[76:79]
	v_mfma_f32_16x16x32_bf16 v[64:67], v[150:153], v[200:203], v[64:67]
	v_mfma_f32_16x16x32_bf16 v[124:127], v[146:149], v[178:181], v[124:127]
	v_mfma_f32_16x16x32_bf16 v[116:119], v[154:157], v[178:181], v[116:119]
	v_mfma_f32_16x16x32_bf16 v[108:111], v[146:149], v[186:189], v[108:111]
	v_mfma_f32_16x16x32_bf16 v[100:103], v[154:157], v[186:189], v[100:103]
	v_mfma_f32_16x16x32_bf16 v[92:95], v[146:149], v[194:197], v[92:95]
	v_mfma_f32_16x16x32_bf16 v[84:87], v[154:157], v[194:197], v[84:87]
	v_mfma_f32_16x16x32_bf16 v[76:79], v[146:149], v[204:207], v[76:79]
	v_mfma_f32_16x16x32_bf16 v[64:67], v[154:157], v[204:207], v[64:67]
	v_mfma_f32_16x16x32_bf16 v[128:131], v[158:161], v[174:177], v[128:131]
	v_mfma_f32_16x16x32_bf16 v[120:123], v[166:169], v[174:177], v[120:123]
	v_mfma_f32_16x16x32_bf16 v[112:115], v[158:161], v[182:185], v[112:115]
	v_mfma_f32_16x16x32_bf16 v[104:107], v[166:169], v[182:185], v[104:107]
	v_mfma_f32_16x16x32_bf16 v[96:99], v[158:161], v[190:193], v[96:99]
	v_mfma_f32_16x16x32_bf16 v[88:91], v[166:169], v[190:193], v[88:91]
	v_mfma_f32_16x16x32_bf16 v[80:83], v[158:161], v[200:203], v[80:83]
	v_mfma_f32_16x16x32_bf16 v[68:71], v[166:169], v[200:203], v[68:71]
	v_mfma_f32_16x16x32_bf16 v[128:131], v[162:165], v[178:181], v[128:131]
	v_mfma_f32_16x16x32_bf16 v[120:123], v[170:173], v[178:181], v[120:123]
	v_mfma_f32_16x16x32_bf16 v[112:115], v[162:165], v[186:189], v[112:115]
	v_mfma_f32_16x16x32_bf16 v[104:107], v[170:173], v[186:189], v[104:107]
	v_mfma_f32_16x16x32_bf16 v[96:99], v[162:165], v[194:197], v[96:99]
	v_mfma_f32_16x16x32_bf16 v[88:91], v[170:173], v[194:197], v[88:91]
	v_mfma_f32_16x16x32_bf16 v[80:83], v[162:165], v[204:207], v[80:83]
	v_mfma_f32_16x16x32_bf16 v[68:71], v[170:173], v[204:207], v[68:71]
	s_barrier
	s_mov_b32 m0, s39
	s_or_b32 s59, s57, 0x80
	ds_read_b128 v[174:177], v137 offset:49152
	ds_read_b128 v[178:181], v137 offset:50176
	ds_read_b128 v[182:185], v137 offset:51200
	ds_read_b128 v[186:189], v137 offset:52224
	ds_read_b128 v[190:193], v137 offset:53248
	ds_read_b128 v[194:197], v137 offset:54272
	ds_read_b128 v[200:203], v137 offset:55296
	ds_read_b128 v[204:207], v137 offset:56320
	buffer_load_dwordx4 v133, s[16:19], s59 offen lds
	s_mov_b32 m0, s40
	s_add_i32 s57, s57, 0x40080
	buffer_load_dwordx4 v135, s[16:19], s59 offen lds
	s_mov_b32 m0, s43
	s_nop 0
	buffer_load_dwordx4 v133, s[16:19], s57 offen lds
	s_mov_b32 m0, s42
	s_nop 0
	buffer_load_dwordx4 v135, s[16:19], s57 offen lds
	s_mov_b32 m0, s41
	s_nop 0
	buffer_load_dwordx4 v132, s[20:23], s58 offen lds
	s_mov_b32 m0, s33
	s_nop 0
	buffer_load_dwordx4 v134, s[20:23], s58 offen lds
	s_waitcnt vmcnt(8)
	s_waitcnt lgkmcnt(0)
	s_barrier
	v_mfma_f32_16x16x32_bf16 v[60:63], v[142:145], v[174:177], v[60:63]
	v_mfma_f32_16x16x32_bf16 v[52:55], v[150:153], v[174:177], v[52:55]
	v_mfma_f32_16x16x32_bf16 v[44:47], v[142:145], v[182:185], v[44:47]
	v_mfma_f32_16x16x32_bf16 v[36:39], v[150:153], v[182:185], v[36:39]
	v_mfma_f32_16x16x32_bf16 v[28:31], v[142:145], v[190:193], v[28:31]
	v_mfma_f32_16x16x32_bf16 v[20:23], v[150:153], v[190:193], v[20:23]
	v_mfma_f32_16x16x32_bf16 v[12:15], v[142:145], v[200:203], v[12:15]
	v_mfma_f32_16x16x32_bf16 v[2:5], v[150:153], v[200:203], v[2:5]
	v_mfma_f32_16x16x32_bf16 v[60:63], v[146:149], v[178:181], v[60:63]
	v_mfma_f32_16x16x32_bf16 v[52:55], v[154:157], v[178:181], v[52:55]
	v_mfma_f32_16x16x32_bf16 v[44:47], v[146:149], v[186:189], v[44:47]
	v_mfma_f32_16x16x32_bf16 v[36:39], v[154:157], v[186:189], v[36:39]
	v_mfma_f32_16x16x32_bf16 v[28:31], v[146:149], v[194:197], v[28:31]
	v_mfma_f32_16x16x32_bf16 v[20:23], v[154:157], v[194:197], v[20:23]
	v_mfma_f32_16x16x32_bf16 v[12:15], v[146:149], v[204:207], v[12:15]
	v_mfma_f32_16x16x32_bf16 v[4:7], v[154:157], v[204:207], v[2:5]
	v_mfma_f32_16x16x32_bf16 v[72:75], v[158:161], v[174:177], v[72:75]
	v_mfma_f32_16x16x32_bf16 v[56:59], v[166:169], v[174:177], v[56:59]
	v_mfma_f32_16x16x32_bf16 v[48:51], v[158:161], v[182:185], v[48:51]
	v_mfma_f32_16x16x32_bf16 v[40:43], v[166:169], v[182:185], v[40:43]
	v_mfma_f32_16x16x32_bf16 v[32:35], v[158:161], v[190:193], v[32:35]
	v_mfma_f32_16x16x32_bf16 v[24:27], v[166:169], v[190:193], v[24:27]
	v_mfma_f32_16x16x32_bf16 v[16:19], v[158:161], v[200:203], v[16:19]
	v_mfma_f32_16x16x32_bf16 v[8:11], v[166:169], v[200:203], v[8:11]
	v_mfma_f32_16x16x32_bf16 v[72:75], v[162:165], v[178:181], v[72:75]
	v_mfma_f32_16x16x32_bf16 v[56:59], v[170:173], v[178:181], v[56:59]
	v_mfma_f32_16x16x32_bf16 v[48:51], v[162:165], v[186:189], v[48:51]
	v_mfma_f32_16x16x32_bf16 v[40:43], v[170:173], v[186:189], v[40:43]
	v_mfma_f32_16x16x32_bf16 v[32:35], v[162:165], v[194:197], v[32:35]
	v_mfma_f32_16x16x32_bf16 v[24:27], v[170:173], v[194:197], v[24:27]
	v_mfma_f32_16x16x32_bf16 v[16:19], v[162:165], v[204:207], v[16:19]
	v_mfma_f32_16x16x32_bf16 v[8:11], v[170:173], v[204:207], v[8:11]
	s_barrier
	s_add_i32 s54, s54, 2
	s_addk_i32 s55, 0x100
	s_addk_i32 s56, 0x100
	s_cmp_gt_u32 s54, 13
	s_cbranch_scc0 .LBB0_1461
	v_readlane_b32 s12, v251, 45
	v_readlane_b32 s13, v251, 46
	s_and_b64 vcc, exec, s[12:13]
	s_cbranch_vccz .LBB0_1464
	s_barrier

; #define PG8_WAIT_V(n) asm volatile("s_waitcnt vmcnt(" #n ")" ::: "memory")
; template <class Epi, bool ALIGN_EPI, bool SP2, class Hook>
; __device__ __forceinline__ void gemm_phase(LAS unsigned char* lds, const Gemm g, const StaticOrder& S, const Epi& E, Acc& acc, const bool fresh, const Hook& H, const int wave_id) {
;     ...
;         for (int t = t0; t < nt; t += 2) {
;             const bool last = (t == nt - 2);
;             const Src a1 = cA + (size_t)(t + 1) * kstep;
;             const Src a2 = last ? nA : cA + (size_t)(t + 2) * kstep, b2 = last ? nB : cB + (size_t)(t + 2) * kstep;
;             const Src a3 = a2 + kstep, b3 = b2 + kstep;
;             if (last && has_next) H(nxt);
;             if constexpr (SP2) {
;             PG8_TRIP_SP2(PG8_WAIT_V(8));
.LBB0_1572:
	v_add_u32_e32 v142, 0x10000, v161
	v_add_u32_e32 v163, 0x14000, v161
	ds_read_b128 v[130:133], v142
	ds_read_b128 v[134:137], v142 offset:1024
	ds_read_b128 v[138:141], v142 offset:2048
	ds_read_b128 v[142:145], v142 offset:3072
	ds_read_b128 v[146:149], v163
	ds_read_b128 v[150:153], v163 offset:1024
	ds_read_b128 v[154:157], v163 offset:2048
	ds_read_b128 v[164:167], v163 offset:3072
	s_add_i32 s16, s2, 0xfff40080
	s_cmp_eq_u32 s61, 40
	s_cselect_b32 s64, s57, s16
	s_cselect_b32 s17, s35, s9
	s_cselect_b32 s16, s34, s8
	s_cselect_b32 s19, s51, s53
	s_cselect_b32 s18, s50, s52
	s_cselect_b32 s62, s58, s3
	s_cselect_b32 s20, s10, s12
	s_cselect_b32 s21, s11, s13
	s_cselect_b32 s22, s30, s14
	s_cselect_b32 s23, s31, s15
	s_or_b32 s63, s64, 0x80
	s_mov_b32 m0, s45
	ds_read_b128 v[168:171], v162
	ds_read_b128 v[172:175], v162 offset:1024
	ds_read_b128 v[176:179], v162 offset:2048
	ds_read_b128 v[180:183], v162 offset:3072
	ds_read_b128 v[184:187], v162 offset:4096
	ds_read_b128 v[188:191], v162 offset:5120
	ds_read_b128 v[192:195], v162 offset:6144
	ds_read_b128 v[200:203], v162 offset:7168
	buffer_load_dwordx4 v0, s[12:15], s2 offen lds
	s_mov_b32 m0, s46
	s_nop 0
	buffer_load_dwordx4 v159, s[12:15], s2 offen lds
	s_waitcnt vmcnt(8)
	s_waitcnt lgkmcnt(0)
	s_barrier
	v_mfma_f32_16x16x32_bf16 v[126:129], v[130:133], v[168:171], v[126:129]
	v_mfma_f32_16x16x32_bf16 v[122:125], v[138:141], v[168:171], v[122:125]
	v_mfma_f32_16x16x32_bf16 v[110:113], v[130:133], v[176:179], v[110:113]
	v_mfma_f32_16x16x32_bf16 v[106:109], v[138:141], v[176:179], v[106:109]
	v_mfma_f32_16x16x32_bf16 v[94:97], v[130:133], v[184:187], v[94:97]
	v_mfma_f32_16x16x32_bf16 v[90:93], v[138:141], v[184:187], v[90:93]
	v_mfma_f32_16x16x32_bf16 v[78:81], v[130:133], v[192:195], v[78:81]
	v_mfma_f32_16x16x32_bf16 v[74:77], v[138:141], v[192:195], v[74:77]
	v_mfma_f32_16x16x32_bf16 v[126:129], v[134:137], v[172:175], v[126:129]
	v_mfma_f32_16x16x32_bf16 v[122:125], v[142:145], v[172:175], v[122:125]
	v_mfma_f32_16x16x32_bf16 v[110:113], v[134:137], v[180:183], v[110:113]
	v_mfma_f32_16x16x32_bf16 v[106:109], v[142:145], v[180:183], v[106:109]
	v_mfma_f32_16x16x32_bf16 v[94:97], v[134:137], v[188:191], v[94:97]
	v_mfma_f32_16x16x32_bf16 v[90:93], v[142:145], v[188:191], v[90:93]
	v_mfma_f32_16x16x32_bf16 v[78:81], v[134:137], v[200:203], v[78:81]
	v_mfma_f32_16x16x32_bf16 v[74:77], v[142:145], v[200:203], v[74:77]
	v_mfma_f32_16x16x32_bf16 v[118:121], v[146:149], v[168:171], v[118:121]
	v_mfma_f32_16x16x32_bf16 v[114:117], v[154:157], v[168:171], v[114:117]
	v_mfma_f32_16x16x32_bf16 v[102:105], v[146:149], v[176:179], v[102:105]
	v_mfma_f32_16x16x32_bf16 v[98:101], v[154:157], v[176:179], v[98:101]
	v_mfma_f32_16x16x32_bf16 v[86:89], v[146:149], v[184:187], v[86:89]
	v_mfma_f32_16x16x32_bf16 v[82:85], v[154:157], v[184:187], v[82:85]
	v_mfma_f32_16x16x32_bf16 v[70:73], v[146:149], v[192:195], v[70:73]
	v_mfma_f32_16x16x32_bf16 v[66:69], v[154:157], v[192:195], v[66:69]
	v_mfma_f32_16x16x32_bf16 v[118:121], v[150:153], v[172:175], v[118:121]
	v_mfma_f32_16x16x32_bf16 v[114:117], v[164:167], v[172:175], v[114:117]
	v_mfma_f32_16x16x32_bf16 v[102:105], v[150:153], v[180:183], v[102:105]
	v_mfma_f32_16x16x32_bf16 v[98:101], v[164:167], v[180:183], v[98:101]
	v_mfma_f32_16x16x32_bf16 v[86:89], v[150:153], v[188:191], v[86:89]
	v_mfma_f32_16x16x32_bf16 v[82:85], v[164:167], v[188:191], v[82:85]
	v_mfma_f32_16x16x32_bf16 v[70:73], v[150:153], v[200:203], v[70:73]
	v_mfma_f32_16x16x32_bf16 v[66:69], v[164:167], v[200:203], v[66:69]
	s_barrier
	s_mov_b32 m0, s92
	ds_read_b128 v[168:171], v162 offset:16384
	ds_read_b128 v[172:175], v162 offset:17408
	ds_read_b128 v[176:179], v162 offset:18432
	ds_read_b128 v[180:183], v162 offset:19456
	ds_read_b128 v[184:187], v162 offset:20480
	ds_read_b128 v[188:191], v162 offset:21504
	ds_read_b128 v[192:195], v162 offset:22528
	ds_read_b128 v[200:203], v162 offset:23552
	buffer_load_dwordx4 v158, s[16:19], s62 offen lds
	s_mov_b32 m0, s93
	s_add_i32 s65, s62, 0xb0000
	buffer_load_dwordx4 v160, s[16:19], s62 offen lds
	s_mov_b32 m0, s94
	s_nop 0
	buffer_load_dwordx4 v158, s[16:19], s65 offen lds
	s_mov_b32 m0, s95
	s_nop 0
	buffer_load_dwordx4 v160, s[16:19], s65 offen lds
	s_mov_b32 m0, s44
	s_nop 0
	buffer_load_dwordx4 v0, s[20:23], s64 offen lds
	s_mov_b32 m0, s36
	s_nop 0
	buffer_load_dwordx4 v159, s[20:23], s64 offen lds
	s_waitcnt vmcnt(8)
	s_waitcnt lgkmcnt(0)
	s_barrier
	v_mfma_f32_16x16x32_bf16 v[62:65], v[130:133], v[168:171], v[62:65]
	v_mfma_f32_16x16x32_bf16 v[58:61], v[138:141], v[168:171], v[58:61]
	v_mfma_f32_16x16x32_bf16 v[46:49], v[130:133], v[176:179], v[46:49]
	v_mfma_f32_16x16x32_bf16 v[42:45], v[138:141], v[176:179], v[42:45]
	v_mfma_f32_16x16x32_bf16 v[30:33], v[130:133], v[184:187], v[30:33]
	v_mfma_f32_16x16x32_bf16 v[26:29], v[138:141], v[184:187], v[26:29]
	v_mfma_f32_16x16x32_bf16 v[14:17], v[130:133], v[192:195], v[14:17]
	v_mfma_f32_16x16x32_bf16 v[10:13], v[138:141], v[192:195], v[10:13]
	v_mfma_f32_16x16x32_bf16 v[62:65], v[134:137], v[172:175], v[62:65]
	v_mfma_f32_16x16x32_bf16 v[58:61], v[142:145], v[172:175], v[58:61]
	v_mfma_f32_16x16x32_bf16 v[46:49], v[134:137], v[180:183], v[46:49]
	v_mfma_f32_16x16x32_bf16 v[42:45], v[142:145], v[180:183], v[42:45]
	v_mfma_f32_16x16x32_bf16 v[30:33], v[134:137], v[188:191], v[30:33]
	v_mfma_f32_16x16x32_bf16 v[26:29], v[142:145], v[188:191], v[26:29]
	v_mfma_f32_16x16x32_bf16 v[14:17], v[134:137], v[200:203], v[14:17]
	v_mfma_f32_16x16x32_bf16 v[10:13], v[142:145], v[200:203], v[10:13]
	v_mfma_f32_16x16x32_bf16 v[54:57], v[146:149], v[168:171], v[54:57]
	v_mfma_f32_16x16x32_bf16 v[50:53], v[154:157], v[168:171], v[50:53]
	v_mfma_f32_16x16x32_bf16 v[38:41], v[146:149], v[176:179], v[38:41]
	v_mfma_f32_16x16x32_bf16 v[34:37], v[154:157], v[176:179], v[34:37]
	v_mfma_f32_16x16x32_bf16 v[22:25], v[146:149], v[184:187], v[22:25]
	v_mfma_f32_16x16x32_bf16 v[18:21], v[154:157], v[184:187], v[18:21]
	v_mfma_f32_16x16x32_bf16 v[6:9], v[146:149], v[192:195], v[6:9]
	v_mfma_f32_16x16x32_bf16 v[2:5], v[154:157], v[192:195], v[2:5]
	v_mfma_f32_16x16x32_bf16 v[54:57], v[150:153], v[172:175], v[54:57]
	v_mfma_f32_16x16x32_bf16 v[50:53], v[164:167], v[172:175], v[50:53]
	v_mfma_f32_16x16x32_bf16 v[38:41], v[150:153], v[180:183], v[38:41]
	v_mfma_f32_16x16x32_bf16 v[34:37], v[164:167], v[180:183], v[34:37]
	v_mfma_f32_16x16x32_bf16 v[22:25], v[150:153], v[188:191], v[22:25]
	v_mfma_f32_16x16x32_bf16 v[18:21], v[164:167], v[188:191], v[18:21]
	v_mfma_f32_16x16x32_bf16 v[6:9], v[150:153], v[200:203], v[6:9]
	v_mfma_f32_16x16x32_bf16 v[2:5], v[164:167], v[200:203], v[2:5]
	s_barrier
; #define PG8_WAIT_V(n) asm volatile("s_waitcnt vmcnt(" #n ")" ::: "memory")
; template <class Epi, bool ALIGN_EPI, bool SP2, class Hook>
; __device__ __forceinline__ void gemm_phase(LAS unsigned char* lds, const Gemm g, const StaticOrder& S, const Epi& E, Acc& acc, const bool fresh, const Hook& H, const int wave_id) {
;     ...
;         for (int t = t0; t < nt; t += 2) {
;             const bool last = (t == nt - 2);
;             const Src a1 = cA + (size_t)(t + 1) * kstep;
;             const Src a2 = last ? nA : cA + (size_t)(t + 2) * kstep, b2 = last ? nB : cB + (size_t)(t + 2) * kstep;
;             const Src a3 = a2 + kstep, b3 = b2 + kstep;
;             if (last && has_next) H(nxt);
;             if constexpr (SP2) {
;             PG8_TRIP_SP2(PG8_WAIT_V(8));
	v_add_u32_e32 v142, 0x18000, v161
	v_add_u32_e32 v163, 0x1c000, v161
	ds_read_b128 v[130:133], v142
	ds_read_b128 v[134:137], v142 offset:1024
	ds_read_b128 v[138:141], v142 offset:2048
	ds_read_b128 v[142:145], v142 offset:3072
	ds_read_b128 v[146:149], v163
	ds_read_b128 v[150:153], v163 offset:1024
	ds_read_b128 v[154:157], v163 offset:2048
	ds_read_b128 v[164:167], v163 offset:3072
	s_add_i32 s64, s64, 0xc0000
	s_mov_b32 m0, s37
	ds_read_b128 v[168:171], v162 offset:32768
	ds_read_b128 v[172:175], v162 offset:33792
	ds_read_b128 v[176:179], v162 offset:34816
	ds_read_b128 v[180:183], v162 offset:35840
	ds_read_b128 v[184:187], v162 offset:36864
	ds_read_b128 v[188:191], v162 offset:37888
	ds_read_b128 v[192:195], v162 offset:38912
	ds_read_b128 v[200:203], v162 offset:39936
	buffer_load_dwordx4 v0, s[20:23], s64 offen lds
	s_mov_b32 m0, s38
	s_nop 0
	buffer_load_dwordx4 v159, s[20:23], s64 offen lds
	s_waitcnt vmcnt(8)
	s_waitcnt lgkmcnt(0)
	s_barrier
	v_mfma_f32_16x16x32_bf16 v[126:129], v[130:133], v[168:171], v[126:129]
	v_mfma_f32_16x16x32_bf16 v[122:125], v[138:141], v[168:171], v[122:125]
	v_mfma_f32_16x16x32_bf16 v[110:113], v[130:133], v[176:179], v[110:113]
	v_mfma_f32_16x16x32_bf16 v[106:109], v[138:141], v[176:179], v[106:109]
	v_mfma_f32_16x16x32_bf16 v[94:97], v[130:133], v[184:187], v[94:97]
	v_mfma_f32_16x16x32_bf16 v[90:93], v[138:141], v[184:187], v[90:93]
	v_mfma_f32_16x16x32_bf16 v[78:81], v[130:133], v[192:195], v[78:81]
	v_mfma_f32_16x16x32_bf16 v[74:77], v[138:141], v[192:195], v[74:77]
	v_mfma_f32_16x16x32_bf16 v[126:129], v[134:137], v[172:175], v[126:129]
	v_mfma_f32_16x16x32_bf16 v[122:125], v[142:145], v[172:175], v[122:125]
	v_mfma_f32_16x16x32_bf16 v[110:113], v[134:137], v[180:183], v[110:113]
	v_mfma_f32_16x16x32_bf16 v[106:109], v[142:145], v[180:183], v[106:109]
	v_mfma_f32_16x16x32_bf16 v[94:97], v[134:137], v[188:191], v[94:97]
	v_mfma_f32_16x16x32_bf16 v[90:93], v[142:145], v[188:191], v[90:93]
	v_mfma_f32_16x16x32_bf16 v[78:81], v[134:137], v[200:203], v[78:81]
	v_mfma_f32_16x16x32_bf16 v[74:77], v[142:145], v[200:203], v[74:77]
	v_mfma_f32_16x16x32_bf16 v[118:121], v[146:149], v[168:171], v[118:121]
	v_mfma_f32_16x16x32_bf16 v[114:117], v[154:157], v[168:171], v[114:117]
	v_mfma_f32_16x16x32_bf16 v[102:105], v[146:149], v[176:179], v[102:105]
	v_mfma_f32_16x16x32_bf16 v[98:101], v[154:157], v[176:179], v[98:101]
	v_mfma_f32_16x16x32_bf16 v[86:89], v[146:149], v[184:187], v[86:89]
	v_mfma_f32_16x16x32_bf16 v[82:85], v[154:157], v[184:187], v[82:85]
	v_mfma_f32_16x16x32_bf16 v[70:73], v[146:149], v[192:195], v[70:73]
	v_mfma_f32_16x16x32_bf16 v[66:69], v[154:157], v[192:195], v[66:69]
	v_mfma_f32_16x16x32_bf16 v[118:121], v[150:153], v[172:175], v[118:121]
	v_mfma_f32_16x16x32_bf16 v[114:117], v[164:167], v[172:175], v[114:117]
	v_mfma_f32_16x16x32_bf16 v[102:105], v[150:153], v[180:183], v[102:105]
	v_mfma_f32_16x16x32_bf16 v[98:101], v[164:167], v[180:183], v[98:101]
	v_mfma_f32_16x16x32_bf16 v[86:89], v[150:153], v[188:191], v[86:89]
	v_mfma_f32_16x16x32_bf16 v[82:85], v[164:167], v[188:191], v[82:85]
	v_mfma_f32_16x16x32_bf16 v[70:73], v[150:153], v[200:203], v[70:73]
	v_mfma_f32_16x16x32_bf16 v[66:69], v[164:167], v[200:203], v[66:69]
	s_barrier
	s_mov_b32 m0, s39
	s_or_b32 s64, s62, 0x80
	ds_read_b128 v[168:171], v162 offset:49152
	ds_read_b128 v[172:175], v162 offset:50176
	ds_read_b128 v[176:179], v162 offset:51200
	ds_read_b128 v[180:183], v162 offset:52224
	ds_read_b128 v[184:187], v162 offset:53248
	ds_read_b128 v[188:191], v162 offset:54272
	ds_read_b128 v[192:195], v162 offset:55296
	ds_read_b128 v[200:203], v162 offset:56320
	buffer_load_dwordx4 v158, s[16:19], s64 offen lds
	s_mov_b32 m0, s40
	s_add_i32 s62, s62, 0xb0080
	buffer_load_dwordx4 v160, s[16:19], s64 offen lds
	s_mov_b32 m0, s43
	s_nop 0
	buffer_load_dwordx4 v158, s[16:19], s62 offen lds
	s_mov_b32 m0, s42
	s_nop 0
	buffer_load_dwordx4 v160, s[16:19], s62 offen lds
	s_mov_b32 m0, s41
	s_nop 0
	buffer_load_dwordx4 v0, s[20:23], s63 offen lds
	s_mov_b32 m0, s33
	s_nop 0
	buffer_load_dwordx4 v159, s[20:23], s63 offen lds
	s_waitcnt vmcnt(8)
	s_waitcnt lgkmcnt(0)
	s_barrier
	v_mfma_f32_16x16x32_bf16 v[62:65], v[130:133], v[168:171], v[62:65]
	v_mfma_f32_16x16x32_bf16 v[58:61], v[138:141], v[168:171], v[58:61]
	v_mfma_f32_16x16x32_bf16 v[46:49], v[130:133], v[176:179], v[46:49]
	v_mfma_f32_16x16x32_bf16 v[42:45], v[138:141], v[176:179], v[42:45]
	v_mfma_f32_16x16x32_bf16 v[30:33], v[130:133], v[184:187], v[30:33]
	v_mfma_f32_16x16x32_bf16 v[26:29], v[138:141], v[184:187], v[26:29]
	v_mfma_f32_16x16x32_bf16 v[14:17], v[130:133], v[192:195], v[14:17]
	v_mfma_f32_16x16x32_bf16 v[10:13], v[138:141], v[192:195], v[10:13]
	v_mfma_f32_16x16x32_bf16 v[62:65], v[134:137], v[172:175], v[62:65]
	v_mfma_f32_16x16x32_bf16 v[58:61], v[142:145], v[172:175], v[58:61]
	v_mfma_f32_16x16x32_bf16 v[46:49], v[134:137], v[180:183], v[46:49]
	v_mfma_f32_16x16x32_bf16 v[42:45], v[142:145], v[180:183], v[42:45]
	v_mfma_f32_16x16x32_bf16 v[30:33], v[134:137], v[188:191], v[30:33]
	v_mfma_f32_16x16x32_bf16 v[26:29], v[142:145], v[188:191], v[26:29]
	v_mfma_f32_16x16x32_bf16 v[14:17], v[134:137], v[200:203], v[14:17]
	v_mfma_f32_16x16x32_bf16 v[10:13], v[142:145], v[200:203], v[10:13]
	v_mfma_f32_16x16x32_bf16 v[54:57], v[146:149], v[168:171], v[54:57]
	v_mfma_f32_16x16x32_bf16 v[50:53], v[154:157], v[168:171], v[50:53]
	v_mfma_f32_16x16x32_bf16 v[38:41], v[146:149], v[176:179], v[38:41]
	v_mfma_f32_16x16x32_bf16 v[34:37], v[154:157], v[176:179], v[34:37]
	v_mfma_f32_16x16x32_bf16 v[22:25], v[146:149], v[184:187], v[22:25]
	v_mfma_f32_16x16x32_bf16 v[18:21], v[154:157], v[184:187], v[18:21]
	v_mfma_f32_16x16x32_bf16 v[6:9], v[146:149], v[192:195], v[6:9]
	v_mfma_f32_16x16x32_bf16 v[2:5], v[154:157], v[192:195], v[2:5]
	v_mfma_f32_16x16x32_bf16 v[54:57], v[150:153], v[172:175], v[54:57]
	v_mfma_f32_16x16x32_bf16 v[50:53], v[164:167], v[172:175], v[50:53]
	v_mfma_f32_16x16x32_bf16 v[38:41], v[150:153], v[180:183], v[38:41]
	v_mfma_f32_16x16x32_bf16 v[34:37], v[164:167], v[180:183], v[34:37]
	v_mfma_f32_16x16x32_bf16 v[22:25], v[150:153], v[188:191], v[22:25]
	v_mfma_f32_16x16x32_bf16 v[18:21], v[164:167], v[188:191], v[18:21]
	v_mfma_f32_16x16x32_bf16 v[6:9], v[150:153], v[200:203], v[6:9]
	v_mfma_f32_16x16x32_bf16 v[2:5], v[164:167], v[200:203], v[2:5]
	s_barrier
	s_add_i32 s61, s61, 2
	s_addk_i32 s2, 0x100
	s_addk_i32 s3, 0x100
	s_cmp_gt_u32 s61, 41
	s_cbranch_scc0 .LBB0_1572
	v_readlane_b32 s2, v251, 45
	v_readlane_b32 s3, v251, 46
	s_and_b64 vcc, exec, s[2:3]
	s_cbranch_vccz .LBB0_1575
	s_barrier

; #define PG8_WAIT_V(n) asm volatile("s_waitcnt vmcnt(" #n ")" ::: "memory")
; template <class Epi, bool ALIGN_EPI, bool SP2, class Hook>
; __device__ __forceinline__ void gemm_phase(LAS unsigned char* lds, const Gemm g, const StaticOrder& S, const Epi& E, Acc& acc, const bool fresh, const Hook& H, const int wave_id) {
;     ...
;         for (int t = t0; t < nt; t += 2) {
;             const bool last = (t == nt - 2);
;             const Src a1 = cA + (size_t)(t + 1) * kstep;
;             const Src a2 = last ? nA : cA + (size_t)(t + 2) * kstep, b2 = last ? nB : cB + (size_t)(t + 2) * kstep;
;             const Src a3 = a2 + kstep, b3 = b2 + kstep;
;             if (last && has_next) H(nxt);
;             if constexpr (SP2) {
;             PG8_TRIP_SP2(PG8_WAIT_V(8));
.LBB0_1614:
	v_add_u32_e32 v0, 0x10000, v172
	ds_read_b128 v[130:133], v0
	ds_read_b128 v[134:137], v0 offset:1024
	ds_read_b128 v[138:141], v0 offset:2048
	ds_read_b128 v[142:145], v0 offset:3072
	v_add_u32_e32 v0, 0x14000, v172
	ds_read_b128 v[146:149], v0
	ds_read_b128 v[150:153], v0 offset:1024
	ds_read_b128 v[154:157], v0 offset:2048
	ds_read_b128 v[158:161], v0 offset:3072
	s_add_i32 s12, s2, 0xfff40080
	s_cmp_eq_u32 s59, 40
	s_cselect_b32 s62, s55, s12
	s_cselect_b32 s13, s31, s77
	s_cselect_b32 s12, s30, s76
	s_cselect_b32 s15, s35, s51
	s_cselect_b32 s14, s34, s50
	s_cselect_b32 s60, s56, s3
	s_cselect_b32 s16, s20, s8
	s_cselect_b32 s17, s21, s9
	s_cselect_b32 s18, s22, s10
	s_cselect_b32 s19, s23, s11
	s_or_b32 s61, s62, 0x80
	s_mov_b32 m0, s45
	ds_read_b128 v[162:165], v173
	ds_read_b128 v[174:177], v173 offset:1024
	ds_read_b128 v[178:181], v173 offset:2048
	ds_read_b128 v[182:185], v173 offset:3072
	ds_read_b128 v[186:189], v173 offset:4096
	ds_read_b128 v[190:193], v173 offset:5120
	ds_read_b128 v[194:197], v173 offset:6144
	ds_read_b128 v[200:203], v173 offset:7168
	buffer_load_dwordx4 v168, s[8:11], s2 offen lds
	s_mov_b32 m0, s46
	s_nop 0
	buffer_load_dwordx4 v170, s[8:11], s2 offen lds
	s_waitcnt vmcnt(8)
	s_waitcnt lgkmcnt(0)
	s_barrier
	v_mfma_f32_16x16x32_bf16 v[126:129], v[130:133], v[162:165], v[126:129]
	v_mfma_f32_16x16x32_bf16 v[122:125], v[138:141], v[162:165], v[122:125]
	v_mfma_f32_16x16x32_bf16 v[110:113], v[130:133], v[178:181], v[110:113]
	v_mfma_f32_16x16x32_bf16 v[106:109], v[138:141], v[178:181], v[106:109]
	v_mfma_f32_16x16x32_bf16 v[94:97], v[130:133], v[186:189], v[94:97]
	v_mfma_f32_16x16x32_bf16 v[90:93], v[138:141], v[186:189], v[90:93]
	v_mfma_f32_16x16x32_bf16 v[78:81], v[130:133], v[194:197], v[78:81]
	v_mfma_f32_16x16x32_bf16 v[74:77], v[138:141], v[194:197], v[74:77]
	v_mfma_f32_16x16x32_bf16 v[126:129], v[134:137], v[174:177], v[126:129]
	v_mfma_f32_16x16x32_bf16 v[122:125], v[142:145], v[174:177], v[122:125]
	v_mfma_f32_16x16x32_bf16 v[110:113], v[134:137], v[182:185], v[110:113]
	v_mfma_f32_16x16x32_bf16 v[106:109], v[142:145], v[182:185], v[106:109]
	v_mfma_f32_16x16x32_bf16 v[94:97], v[134:137], v[190:193], v[94:97]
	v_mfma_f32_16x16x32_bf16 v[90:93], v[142:145], v[190:193], v[90:93]
	v_mfma_f32_16x16x32_bf16 v[78:81], v[134:137], v[200:203], v[78:81]
	v_mfma_f32_16x16x32_bf16 v[74:77], v[142:145], v[200:203], v[74:77]
	v_mfma_f32_16x16x32_bf16 v[118:121], v[146:149], v[162:165], v[118:121]
	v_mfma_f32_16x16x32_bf16 v[114:117], v[154:157], v[162:165], v[114:117]
	v_mfma_f32_16x16x32_bf16 v[102:105], v[146:149], v[178:181], v[102:105]
	v_mfma_f32_16x16x32_bf16 v[98:101], v[154:157], v[178:181], v[98:101]
	v_mfma_f32_16x16x32_bf16 v[86:89], v[146:149], v[186:189], v[86:89]
	v_mfma_f32_16x16x32_bf16 v[82:85], v[154:157], v[186:189], v[82:85]
	v_mfma_f32_16x16x32_bf16 v[70:73], v[146:149], v[194:197], v[70:73]
	v_mfma_f32_16x16x32_bf16 v[66:69], v[154:157], v[194:197], v[66:69]
	v_mfma_f32_16x16x32_bf16 v[118:121], v[150:153], v[174:177], v[118:121]
	v_mfma_f32_16x16x32_bf16 v[114:117], v[158:161], v[174:177], v[114:117]
	v_mfma_f32_16x16x32_bf16 v[102:105], v[150:153], v[182:185], v[102:105]
	v_mfma_f32_16x16x32_bf16 v[98:101], v[158:161], v[182:185], v[98:101]
	v_mfma_f32_16x16x32_bf16 v[86:89], v[150:153], v[190:193], v[86:89]
	v_mfma_f32_16x16x32_bf16 v[82:85], v[158:161], v[190:193], v[82:85]
	v_mfma_f32_16x16x32_bf16 v[70:73], v[150:153], v[200:203], v[70:73]
	v_mfma_f32_16x16x32_bf16 v[66:69], v[158:161], v[200:203], v[66:69]
	s_barrier
	s_mov_b32 m0, s92
	ds_read_b128 v[162:165], v173 offset:16384
	ds_read_b128 v[174:177], v173 offset:17408
	ds_read_b128 v[178:181], v173 offset:18432
	ds_read_b128 v[182:185], v173 offset:19456
	ds_read_b128 v[186:189], v173 offset:20480
	ds_read_b128 v[190:193], v173 offset:21504
	ds_read_b128 v[194:197], v173 offset:22528
	ds_read_b128 v[200:203], v173 offset:23552
	buffer_load_dwordx4 v169, s[12:15], s60 offen lds
	s_mov_b32 m0, s93
	s_add_i32 s63, s60, 0xb0000
	buffer_load_dwordx4 v171, s[12:15], s60 offen lds
	s_mov_b32 m0, s94
	s_nop 0
	buffer_load_dwordx4 v169, s[12:15], s63 offen lds
	s_mov_b32 m0, s95
	s_nop 0
	buffer_load_dwordx4 v171, s[12:15], s63 offen lds
	s_mov_b32 m0, s44
	s_nop 0
	buffer_load_dwordx4 v168, s[16:19], s62 offen lds
	s_mov_b32 m0, s36
	s_nop 0
	buffer_load_dwordx4 v170, s[16:19], s62 offen lds
	s_waitcnt vmcnt(8)
	s_waitcnt lgkmcnt(0)
	s_barrier
	v_mfma_f32_16x16x32_bf16 v[62:65], v[130:133], v[162:165], v[62:65]
	v_mfma_f32_16x16x32_bf16 v[58:61], v[138:141], v[162:165], v[58:61]
	v_mfma_f32_16x16x32_bf16 v[46:49], v[130:133], v[178:181], v[46:49]
	v_mfma_f32_16x16x32_bf16 v[42:45], v[138:141], v[178:181], v[42:45]
	v_mfma_f32_16x16x32_bf16 v[30:33], v[130:133], v[186:189], v[30:33]
	v_mfma_f32_16x16x32_bf16 v[26:29], v[138:141], v[186:189], v[26:29]
	v_mfma_f32_16x16x32_bf16 v[14:17], v[130:133], v[194:197], v[14:17]
	v_mfma_f32_16x16x32_bf16 v[10:13], v[138:141], v[194:197], v[10:13]
	v_mfma_f32_16x16x32_bf16 v[62:65], v[134:137], v[174:177], v[62:65]
	v_mfma_f32_16x16x32_bf16 v[58:61], v[142:145], v[174:177], v[58:61]
	v_mfma_f32_16x16x32_bf16 v[46:49], v[134:137], v[182:185], v[46:49]
	v_mfma_f32_16x16x32_bf16 v[42:45], v[142:145], v[182:185], v[42:45]
	v_mfma_f32_16x16x32_bf16 v[30:33], v[134:137], v[190:193], v[30:33]
	v_mfma_f32_16x16x32_bf16 v[26:29], v[142:145], v[190:193], v[26:29]
	v_mfma_f32_16x16x32_bf16 v[14:17], v[134:137], v[200:203], v[14:17]
	v_mfma_f32_16x16x32_bf16 v[10:13], v[142:145], v[200:203], v[10:13]
	v_mfma_f32_16x16x32_bf16 v[54:57], v[146:149], v[162:165], v[54:57]
	v_mfma_f32_16x16x32_bf16 v[50:53], v[154:157], v[162:165], v[50:53]
	v_mfma_f32_16x16x32_bf16 v[38:41], v[146:149], v[178:181], v[38:41]
	v_mfma_f32_16x16x32_bf16 v[34:37], v[154:157], v[178:181], v[34:37]
	v_mfma_f32_16x16x32_bf16 v[22:25], v[146:149], v[186:189], v[22:25]
	v_mfma_f32_16x16x32_bf16 v[18:21], v[154:157], v[186:189], v[18:21]
	v_mfma_f32_16x16x32_bf16 v[6:9], v[146:149], v[194:197], v[6:9]
	v_mfma_f32_16x16x32_bf16 v[2:5], v[154:157], v[194:197], v[2:5]
	v_mfma_f32_16x16x32_bf16 v[54:57], v[150:153], v[174:177], v[54:57]
	v_mfma_f32_16x16x32_bf16 v[50:53], v[158:161], v[174:177], v[50:53]
	v_mfma_f32_16x16x32_bf16 v[38:41], v[150:153], v[182:185], v[38:41]
	v_mfma_f32_16x16x32_bf16 v[34:37], v[158:161], v[182:185], v[34:37]
	v_mfma_f32_16x16x32_bf16 v[22:25], v[150:153], v[190:193], v[22:25]
	v_mfma_f32_16x16x32_bf16 v[18:21], v[158:161], v[190:193], v[18:21]
	v_mfma_f32_16x16x32_bf16 v[6:9], v[150:153], v[200:203], v[6:9]
	v_mfma_f32_16x16x32_bf16 v[2:5], v[158:161], v[200:203], v[2:5]
	s_barrier
; #define PG8_WAIT_V(n) asm volatile("s_waitcnt vmcnt(" #n ")" ::: "memory")
; template <class Epi, bool ALIGN_EPI, bool SP2, class Hook>
; __device__ __forceinline__ void gemm_phase(LAS unsigned char* lds, const Gemm g, const StaticOrder& S, const Epi& E, Acc& acc, const bool fresh, const Hook& H, const int wave_id) {
;     ...
;         for (int t = t0; t < nt; t += 2) {
;             const bool last = (t == nt - 2);
;             const Src a1 = cA + (size_t)(t + 1) * kstep;
;             const Src a2 = last ? nA : cA + (size_t)(t + 2) * kstep, b2 = last ? nB : cB + (size_t)(t + 2) * kstep;
;             const Src a3 = a2 + kstep, b3 = b2 + kstep;
;             if (last && has_next) H(nxt);
;             if constexpr (SP2) {
;             PG8_TRIP_SP2(PG8_WAIT_V(8));
	v_add_u32_e32 v0, 0x18000, v172
	ds_read_b128 v[130:133], v0
	ds_read_b128 v[134:137], v0 offset:1024
	ds_read_b128 v[138:141], v0 offset:2048
	ds_read_b128 v[142:145], v0 offset:3072
	v_add_u32_e32 v0, 0x1c000, v172
	ds_read_b128 v[146:149], v0
	ds_read_b128 v[150:153], v0 offset:1024
	ds_read_b128 v[154:157], v0 offset:2048
	ds_read_b128 v[158:161], v0 offset:3072
	s_add_i32 s62, s62, 0xc0000
	s_mov_b32 m0, s37
	ds_read_b128 v[162:165], v173 offset:32768
	ds_read_b128 v[174:177], v173 offset:33792
	ds_read_b128 v[178:181], v173 offset:34816
	ds_read_b128 v[182:185], v173 offset:35840
	ds_read_b128 v[186:189], v173 offset:36864
	ds_read_b128 v[190:193], v173 offset:37888
	ds_read_b128 v[194:197], v173 offset:38912
	ds_read_b128 v[200:203], v173 offset:39936
	buffer_load_dwordx4 v168, s[16:19], s62 offen lds
	s_mov_b32 m0, s38
	s_nop 0
	buffer_load_dwordx4 v170, s[16:19], s62 offen lds
	s_waitcnt vmcnt(8)
	s_waitcnt lgkmcnt(0)
	s_barrier
	v_mfma_f32_16x16x32_bf16 v[126:129], v[130:133], v[162:165], v[126:129]
	v_mfma_f32_16x16x32_bf16 v[122:125], v[138:141], v[162:165], v[122:125]
	v_mfma_f32_16x16x32_bf16 v[110:113], v[130:133], v[178:181], v[110:113]
	v_mfma_f32_16x16x32_bf16 v[106:109], v[138:141], v[178:181], v[106:109]
	v_mfma_f32_16x16x32_bf16 v[94:97], v[130:133], v[186:189], v[94:97]
	v_mfma_f32_16x16x32_bf16 v[90:93], v[138:141], v[186:189], v[90:93]
	v_mfma_f32_16x16x32_bf16 v[78:81], v[130:133], v[194:197], v[78:81]
	v_mfma_f32_16x16x32_bf16 v[74:77], v[138:141], v[194:197], v[74:77]
	v_mfma_f32_16x16x32_bf16 v[126:129], v[134:137], v[174:177], v[126:129]
	v_mfma_f32_16x16x32_bf16 v[122:125], v[142:145], v[174:177], v[122:125]
	v_mfma_f32_16x16x32_bf16 v[110:113], v[134:137], v[182:185], v[110:113]
	v_mfma_f32_16x16x32_bf16 v[106:109], v[142:145], v[182:185], v[106:109]
	v_mfma_f32_16x16x32_bf16 v[94:97], v[134:137], v[190:193], v[94:97]
	v_mfma_f32_16x16x32_bf16 v[90:93], v[142:145], v[190:193], v[90:93]
	v_mfma_f32_16x16x32_bf16 v[78:81], v[134:137], v[200:203], v[78:81]
	v_mfma_f32_16x16x32_bf16 v[74:77], v[142:145], v[200:203], v[74:77]
	v_mfma_f32_16x16x32_bf16 v[118:121], v[146:149], v[162:165], v[118:121]
	v_mfma_f32_16x16x32_bf16 v[114:117], v[154:157], v[162:165], v[114:117]
	v_mfma_f32_16x16x32_bf16 v[102:105], v[146:149], v[178:181], v[102:105]
	v_mfma_f32_16x16x32_bf16 v[98:101], v[154:157], v[178:181], v[98:101]
	v_mfma_f32_16x16x32_bf16 v[86:89], v[146:149], v[186:189], v[86:89]
	v_mfma_f32_16x16x32_bf16 v[82:85], v[154:157], v[186:189], v[82:85]
	v_mfma_f32_16x16x32_bf16 v[70:73], v[146:149], v[194:197], v[70:73]
	v_mfma_f32_16x16x32_bf16 v[66:69], v[154:157], v[194:197], v[66:69]
	v_mfma_f32_16x16x32_bf16 v[118:121], v[150:153], v[174:177], v[118:121]
	v_mfma_f32_16x16x32_bf16 v[114:117], v[158:161], v[174:177], v[114:117]
	v_mfma_f32_16x16x32_bf16 v[102:105], v[150:153], v[182:185], v[102:105]
	v_mfma_f32_16x16x32_bf16 v[98:101], v[158:161], v[182:185], v[98:101]
	v_mfma_f32_16x16x32_bf16 v[86:89], v[150:153], v[190:193], v[86:89]
	v_mfma_f32_16x16x32_bf16 v[82:85], v[158:161], v[190:193], v[82:85]
	v_mfma_f32_16x16x32_bf16 v[70:73], v[150:153], v[200:203], v[70:73]
	v_mfma_f32_16x16x32_bf16 v[66:69], v[158:161], v[200:203], v[66:69]
	s_barrier
	s_mov_b32 m0, s39
	s_or_b32 s62, s60, 0x80
	ds_read_b128 v[162:165], v173 offset:49152
	ds_read_b128 v[174:177], v173 offset:50176
	ds_read_b128 v[178:181], v173 offset:51200
	ds_read_b128 v[182:185], v173 offset:52224
	ds_read_b128 v[186:189], v173 offset:53248
	ds_read_b128 v[190:193], v173 offset:54272
	ds_read_b128 v[194:197], v173 offset:55296
	ds_read_b128 v[200:203], v173 offset:56320
	buffer_load_dwordx4 v169, s[12:15], s62 offen lds
	s_mov_b32 m0, s40
	s_add_i32 s60, s60, 0xb0080
	buffer_load_dwordx4 v171, s[12:15], s62 offen lds
	s_mov_b32 m0, s43
	s_nop 0
	buffer_load_dwordx4 v169, s[12:15], s60 offen lds
	s_mov_b32 m0, s42
	s_nop 0
	buffer_load_dwordx4 v171, s[12:15], s60 offen lds
	s_mov_b32 m0, s41
	s_nop 0
	buffer_load_dwordx4 v168, s[16:19], s61 offen lds
	s_mov_b32 m0, s33
	s_nop 0
	buffer_load_dwordx4 v170, s[16:19], s61 offen lds
	s_waitcnt vmcnt(8)
	s_waitcnt lgkmcnt(0)
	s_barrier
	v_mfma_f32_16x16x32_bf16 v[62:65], v[130:133], v[162:165], v[62:65]
	v_mfma_f32_16x16x32_bf16 v[58:61], v[138:141], v[162:165], v[58:61]
	v_mfma_f32_16x16x32_bf16 v[46:49], v[130:133], v[178:181], v[46:49]
	v_mfma_f32_16x16x32_bf16 v[42:45], v[138:141], v[178:181], v[42:45]
	v_mfma_f32_16x16x32_bf16 v[30:33], v[130:133], v[186:189], v[30:33]
	v_mfma_f32_16x16x32_bf16 v[26:29], v[138:141], v[186:189], v[26:29]
	v_mfma_f32_16x16x32_bf16 v[14:17], v[130:133], v[194:197], v[14:17]
	v_mfma_f32_16x16x32_bf16 v[10:13], v[138:141], v[194:197], v[10:13]
	v_mfma_f32_16x16x32_bf16 v[62:65], v[134:137], v[174:177], v[62:65]
	v_mfma_f32_16x16x32_bf16 v[58:61], v[142:145], v[174:177], v[58:61]
	v_mfma_f32_16x16x32_bf16 v[46:49], v[134:137], v[182:185], v[46:49]
	v_mfma_f32_16x16x32_bf16 v[42:45], v[142:145], v[182:185], v[42:45]
	v_mfma_f32_16x16x32_bf16 v[30:33], v[134:137], v[190:193], v[30:33]
	v_mfma_f32_16x16x32_bf16 v[26:29], v[142:145], v[190:193], v[26:29]
	v_mfma_f32_16x16x32_bf16 v[14:17], v[134:137], v[200:203], v[14:17]
	v_mfma_f32_16x16x32_bf16 v[10:13], v[142:145], v[200:203], v[10:13]
	v_mfma_f32_16x16x32_bf16 v[54:57], v[146:149], v[162:165], v[54:57]
	v_mfma_f32_16x16x32_bf16 v[50:53], v[154:157], v[162:165], v[50:53]
	v_mfma_f32_16x16x32_bf16 v[38:41], v[146:149], v[178:181], v[38:41]
	v_mfma_f32_16x16x32_bf16 v[34:37], v[154:157], v[178:181], v[34:37]
	v_mfma_f32_16x16x32_bf16 v[22:25], v[146:149], v[186:189], v[22:25]
	v_mfma_f32_16x16x32_bf16 v[18:21], v[154:157], v[186:189], v[18:21]
	v_mfma_f32_16x16x32_bf16 v[6:9], v[146:149], v[194:197], v[6:9]
	v_mfma_f32_16x16x32_bf16 v[2:5], v[154:157], v[194:197], v[2:5]
	v_mfma_f32_16x16x32_bf16 v[54:57], v[150:153], v[174:177], v[54:57]
	v_mfma_f32_16x16x32_bf16 v[50:53], v[158:161], v[174:177], v[50:53]
	v_mfma_f32_16x16x32_bf16 v[38:41], v[150:153], v[182:185], v[38:41]
	v_mfma_f32_16x16x32_bf16 v[34:37], v[158:161], v[182:185], v[34:37]
	v_mfma_f32_16x16x32_bf16 v[22:25], v[150:153], v[190:193], v[22:25]
	v_mfma_f32_16x16x32_bf16 v[18:21], v[158:161], v[190:193], v[18:21]
	v_mfma_f32_16x16x32_bf16 v[6:9], v[150:153], v[200:203], v[6:9]
	v_mfma_f32_16x16x32_bf16 v[2:5], v[158:161], v[200:203], v[2:5]
	s_barrier
	s_add_i32 s59, s59, 2
	s_addk_i32 s2, 0x100
	s_addk_i32 s3, 0x100
	s_cmp_gt_u32 s59, 41
	s_cbranch_scc0 .LBB0_1614
	v_readlane_b32 s2, v251, 45
	v_readlane_b32 s3, v251, 46
	s_and_b64 vcc, exec, s[2:3]
	s_cbranch_vccz .LBB0_1617
	s_barrier
